# v52 with all 144 per-segment s_setprio flips deleted (they are dead at the .s level)
# speedup vs baseline: 1.0022x; 1.0017x over previous
; #define PG8_STAGE(bufoff, gbase, voff) do { _Pragma("unroll") for (int _i = 0; _i < 2; ++_i) \
;         __builtin_amdgcn_global_load_lds((const unsigned*)((const char*)(gbase) + (voff)[_i]), (PG8_LAS unsigned*)(lds + (bufoff) + ldsw + _i * 8192), 16, 0, 0); } while (0)
; #define PG8_LDA(dst, b, h) do { _Pragma("unroll") for (int m = 0; m < 4; ++m) _Pragma("unroll") for (int k = 0; k < 2; ++k) dst[m][k] = *(const PG8_LAS bf16x8*)(lds + PG8_SA(b, h) + aoff + m * 2048 + k * 1024); } while (0)
; #define PG8_LDB(dst, b, h) do { _Pragma("unroll") for (int n = 0; n < 2; ++n) _Pragma("unroll") for (int k = 0; k < 2; ++k) dst[n][k] = *(const PG8_LAS bf16x8*)(lds + PG8_SB(b, h) + boff + n * 2048 + k * 1024); } while (0)
; #define PG8_MMA(ai, bj, At, Bt) do { __builtin_amdgcn_s_setprio(1); _Pragma("unroll") for (int m = 0; m < 4; ++m) _Pragma("unroll") for (int n = 0; n < 2; ++n) _Pragma("unroll") for (int k = 0; k < 2; ++k) \
;         acc[ai][bj][m][n] = __builtin_amdgcn_mfma_f32_16x16x32_bf16(Bt[n][k], At[m][k], acc[ai][bj][m][n], 0, 0, 0); __builtin_amdgcn_s_setprio(0); } while (0)
; #define PG8_WAIT_V(n) asm volatile("s_waitcnt vmcnt(" #n ")" ::: "memory")
; #define PG8_WAIT_L(n) asm volatile("s_waitcnt lgkmcnt(" #n ")" ::: "memory")
; template <class Epi, class Sched, bool ALIGN_EPI = false, bool SP2 = false>
; __device__ __forceinline__ void gemm_phase(PG8_LAS unsigned char* lds, const Gemm g, const Sched& S, const Epi& E) {
;     ...
;             const bool last = (t == nt - 2);
;             const char* a1 = cA + (size_t)(t + 1) * kstep;
;             const char* a2 = last ? nA : cA + (size_t)(t + 2) * kstep; const char* b2 = last ? nB : cB + (size_t)(t + 2) * kstep;
;             const char* a3 = a2 + kstep; const char* b3 = b2 + kstep;
;             if (last && has_next) S.a_ready(nxt);
;             if constexpr (SP2) {
;             PG8_LDB(B0, 0, 0); PG8_LDB(B1, 0, 1); PG8_SCHED; PG8_LDA(At, 0, 0); PG8_STAGE(PG8_SA(1, 1), a1 + hstep, voffA);
;             PG8_WAIT_V(8); PG8_WAIT_L(0); PG8_BAR; PG8_MMA(0, 0, At, B0); PG8_MMA(0, 1, At, B1); PG8_BAR; PG8_SCHED;
;             PG8_LDA(At, 0, 1); PG8_STAGE(PG8_SB(0, 0), b2, voffB); PG8_STAGE(PG8_SB(0, 1), b2 + hstep, voffB); PG8_STAGE(PG8_SA(0, 0), a2, voffA);
;             PG8_WAIT_V(8); PG8_WAIT_L(0); PG8_BAR; PG8_MMA(1, 0, At, B0); PG8_MMA(1, 1, At, B1); PG8_BAR; PG8_SCHED;
.LBB0_139:
	ds_read_b128 v[2:5], v187
	ds_read_b128 v[6:9], v187 offset:1024
	ds_read_b128 v[138:141], v187 offset:2048
	ds_read_b128 v[142:145], v187 offset:3072
	ds_read_b128 v[146:149], v197
	ds_read_b128 v[150:153], v197 offset:1024
	ds_read_b128 v[154:157], v197 offset:2048
	ds_read_b128 v[158:161], v197 offset:3072
	s_add_u32 s14, s12, 0xfff00080
	s_addc_u32 s15, s13, -1
	s_cmp_eq_u32 s33, 60
	s_cselect_b32 s17, s2, s15
	s_cselect_b32 s16, s11, s14
	s_cselect_b32 s15, s26, s30
	s_cselect_b32 s14, s28, s29
	v_lshl_add_u64 v[162:163], s[12:13], 0, v[188:189]
	s_add_i32 m0, s27, 0xc000
	ds_read_b128 v[202:205], v199
	ds_read_b128 v[206:209], v199 offset:1024
	ds_read_b128 v[214:217], v199 offset:2048
	ds_read_b128 v[218:221], v199 offset:3072
	ds_read_b128 v[222:225], v199 offset:4096
	ds_read_b128 v[226:229], v199 offset:5120
	ds_read_b128 v[230:233], v199 offset:6144
	ds_read_b128 v[234:237], v199 offset:7168
	global_load_lds_dwordx4 v[162:163], off
	v_lshl_add_u64 v[162:163], s[12:13], 0, v[190:191]
	s_add_i32 m0, s27, 0xe000
	s_nop 0
	global_load_lds_dwordx4 v[162:163], off
	s_waitcnt vmcnt(8)
	s_waitcnt lgkmcnt(0)
	s_barrier
	v_mfma_f32_16x16x32_bf16 v[134:137], v[2:5], v[202:205], v[134:137]
	v_mfma_f32_16x16x32_bf16 v[134:137], v[6:9], v[206:209], v[134:137]
	v_mfma_f32_16x16x32_bf16 v[118:121], v[6:9], v[218:221], v[118:121]
	v_mfma_f32_16x16x32_bf16 v[118:121], v[2:5], v[214:217], v[118:121]
	v_mfma_f32_16x16x32_bf16 v[102:105], v[2:5], v[222:225], v[102:105]
	v_mfma_f32_16x16x32_bf16 v[102:105], v[6:9], v[226:229], v[102:105]
	v_mfma_f32_16x16x32_bf16 v[86:89], v[6:9], v[234:237], v[86:89]
	v_mfma_f32_16x16x32_bf16 v[86:89], v[2:5], v[230:233], v[86:89]
	v_mfma_f32_16x16x32_bf16 v[82:85], v[138:141], v[230:233], v[82:85]
	v_mfma_f32_16x16x32_bf16 v[82:85], v[142:145], v[234:237], v[82:85]
	v_mfma_f32_16x16x32_bf16 v[130:133], v[142:145], v[206:209], v[130:133]
	v_mfma_f32_16x16x32_bf16 v[130:133], v[138:141], v[202:205], v[130:133]
	v_mfma_f32_16x16x32_bf16 v[114:117], v[138:141], v[214:217], v[114:117]
	v_mfma_f32_16x16x32_bf16 v[114:117], v[142:145], v[218:221], v[114:117]
	v_mfma_f32_16x16x32_bf16 v[98:101], v[142:145], v[226:229], v[98:101]
	v_mfma_f32_16x16x32_bf16 v[98:101], v[138:141], v[222:225], v[98:101]
	v_mfma_f32_16x16x32_bf16 v[94:97], v[146:149], v[222:225], v[94:97]
	v_mfma_f32_16x16x32_bf16 v[94:97], v[150:153], v[226:229], v[94:97]
	v_mfma_f32_16x16x32_bf16 v[126:129], v[150:153], v[206:209], v[126:129]
	v_mfma_f32_16x16x32_bf16 v[126:129], v[146:149], v[202:205], v[126:129]
	v_mfma_f32_16x16x32_bf16 v[110:113], v[146:149], v[214:217], v[110:113]
	v_mfma_f32_16x16x32_bf16 v[110:113], v[150:153], v[218:221], v[110:113]
	v_mfma_f32_16x16x32_bf16 v[78:81], v[150:153], v[234:237], v[78:81]
	v_mfma_f32_16x16x32_bf16 v[78:81], v[146:149], v[230:233], v[78:81]
	v_mfma_f32_16x16x32_bf16 v[74:77], v[154:157], v[230:233], v[74:77]
	v_mfma_f32_16x16x32_bf16 v[74:77], v[158:161], v[234:237], v[74:77]
	v_mfma_f32_16x16x32_bf16 v[122:125], v[158:161], v[206:209], v[122:125]
	v_mfma_f32_16x16x32_bf16 v[122:125], v[154:157], v[202:205], v[122:125]
	v_mfma_f32_16x16x32_bf16 v[106:109], v[154:157], v[214:217], v[106:109]
	v_mfma_f32_16x16x32_bf16 v[106:109], v[158:161], v[218:221], v[106:109]
	v_mfma_f32_16x16x32_bf16 v[90:93], v[158:161], v[226:229], v[90:93]
	v_mfma_f32_16x16x32_bf16 v[90:93], v[154:157], v[222:225], v[90:93]
	s_barrier
	s_add_i32 s34, s41, s25
	v_lshl_add_u64 v[162:163], s[14:15], 0, v[168:169]
	s_mov_b32 m0, s34
	ds_read_b128 v[202:205], v199 offset:16384
	ds_read_b128 v[206:209], v199 offset:17408
	ds_read_b128 v[214:217], v199 offset:18432
	ds_read_b128 v[218:221], v199 offset:19456
	ds_read_b128 v[222:225], v199 offset:20480
	ds_read_b128 v[226:229], v199 offset:21504
	ds_read_b128 v[230:233], v199 offset:22528
	ds_read_b128 v[234:237], v199 offset:23552
	global_load_lds_dwordx4 v[162:163], off
	s_add_i32 m0, s34, 0x2000
	s_add_u32 s34, s14, 0x100000
	v_lshl_add_u64 v[210:211], s[14:15], 0, v[172:173]
	s_addc_u32 s35, s15, 0
	s_add_i32 s79, s92, s25
	global_load_lds_dwordx4 v[210:211], off
	v_lshl_add_u64 v[238:239], s[34:35], 0, v[168:169]
	s_mov_b32 m0, s79
	v_lshl_add_u64 v[240:241], s[16:17], 0, v[170:171]
	global_load_lds_dwordx4 v[238:239], off
	v_lshl_add_u64 v[238:239], s[34:35], 0, v[172:173]
	s_add_i32 m0, s79, 0x2000
	s_nop 0
	global_load_lds_dwordx4 v[238:239], off
	v_lshl_add_u64 v[238:239], s[16:17], 0, v[164:165]
	s_mov_b32 m0, s27
	s_nop 0
	global_load_lds_dwordx4 v[238:239], off
	s_mov_b32 m0, s39
	s_nop 0
	global_load_lds_dwordx4 v[240:241], off
	s_waitcnt vmcnt(8)
	s_waitcnt lgkmcnt(0)
	s_barrier
; #define PG8_STAGE(bufoff, gbase, voff) do { _Pragma("unroll") for (int _i = 0; _i < 2; ++_i) \
;         __builtin_amdgcn_global_load_lds((const unsigned*)((const char*)(gbase) + (voff)[_i]), (PG8_LAS unsigned*)(lds + (bufoff) + ldsw + _i * 8192), 16, 0, 0); } while (0)
; #define PG8_LDA(dst, b, h) do { _Pragma("unroll") for (int m = 0; m < 4; ++m) _Pragma("unroll") for (int k = 0; k < 2; ++k) dst[m][k] = *(const PG8_LAS bf16x8*)(lds + PG8_SA(b, h) + aoff + m * 2048 + k * 1024); } while (0)
; #define PG8_LDB(dst, b, h) do { _Pragma("unroll") for (int n = 0; n < 2; ++n) _Pragma("unroll") for (int k = 0; k < 2; ++k) dst[n][k] = *(const PG8_LAS bf16x8*)(lds + PG8_SB(b, h) + boff + n * 2048 + k * 1024); } while (0)
; #define PG8_MMA(ai, bj, At, Bt) do { __builtin_amdgcn_s_setprio(1); _Pragma("unroll") for (int m = 0; m < 4; ++m) _Pragma("unroll") for (int n = 0; n < 2; ++n) _Pragma("unroll") for (int k = 0; k < 2; ++k) \
;         acc[ai][bj][m][n] = __builtin_amdgcn_mfma_f32_16x16x32_bf16(Bt[n][k], At[m][k], acc[ai][bj][m][n], 0, 0, 0); __builtin_amdgcn_s_setprio(0); } while (0)
; #define PG8_WAIT_V(n) asm volatile("s_waitcnt vmcnt(" #n ")" ::: "memory")
; #define PG8_WAIT_L(n) asm volatile("s_waitcnt lgkmcnt(" #n ")" ::: "memory")
; #define PG8_BAR __builtin_amdgcn_s_barrier()
; #define PG8_SCHED __builtin_amdgcn_sched_barrier(0)
; template <class Epi, class Sched, bool ALIGN_EPI = false, bool SP2 = false>
; __device__ __forceinline__ void gemm_phase(PG8_LAS unsigned char* lds, const Gemm g, const Sched& S, const Epi& E) {
;     ...
;             PG8_WAIT_V(8); PG8_WAIT_L(0); PG8_BAR; PG8_MMA(1, 0, At, B0); PG8_MMA(1, 1, At, B1); PG8_BAR; PG8_SCHED;
;             PG8_LDB(B0, 1, 0); PG8_LDB(B1, 1, 1); PG8_SCHED; PG8_LDA(At, 1, 0); PG8_STAGE(PG8_SA(0, 1), a2 + hstep, voffA);
;             PG8_WAIT_V(8); PG8_WAIT_L(0); PG8_BAR; PG8_MMA(0, 0, At, B0); PG8_MMA(0, 1, At, B1); PG8_BAR; PG8_SCHED;
	v_mfma_f32_16x16x32_bf16 v[70:73], v[6:9], v[206:209], v[70:73]
	v_mfma_f32_16x16x32_bf16 v[70:73], v[2:5], v[202:205], v[70:73]
	v_mfma_f32_16x16x32_bf16 v[54:57], v[2:5], v[214:217], v[54:57]
	v_mfma_f32_16x16x32_bf16 v[54:57], v[6:9], v[218:221], v[54:57]
	v_mfma_f32_16x16x32_bf16 v[38:41], v[6:9], v[226:229], v[38:41]
	v_mfma_f32_16x16x32_bf16 v[38:41], v[2:5], v[222:225], v[38:41]
	v_mfma_f32_16x16x32_bf16 v[2:5], v[2:5], v[230:233], v[22:25]
	v_mfma_f32_16x16x32_bf16 v[2:5], v[6:9], v[234:237], v[2:5]
	v_mfma_f32_16x16x32_bf16 v[6:9], v[142:145], v[234:237], v[18:21]
	v_mfma_f32_16x16x32_bf16 v[6:9], v[138:141], v[230:233], v[6:9]
	v_mfma_f32_16x16x32_bf16 v[66:69], v[138:141], v[202:205], v[66:69]
	v_mfma_f32_16x16x32_bf16 v[66:69], v[142:145], v[206:209], v[66:69]
	v_mfma_f32_16x16x32_bf16 v[50:53], v[142:145], v[218:221], v[50:53]
	v_mfma_f32_16x16x32_bf16 v[50:53], v[138:141], v[214:217], v[50:53]
	v_mfma_f32_16x16x32_bf16 v[34:37], v[138:141], v[222:225], v[34:37]
	v_mfma_f32_16x16x32_bf16 v[34:37], v[142:145], v[226:229], v[34:37]
	v_mfma_f32_16x16x32_bf16 v[18:21], v[150:153], v[226:229], v[30:33]
	v_mfma_f32_16x16x32_bf16 v[30:33], v[146:149], v[222:225], v[18:21]
	v_mfma_f32_16x16x32_bf16 v[14:17], v[146:149], v[230:233], v[14:17]
	v_mfma_f32_16x16x32_bf16 v[14:17], v[150:153], v[234:237], v[14:17]
	v_mfma_f32_16x16x32_bf16 v[18:21], v[150:153], v[206:209], v[62:65]
	v_mfma_f32_16x16x32_bf16 v[62:65], v[146:149], v[202:205], v[18:21]
	v_mfma_f32_16x16x32_bf16 v[18:21], v[146:149], v[214:217], v[46:49]
	v_mfma_f32_16x16x32_bf16 v[46:49], v[150:153], v[218:221], v[18:21]
	v_mfma_f32_16x16x32_bf16 v[18:21], v[158:161], v[218:221], v[42:45]
	v_mfma_f32_16x16x32_bf16 v[42:45], v[154:157], v[214:217], v[18:21]
	v_mfma_f32_16x16x32_bf16 v[18:21], v[154:157], v[222:225], v[26:29]
	v_mfma_f32_16x16x32_bf16 v[26:29], v[158:161], v[226:229], v[18:21]
	v_mfma_f32_16x16x32_bf16 v[10:13], v[158:161], v[234:237], v[10:13]
	v_mfma_f32_16x16x32_bf16 v[10:13], v[154:157], v[230:233], v[10:13]
	v_mfma_f32_16x16x32_bf16 v[18:21], v[154:157], v[202:205], v[58:61]
	v_mfma_f32_16x16x32_bf16 v[58:61], v[158:161], v[206:209], v[18:21]
	s_barrier
	s_add_i32 s34, 0, 0x18000
	s_add_i32 s35, 0, 0x1c000
	v_add_u32_e32 v142, s34, v179
	v_add_u32_e32 v158, s35, v179
	ds_read_b128 v[18:21], v142
	ds_read_b128 v[22:25], v142 offset:1024
	ds_read_b128 v[138:141], v142 offset:2048
	ds_read_b128 v[142:145], v142 offset:3072
	ds_read_b128 v[146:149], v158
	ds_read_b128 v[150:153], v158 offset:1024
	ds_read_b128 v[154:157], v158 offset:2048
	ds_read_b128 v[158:161], v158 offset:3072
	s_add_u32 s16, s16, 0x100000
	s_addc_u32 s17, s17, 0
	s_mov_b32 m0, s71
	v_lshl_add_u64 v[242:243], s[16:17], 0, v[164:165]
	ds_read_b128 v[202:205], v199 offset:32768
	ds_read_b128 v[206:209], v199 offset:33792
	ds_read_b128 v[214:217], v199 offset:34816
	ds_read_b128 v[218:221], v199 offset:35840
	ds_read_b128 v[222:225], v199 offset:36864
	ds_read_b128 v[226:229], v199 offset:37888
	ds_read_b128 v[230:233], v199 offset:38912
	ds_read_b128 v[234:237], v199 offset:39936
	global_load_lds_dwordx4 v[242:243], off
	v_lshl_add_u64 v[242:243], s[16:17], 0, v[170:171]
	s_mov_b32 m0, s87
	s_nop 0
	global_load_lds_dwordx4 v[242:243], off
	s_waitcnt vmcnt(8)
	s_waitcnt lgkmcnt(0)
	s_barrier
	v_mfma_f32_16x16x32_bf16 v[134:137], v[18:21], v[202:205], v[134:137]
	v_mfma_f32_16x16x32_bf16 v[134:137], v[22:25], v[206:209], v[134:137]
	v_mfma_f32_16x16x32_bf16 v[118:121], v[22:25], v[218:221], v[118:121]
	v_mfma_f32_16x16x32_bf16 v[118:121], v[18:21], v[214:217], v[118:121]
	v_mfma_f32_16x16x32_bf16 v[102:105], v[18:21], v[222:225], v[102:105]
	v_mfma_f32_16x16x32_bf16 v[102:105], v[22:25], v[226:229], v[102:105]
	v_mfma_f32_16x16x32_bf16 v[86:89], v[22:25], v[234:237], v[86:89]
	v_mfma_f32_16x16x32_bf16 v[86:89], v[18:21], v[230:233], v[86:89]
	v_mfma_f32_16x16x32_bf16 v[82:85], v[138:141], v[230:233], v[82:85]
	v_mfma_f32_16x16x32_bf16 v[82:85], v[142:145], v[234:237], v[82:85]
	v_mfma_f32_16x16x32_bf16 v[130:133], v[142:145], v[206:209], v[130:133]
	v_mfma_f32_16x16x32_bf16 v[130:133], v[138:141], v[202:205], v[130:133]
	v_mfma_f32_16x16x32_bf16 v[114:117], v[138:141], v[214:217], v[114:117]
	v_mfma_f32_16x16x32_bf16 v[114:117], v[142:145], v[218:221], v[114:117]
	v_mfma_f32_16x16x32_bf16 v[98:101], v[142:145], v[226:229], v[98:101]
	v_mfma_f32_16x16x32_bf16 v[98:101], v[138:141], v[222:225], v[98:101]
	v_mfma_f32_16x16x32_bf16 v[94:97], v[146:149], v[222:225], v[94:97]
	v_mfma_f32_16x16x32_bf16 v[94:97], v[150:153], v[226:229], v[94:97]
	v_mfma_f32_16x16x32_bf16 v[126:129], v[150:153], v[206:209], v[126:129]
	v_mfma_f32_16x16x32_bf16 v[126:129], v[146:149], v[202:205], v[126:129]
	v_mfma_f32_16x16x32_bf16 v[110:113], v[146:149], v[214:217], v[110:113]
	v_mfma_f32_16x16x32_bf16 v[110:113], v[150:153], v[218:221], v[110:113]
	v_mfma_f32_16x16x32_bf16 v[78:81], v[150:153], v[234:237], v[78:81]
	v_mfma_f32_16x16x32_bf16 v[78:81], v[146:149], v[230:233], v[78:81]
	v_mfma_f32_16x16x32_bf16 v[74:77], v[154:157], v[230:233], v[74:77]
	v_mfma_f32_16x16x32_bf16 v[74:77], v[158:161], v[234:237], v[74:77]
	v_mfma_f32_16x16x32_bf16 v[122:125], v[158:161], v[206:209], v[122:125]
	v_mfma_f32_16x16x32_bf16 v[122:125], v[154:157], v[202:205], v[122:125]
	v_mfma_f32_16x16x32_bf16 v[106:109], v[154:157], v[214:217], v[106:109]
	v_mfma_f32_16x16x32_bf16 v[106:109], v[158:161], v[218:221], v[106:109]
	v_mfma_f32_16x16x32_bf16 v[90:93], v[158:161], v[226:229], v[90:93]
	v_mfma_f32_16x16x32_bf16 v[90:93], v[154:157], v[222:225], v[90:93]
	s_barrier
; #define PG8_STAGE(bufoff, gbase, voff) do { _Pragma("unroll") for (int _i = 0; _i < 2; ++_i) \
;         __builtin_amdgcn_global_load_lds((const unsigned*)((const char*)(gbase) + (voff)[_i]), (PG8_LAS unsigned*)(lds + (bufoff) + ldsw + _i * 8192), 16, 0, 0); } while (0)
; #define PG8_LDA(dst, b, h) do { _Pragma("unroll") for (int m = 0; m < 4; ++m) _Pragma("unroll") for (int k = 0; k < 2; ++k) dst[m][k] = *(const PG8_LAS bf16x8*)(lds + PG8_SA(b, h) + aoff + m * 2048 + k * 1024); } while (0)
; #define PG8_MMA(ai, bj, At, Bt) do { __builtin_amdgcn_s_setprio(1); _Pragma("unroll") for (int m = 0; m < 4; ++m) _Pragma("unroll") for (int n = 0; n < 2; ++n) _Pragma("unroll") for (int k = 0; k < 2; ++k) \
;         acc[ai][bj][m][n] = __builtin_amdgcn_mfma_f32_16x16x32_bf16(Bt[n][k], At[m][k], acc[ai][bj][m][n], 0, 0, 0); __builtin_amdgcn_s_setprio(0); } while (0)
; #define PG8_WAIT_V(n) asm volatile("s_waitcnt vmcnt(" #n ")" ::: "memory")
; #define PG8_WAIT_L(n) asm volatile("s_waitcnt lgkmcnt(" #n ")" ::: "memory")
; #define PG8_BAR __builtin_amdgcn_s_barrier()
; #define PG8_SCHED __builtin_amdgcn_sched_barrier(0)
; template <class Epi, class Sched, bool ALIGN_EPI = false, bool SP2 = false>
; __device__ __forceinline__ void gemm_phase(PG8_LAS unsigned char* lds, const Gemm g, const Sched& S, const Epi& E) {
;     ...
;         for (int t = 0; t < nt; t += 2) {
;     ...
;             PG8_LDA(At, 1, 1); PG8_STAGE(PG8_SB(1, 0), b3, voffB); PG8_STAGE(PG8_SB(1, 1), b3 + hstep, voffB); PG8_STAGE(PG8_SA(1, 0), a3, voffA);
;             PG8_WAIT_V(8); PG8_WAIT_L(0); PG8_BAR; PG8_MMA(1, 0, At, B0); PG8_MMA(1, 1, At, B1); PG8_BAR; PG8_SCHED;
	s_add_i32 s16, s34, s25
	v_lshl_add_u64 v[162:163], v[162:163], 0, s[46:47]
	s_mov_b32 m0, s16
	ds_read_b128 v[202:205], v199 offset:49152
	ds_read_b128 v[206:209], v199 offset:50176
	ds_read_b128 v[214:217], v199 offset:51200
	ds_read_b128 v[218:221], v199 offset:52224
	ds_read_b128 v[222:225], v199 offset:53248
	ds_read_b128 v[226:229], v199 offset:54272
	ds_read_b128 v[230:233], v199 offset:55296
	ds_read_b128 v[234:237], v199 offset:56320
	global_load_lds_dwordx4 v[162:163], off
	s_add_i32 m0, s16, 0x2000
	s_add_u32 s14, s14, 0x100080
	v_lshl_add_u64 v[162:163], v[210:211], 0, s[46:47]
	s_addc_u32 s15, s15, 0
	s_add_i32 s16, s35, s25
	global_load_lds_dwordx4 v[162:163], off
	v_lshl_add_u64 v[162:163], s[14:15], 0, v[168:169]
	s_mov_b32 m0, s16
	s_nop 0
	global_load_lds_dwordx4 v[162:163], off
	v_lshl_add_u64 v[162:163], s[14:15], 0, v[172:173]
	s_add_i32 m0, s16, 0x2000
	s_nop 0
	global_load_lds_dwordx4 v[162:163], off
	v_lshl_add_u64 v[162:163], v[238:239], 0, s[46:47]
	s_mov_b32 m0, s95
	s_nop 0
	global_load_lds_dwordx4 v[162:163], off
	v_lshl_add_u64 v[162:163], v[240:241], 0, s[46:47]
	s_mov_b32 m0, s96
	s_nop 0
	global_load_lds_dwordx4 v[162:163], off
	s_waitcnt vmcnt(8)
	s_waitcnt lgkmcnt(0)
	s_barrier
	v_mfma_f32_16x16x32_bf16 v[70:73], v[18:21], v[202:205], v[70:73]
	v_mfma_f32_16x16x32_bf16 v[70:73], v[22:25], v[206:209], v[70:73]
	v_mfma_f32_16x16x32_bf16 v[54:57], v[22:25], v[218:221], v[54:57]
	v_mfma_f32_16x16x32_bf16 v[54:57], v[18:21], v[214:217], v[54:57]
	v_mfma_f32_16x16x32_bf16 v[38:41], v[18:21], v[222:225], v[38:41]
	v_mfma_f32_16x16x32_bf16 v[38:41], v[22:25], v[226:229], v[38:41]
	v_mfma_f32_16x16x32_bf16 v[2:5], v[22:25], v[234:237], v[2:5]
	v_mfma_f32_16x16x32_bf16 v[22:25], v[18:21], v[230:233], v[2:5]
	v_mfma_f32_16x16x32_bf16 v[2:5], v[138:141], v[230:233], v[6:9]
	v_mfma_f32_16x16x32_bf16 v[18:21], v[142:145], v[234:237], v[2:5]
	v_mfma_f32_16x16x32_bf16 v[66:69], v[142:145], v[206:209], v[66:69]
	v_mfma_f32_16x16x32_bf16 v[66:69], v[138:141], v[202:205], v[66:69]
	v_mfma_f32_16x16x32_bf16 v[50:53], v[138:141], v[214:217], v[50:53]
	v_mfma_f32_16x16x32_bf16 v[50:53], v[142:145], v[218:221], v[50:53]
	v_mfma_f32_16x16x32_bf16 v[34:37], v[142:145], v[226:229], v[34:37]
	v_mfma_f32_16x16x32_bf16 v[34:37], v[138:141], v[222:225], v[34:37]
	v_mfma_f32_16x16x32_bf16 v[2:5], v[146:149], v[222:225], v[30:33]
	v_mfma_f32_16x16x32_bf16 v[30:33], v[150:153], v[226:229], v[2:5]
	v_mfma_f32_16x16x32_bf16 v[2:5], v[150:153], v[234:237], v[14:17]
	v_mfma_f32_16x16x32_bf16 v[14:17], v[146:149], v[230:233], v[2:5]
	v_mfma_f32_16x16x32_bf16 v[2:5], v[146:149], v[202:205], v[62:65]
	v_mfma_f32_16x16x32_bf16 v[62:65], v[150:153], v[206:209], v[2:5]
	v_mfma_f32_16x16x32_bf16 v[2:5], v[150:153], v[218:221], v[46:49]
	v_mfma_f32_16x16x32_bf16 v[46:49], v[146:149], v[214:217], v[2:5]
	v_mfma_f32_16x16x32_bf16 v[2:5], v[154:157], v[214:217], v[42:45]
	v_mfma_f32_16x16x32_bf16 v[42:45], v[158:161], v[218:221], v[2:5]
	v_mfma_f32_16x16x32_bf16 v[2:5], v[158:161], v[226:229], v[26:29]
	v_mfma_f32_16x16x32_bf16 v[26:29], v[154:157], v[222:225], v[2:5]
	v_mfma_f32_16x16x32_bf16 v[2:5], v[154:157], v[230:233], v[10:13]
	v_mfma_f32_16x16x32_bf16 v[10:13], v[158:161], v[234:237], v[2:5]
	v_mfma_f32_16x16x32_bf16 v[2:5], v[158:161], v[206:209], v[58:61]
	v_mfma_f32_16x16x32_bf16 v[58:61], v[154:157], v[202:205], v[2:5]
	s_barrier
	s_add_i32 s33, s33, 2
	s_add_u32 s12, s12, 0x100
	s_addc_u32 s13, s13, 0
	s_add_u32 s29, s29, 0x100
	s_addc_u32 s30, s30, 0
	s_cmp_gt_u32 s33, 61
	s_cbranch_scc0 .LBB0_139
	s_and_b64 vcc, exec, s[48:49]
	s_cbranch_vccz .LBB0_142
	s_barrier

; #define PG8_STAGE(bufoff, gbase, voff) do { _Pragma("unroll") for (int _i = 0; _i < 2; ++_i) \
;         __builtin_amdgcn_global_load_lds((const unsigned*)((const char*)(gbase) + (voff)[_i]), (PG8_LAS unsigned*)(lds + (bufoff) + ldsw + _i * 8192), 16, 0, 0); } while (0)
; #define PG8_LDA(dst, b, h) do { _Pragma("unroll") for (int m = 0; m < 4; ++m) _Pragma("unroll") for (int k = 0; k < 2; ++k) dst[m][k] = *(const PG8_LAS bf16x8*)(lds + PG8_SA(b, h) + aoff + m * 2048 + k * 1024); } while (0)
; #define PG8_LDB(dst, b, h) do { _Pragma("unroll") for (int n = 0; n < 2; ++n) _Pragma("unroll") for (int k = 0; k < 2; ++k) dst[n][k] = *(const PG8_LAS bf16x8*)(lds + PG8_SB(b, h) + boff + n * 2048 + k * 1024); } while (0)
; #define PG8_MMA(ai, bj, At, Bt) do { __builtin_amdgcn_s_setprio(1); _Pragma("unroll") for (int m = 0; m < 4; ++m) _Pragma("unroll") for (int n = 0; n < 2; ++n) _Pragma("unroll") for (int k = 0; k < 2; ++k) \
;         acc[ai][bj][m][n] = __builtin_amdgcn_mfma_f32_16x16x32_bf16(Bt[n][k], At[m][k], acc[ai][bj][m][n], 0, 0, 0); __builtin_amdgcn_s_setprio(0); } while (0)
; #define PG8_WAIT_V(n) asm volatile("s_waitcnt vmcnt(" #n ")" ::: "memory")
; #define PG8_WAIT_L(n) asm volatile("s_waitcnt lgkmcnt(" #n ")" ::: "memory")
; #define PG8_BAR __builtin_amdgcn_s_barrier()
; #define PG8_SCHED __builtin_amdgcn_sched_barrier(0)
; template <class Epi, class Sched, bool ALIGN_EPI = false, bool SP2 = false>
; __device__ __forceinline__ void gemm_phase(PG8_LAS unsigned char* lds, const Gemm g, const Sched& S, const Epi& E) {
;     ...
;             PG8_LDB(B0, 0, 0); PG8_LDB(B1, 0, 1); PG8_SCHED; PG8_LDA(At, 0, 0); PG8_STAGE(PG8_SA(1, 1), a1 + hstep, voffA);
;             PG8_WAIT_V(8); PG8_WAIT_L(0); PG8_BAR; PG8_MMA(0, 0, At, B0); PG8_MMA(0, 1, At, B1); PG8_BAR; PG8_SCHED;
;             PG8_LDA(At, 0, 1); PG8_STAGE(PG8_SB(0, 0), b2, voffB); PG8_STAGE(PG8_SB(0, 1), b2 + hstep, voffB); PG8_STAGE(PG8_SA(0, 0), a2, voffA);
;             PG8_WAIT_V(8); PG8_WAIT_L(0); PG8_BAR; PG8_MMA(1, 0, At, B0); PG8_MMA(1, 1, At, B1); PG8_BAR; PG8_SCHED;
.LBB0_592:
	s_or_b32 s10, s52, 1
	s_lshl_b64 s[96:97], s[10:11], 7
	s_add_i32 s10, s52, 2
	s_lshl_b64 s[54:55], s[10:11], 7
	s_cmp_lg_u32 s52, s94
	s_cselect_b32 s52, s54, 0
	s_cselect_b32 s53, s55, 0
	s_add_u32 s54, s50, s52
	s_addc_u32 s55, s51, s53
	s_add_i32 s95, 0, 0x10000
	v_add_u32_e32 v87, s95, v85
	ds_read_b128 v[88:91], v87
	ds_read_b128 v[92:95], v87 offset:1024
	ds_read_b128 v[100:103], v87 offset:2048
	ds_read_b128 v[104:107], v87 offset:3072
	s_add_u32 s52, s48, s52
	s_addc_u32 s53, s49, s53
	s_add_u32 s96, s50, s96
	s_addc_u32 s97, s51, s97
	s_add_u32 s96, s96, 0x100000
	s_addc_u32 s97, s97, 0
	v_lshl_add_u64 v[96:97], s[96:97], 0, v[66:67]
	s_add_i32 m0, s17, 0xc000
	ds_read_b128 v[108:111], v86
	ds_read_b128 v[112:115], v86 offset:1024
	ds_read_b128 v[116:119], v86 offset:2048
	ds_read_b128 v[120:123], v86 offset:3072
	ds_read_b128 v[124:127], v86 offset:4096
	ds_read_b128 v[128:131], v86 offset:5120
	ds_read_b128 v[132:135], v86 offset:6144
	ds_read_b128 v[136:139], v86 offset:7168
	global_load_lds_dwordx4 v[96:97], off
	v_lshl_add_u64 v[96:97], s[96:97], 0, v[76:77]
	s_add_i32 m0, s17, 0xe000
	s_nop 0
	global_load_lds_dwordx4 v[96:97], off
	s_waitcnt vmcnt(8)
	s_waitcnt lgkmcnt(0)
	s_barrier
	v_mfma_f32_16x16x32_bf16 v[62:65], v[88:91], v[108:111], v[62:65]
	v_mfma_f32_16x16x32_bf16 v[62:65], v[92:95], v[112:115], v[62:65]
	v_mfma_f32_16x16x32_bf16 v[54:57], v[92:95], v[120:123], v[54:57]
	v_mfma_f32_16x16x32_bf16 v[54:57], v[88:91], v[116:119], v[54:57]
	v_mfma_f32_16x16x32_bf16 v[46:49], v[88:91], v[124:127], v[46:49]
	v_mfma_f32_16x16x32_bf16 v[46:49], v[92:95], v[128:131], v[46:49]
	v_mfma_f32_16x16x32_bf16 v[38:41], v[92:95], v[136:139], v[38:41]
	v_mfma_f32_16x16x32_bf16 v[38:41], v[88:91], v[132:135], v[38:41]
	v_mfma_f32_16x16x32_bf16 v[34:37], v[100:103], v[132:135], v[34:37]
	v_mfma_f32_16x16x32_bf16 v[34:37], v[104:107], v[136:139], v[34:37]
	v_mfma_f32_16x16x32_bf16 v[58:61], v[104:107], v[112:115], v[58:61]
	v_mfma_f32_16x16x32_bf16 v[58:61], v[100:103], v[108:111], v[58:61]
	v_mfma_f32_16x16x32_bf16 v[50:53], v[100:103], v[116:119], v[50:53]
	v_mfma_f32_16x16x32_bf16 v[50:53], v[104:107], v[120:123], v[50:53]
	v_mfma_f32_16x16x32_bf16 v[42:45], v[104:107], v[128:131], v[42:45]
	v_mfma_f32_16x16x32_bf16 v[42:45], v[100:103], v[124:127], v[42:45]
	s_barrier
	s_add_i32 s95, s95, s29
	v_lshl_add_u64 v[96:97], s[52:53], 0, v[78:79]
	s_mov_b32 m0, s95
	ds_read_b128 v[108:111], v86 offset:16384
	ds_read_b128 v[112:115], v86 offset:17408
	ds_read_b128 v[116:119], v86 offset:18432
	ds_read_b128 v[120:123], v86 offset:19456
	ds_read_b128 v[124:127], v86 offset:20480
	ds_read_b128 v[128:131], v86 offset:21504
	ds_read_b128 v[132:135], v86 offset:22528
	ds_read_b128 v[136:139], v86 offset:23552
	global_load_lds_dwordx4 v[96:97], off
	s_add_i32 m0, s95, 0x2000
	s_add_u32 s96, s52, 0x100000
	v_lshl_add_u64 v[140:141], s[52:53], 0, v[74:75]
	s_addc_u32 s97, s53, 0
	global_load_lds_dwordx4 v[140:141], off
	v_lshl_add_u64 v[142:143], s[96:97], 0, v[78:79]
	s_mov_b32 m0, s30
	v_lshl_add_u64 v[144:145], s[54:55], 0, v[76:77]
	global_load_lds_dwordx4 v[142:143], off
	v_lshl_add_u64 v[142:143], s[96:97], 0, v[74:75]
	s_mov_b32 m0, s33
	s_nop 0
	global_load_lds_dwordx4 v[142:143], off
	v_lshl_add_u64 v[142:143], s[54:55], 0, v[66:67]
	s_mov_b32 m0, s17
	s_nop 0
	global_load_lds_dwordx4 v[142:143], off
	s_mov_b32 m0, s34
	s_nop 0
	global_load_lds_dwordx4 v[144:145], off
	s_waitcnt vmcnt(8)
	s_waitcnt lgkmcnt(0)
	s_barrier
	v_mfma_f32_16x16x32_bf16 v[30:33], v[88:91], v[108:111], v[30:33]
	v_mfma_f32_16x16x32_bf16 v[30:33], v[92:95], v[112:115], v[30:33]
	v_mfma_f32_16x16x32_bf16 v[22:25], v[92:95], v[120:123], v[22:25]
	v_mfma_f32_16x16x32_bf16 v[22:25], v[88:91], v[116:119], v[22:25]
	v_mfma_f32_16x16x32_bf16 v[14:17], v[88:91], v[124:127], v[14:17]
	v_mfma_f32_16x16x32_bf16 v[14:17], v[92:95], v[128:131], v[14:17]
	v_mfma_f32_16x16x32_bf16 v[6:9], v[92:95], v[136:139], v[6:9]
	v_mfma_f32_16x16x32_bf16 v[6:9], v[88:91], v[132:135], v[6:9]
	v_mfma_f32_16x16x32_bf16 v[2:5], v[100:103], v[132:135], v[2:5]
	v_mfma_f32_16x16x32_bf16 v[2:5], v[104:107], v[136:139], v[2:5]
	v_mfma_f32_16x16x32_bf16 v[26:29], v[104:107], v[112:115], v[26:29]
	v_mfma_f32_16x16x32_bf16 v[26:29], v[100:103], v[108:111], v[26:29]
	v_mfma_f32_16x16x32_bf16 v[18:21], v[100:103], v[116:119], v[18:21]
	v_mfma_f32_16x16x32_bf16 v[18:21], v[104:107], v[120:123], v[18:21]
	v_mfma_f32_16x16x32_bf16 v[10:13], v[104:107], v[128:131], v[10:13]
	v_mfma_f32_16x16x32_bf16 v[10:13], v[100:103], v[124:127], v[10:13]
	s_barrier
; #define PG8_STAGE(bufoff, gbase, voff) do { _Pragma("unroll") for (int _i = 0; _i < 2; ++_i) \
;         __builtin_amdgcn_global_load_lds((const unsigned*)((const char*)(gbase) + (voff)[_i]), (PG8_LAS unsigned*)(lds + (bufoff) + ldsw + _i * 8192), 16, 0, 0); } while (0)
; #define PG8_LDA(dst, b, h) do { _Pragma("unroll") for (int m = 0; m < 4; ++m) _Pragma("unroll") for (int k = 0; k < 2; ++k) dst[m][k] = *(const PG8_LAS bf16x8*)(lds + PG8_SA(b, h) + aoff + m * 2048 + k * 1024); } while (0)
; #define PG8_LDB(dst, b, h) do { _Pragma("unroll") for (int n = 0; n < 2; ++n) _Pragma("unroll") for (int k = 0; k < 2; ++k) dst[n][k] = *(const PG8_LAS bf16x8*)(lds + PG8_SB(b, h) + boff + n * 2048 + k * 1024); } while (0)
; #define PG8_MMA(ai, bj, At, Bt) do { __builtin_amdgcn_s_setprio(1); _Pragma("unroll") for (int m = 0; m < 4; ++m) _Pragma("unroll") for (int n = 0; n < 2; ++n) _Pragma("unroll") for (int k = 0; k < 2; ++k) \
;         acc[ai][bj][m][n] = __builtin_amdgcn_mfma_f32_16x16x32_bf16(Bt[n][k], At[m][k], acc[ai][bj][m][n], 0, 0, 0); __builtin_amdgcn_s_setprio(0); } while (0)
; #define PG8_WAIT_V(n) asm volatile("s_waitcnt vmcnt(" #n ")" ::: "memory")
; #define PG8_WAIT_L(n) asm volatile("s_waitcnt lgkmcnt(" #n ")" ::: "memory")
; #define PG8_BAR __builtin_amdgcn_s_barrier()
; #define PG8_SCHED __builtin_amdgcn_sched_barrier(0)
; template <class Epi, class Sched, bool ALIGN_EPI = false, bool SP2 = false>
; __device__ __forceinline__ void gemm_phase(PG8_LAS unsigned char* lds, const Gemm g, const Sched& S, const Epi& E) {
;     ...
;             PG8_LDB(B0, 1, 0); PG8_LDB(B1, 1, 1); PG8_SCHED; PG8_LDA(At, 1, 0); PG8_STAGE(PG8_SA(0, 1), a2 + hstep, voffA);
;             PG8_WAIT_V(8); PG8_WAIT_L(0); PG8_BAR; PG8_MMA(0, 0, At, B0); PG8_MMA(0, 1, At, B1); PG8_BAR; PG8_SCHED;
;             PG8_LDA(At, 1, 1); PG8_STAGE(PG8_SB(1, 0), b3, voffB); PG8_STAGE(PG8_SB(1, 1), b3 + hstep, voffB); PG8_STAGE(PG8_SA(1, 0), a3, voffA);
;             PG8_WAIT_V(8); PG8_WAIT_L(0); PG8_BAR; PG8_MMA(1, 0, At, B0); PG8_MMA(1, 1, At, B1); PG8_BAR; PG8_SCHED;
; __global__ void __launch_bounds__(NTHREADS, 2) fwd_kernel(Args args) {
;     ...
;       for (;;) { const int c = q_next(F, CW_DQ3); if (c >= 204 + 64 + 64 + 64 + 256) break;
	s_add_i32 s95, 0, 0x18000
	v_add_u32_e32 v87, s95, v85
	ds_read_b128 v[88:91], v87
	ds_read_b128 v[92:95], v87 offset:1024
	ds_read_b128 v[100:103], v87 offset:2048
	ds_read_b128 v[104:107], v87 offset:3072
	s_add_u32 s54, s54, 0x100000
	s_addc_u32 s55, s55, 0
	s_mov_b32 m0, s35
	v_lshl_add_u64 v[146:147], s[54:55], 0, v[66:67]
	ds_read_b128 v[108:111], v86 offset:32768
	ds_read_b128 v[112:115], v86 offset:33792
	ds_read_b128 v[116:119], v86 offset:34816
	ds_read_b128 v[120:123], v86 offset:35840
	ds_read_b128 v[124:127], v86 offset:36864
	ds_read_b128 v[128:131], v86 offset:37888
	ds_read_b128 v[132:135], v86 offset:38912
	ds_read_b128 v[136:139], v86 offset:39936
	global_load_lds_dwordx4 v[146:147], off
	v_lshl_add_u64 v[146:147], s[54:55], 0, v[76:77]
	s_mov_b32 m0, s88
	s_nop 0
	global_load_lds_dwordx4 v[146:147], off
	s_waitcnt vmcnt(8)
	s_waitcnt lgkmcnt(0)
	s_barrier
	v_mfma_f32_16x16x32_bf16 v[62:65], v[88:91], v[108:111], v[62:65]
	v_mfma_f32_16x16x32_bf16 v[62:65], v[92:95], v[112:115], v[62:65]
	v_mfma_f32_16x16x32_bf16 v[54:57], v[92:95], v[120:123], v[54:57]
	v_mfma_f32_16x16x32_bf16 v[54:57], v[88:91], v[116:119], v[54:57]
	v_mfma_f32_16x16x32_bf16 v[46:49], v[88:91], v[124:127], v[46:49]
	v_mfma_f32_16x16x32_bf16 v[46:49], v[92:95], v[128:131], v[46:49]
	v_mfma_f32_16x16x32_bf16 v[38:41], v[92:95], v[136:139], v[38:41]
	v_mfma_f32_16x16x32_bf16 v[38:41], v[88:91], v[132:135], v[38:41]
	v_mfma_f32_16x16x32_bf16 v[34:37], v[100:103], v[132:135], v[34:37]
	v_mfma_f32_16x16x32_bf16 v[34:37], v[104:107], v[136:139], v[34:37]
	v_mfma_f32_16x16x32_bf16 v[58:61], v[104:107], v[112:115], v[58:61]
	v_mfma_f32_16x16x32_bf16 v[58:61], v[100:103], v[108:111], v[58:61]
	v_mfma_f32_16x16x32_bf16 v[50:53], v[100:103], v[116:119], v[50:53]
	v_mfma_f32_16x16x32_bf16 v[50:53], v[104:107], v[120:123], v[50:53]
	v_mfma_f32_16x16x32_bf16 v[42:45], v[104:107], v[128:131], v[42:45]
	v_mfma_f32_16x16x32_bf16 v[42:45], v[100:103], v[124:127], v[42:45]
	s_barrier
	s_add_i32 s54, s95, s29
	v_lshl_add_u64 v[96:97], v[96:97], 0, s[14:15]
	s_mov_b32 m0, s54
	ds_read_b128 v[108:111], v86 offset:49152
	ds_read_b128 v[112:115], v86 offset:50176
	ds_read_b128 v[116:119], v86 offset:51200
	ds_read_b128 v[120:123], v86 offset:52224
	ds_read_b128 v[124:127], v86 offset:53248
	ds_read_b128 v[128:131], v86 offset:54272
	ds_read_b128 v[132:135], v86 offset:55296
	ds_read_b128 v[136:139], v86 offset:56320
	global_load_lds_dwordx4 v[96:97], off
	s_add_i32 m0, s54, 0x2000
	s_add_u32 s52, s52, 0x100080
	v_lshl_add_u64 v[96:97], v[140:141], 0, s[14:15]
	s_addc_u32 s53, s53, 0
	global_load_lds_dwordx4 v[96:97], off
	v_lshl_add_u64 v[96:97], s[52:53], 0, v[78:79]
	s_mov_b32 m0, s92
	s_nop 0
	global_load_lds_dwordx4 v[96:97], off
	v_lshl_add_u64 v[96:97], s[52:53], 0, v[74:75]
	s_mov_b32 m0, s93
	s_nop 0
	global_load_lds_dwordx4 v[96:97], off
	v_lshl_add_u64 v[96:97], v[142:143], 0, s[14:15]
	s_mov_b32 m0, s90
	s_nop 0
	global_load_lds_dwordx4 v[96:97], off
	v_lshl_add_u64 v[96:97], v[144:145], 0, s[14:15]
	s_mov_b32 m0, s91
	s_nop 0
	global_load_lds_dwordx4 v[96:97], off
	s_waitcnt vmcnt(8)
	s_waitcnt lgkmcnt(0)
	s_barrier
	v_mfma_f32_16x16x32_bf16 v[30:33], v[88:91], v[108:111], v[30:33]
	v_mfma_f32_16x16x32_bf16 v[30:33], v[92:95], v[112:115], v[30:33]
	v_mfma_f32_16x16x32_bf16 v[22:25], v[92:95], v[120:123], v[22:25]
	v_mfma_f32_16x16x32_bf16 v[22:25], v[88:91], v[116:119], v[22:25]
	v_mfma_f32_16x16x32_bf16 v[14:17], v[88:91], v[124:127], v[14:17]
	v_mfma_f32_16x16x32_bf16 v[14:17], v[92:95], v[128:131], v[14:17]
	v_mfma_f32_16x16x32_bf16 v[6:9], v[92:95], v[136:139], v[6:9]
	v_mfma_f32_16x16x32_bf16 v[6:9], v[88:91], v[132:135], v[6:9]
	v_mfma_f32_16x16x32_bf16 v[2:5], v[100:103], v[132:135], v[2:5]
	v_mfma_f32_16x16x32_bf16 v[2:5], v[104:107], v[136:139], v[2:5]
	v_mfma_f32_16x16x32_bf16 v[26:29], v[104:107], v[112:115], v[26:29]
	v_mfma_f32_16x16x32_bf16 v[26:29], v[100:103], v[108:111], v[26:29]
	v_mfma_f32_16x16x32_bf16 v[18:21], v[100:103], v[116:119], v[18:21]
	v_mfma_f32_16x16x32_bf16 v[18:21], v[104:107], v[120:123], v[18:21]
	v_mfma_f32_16x16x32_bf16 v[10:13], v[104:107], v[128:131], v[10:13]
	v_mfma_f32_16x16x32_bf16 v[10:13], v[100:103], v[124:127], v[10:13]
	s_barrier
	s_cmp_ge_u32 s10, s28
	s_mov_b32 s52, s10
	s_cbranch_scc0 .LBB0_592
	s_cmpk_lt_u32 s26, 0x100
	s_cbranch_scc0 .LBB0_482
	s_barrier
	s_branch .LBB0_482

; #define PG8_STAGE(bufoff, gbase, voff) do { _Pragma("unroll") for (int _i = 0; _i < 2; ++_i) \
;         __builtin_amdgcn_global_load_lds((const unsigned*)((const char*)(gbase) + (voff)[_i]), (PG8_LAS unsigned*)(lds + (bufoff) + ldsw + _i * 8192), 16, 0, 0); } while (0)
; #define PG8_LDA(dst, b, h) do { _Pragma("unroll") for (int m = 0; m < 4; ++m) _Pragma("unroll") for (int k = 0; k < 2; ++k) dst[m][k] = *(const PG8_LAS bf16x8*)(lds + PG8_SA(b, h) + aoff + m * 2048 + k * 1024); } while (0)
; #define PG8_LDB(dst, b, h) do { _Pragma("unroll") for (int n = 0; n < 2; ++n) _Pragma("unroll") for (int k = 0; k < 2; ++k) dst[n][k] = *(const PG8_LAS bf16x8*)(lds + PG8_SB(b, h) + boff + n * 2048 + k * 1024); } while (0)
; #define PG8_MMA(ai, bj, At, Bt) do { __builtin_amdgcn_s_setprio(1); _Pragma("unroll") for (int m = 0; m < 4; ++m) _Pragma("unroll") for (int n = 0; n < 2; ++n) _Pragma("unroll") for (int k = 0; k < 2; ++k) \
;         acc[ai][bj][m][n] = __builtin_amdgcn_mfma_f32_16x16x32_bf16(Bt[n][k], At[m][k], acc[ai][bj][m][n], 0, 0, 0); __builtin_amdgcn_s_setprio(0); } while (0)
; #define PG8_WAIT_V(n) asm volatile("s_waitcnt vmcnt(" #n ")" ::: "memory")
; #define PG8_WAIT_L(n) asm volatile("s_waitcnt lgkmcnt(" #n ")" ::: "memory")
; template <class Epi, class Sched, bool ALIGN_EPI = false, bool SP2 = false>
; __device__ __forceinline__ void gemm_phase(PG8_LAS unsigned char* lds, const Gemm g, const Sched& S, const Epi& E) {
;     ...
;             const bool last = (t == nt - 2);
;             const char* a1 = cA + (size_t)(t + 1) * kstep;
;             const char* a2 = last ? nA : cA + (size_t)(t + 2) * kstep; const char* b2 = last ? nB : cB + (size_t)(t + 2) * kstep;
;             const char* a3 = a2 + kstep; const char* b3 = b2 + kstep;
;             if (last && has_next) S.a_ready(nxt);
;             if constexpr (SP2) {
;             PG8_LDB(B0, 0, 0); PG8_LDB(B1, 0, 1); PG8_SCHED; PG8_LDA(At, 0, 0); PG8_STAGE(PG8_SA(1, 1), a1 + hstep, voffA);
;             PG8_WAIT_V(8); PG8_WAIT_L(0); PG8_BAR; PG8_MMA(0, 0, At, B0); PG8_MMA(0, 1, At, B1); PG8_BAR; PG8_SCHED;
;             PG8_LDA(At, 0, 1); PG8_STAGE(PG8_SB(0, 0), b2, voffB); PG8_STAGE(PG8_SB(0, 1), b2 + hstep, voffB); PG8_STAGE(PG8_SA(0, 0), a2, voffA);
;             PG8_WAIT_V(8); PG8_WAIT_L(0); PG8_BAR; PG8_MMA(1, 0, At, B0); PG8_MMA(1, 1, At, B1); PG8_BAR; PG8_SCHED;
.LBB0_1062:
	ds_read_b128 v[146:149], v155
	ds_read_b128 v[158:161], v155 offset:1024
	ds_read_b128 v[168:171], v155 offset:2048
	ds_read_b128 v[172:175], v155 offset:3072
	ds_read_b128 v[176:179], v156
	ds_read_b128 v[180:183], v156 offset:1024
	ds_read_b128 v[184:187], v156 offset:2048
	ds_read_b128 v[188:191], v156 offset:3072
	s_add_u32 s72, s70, 0xfff80080
	s_addc_u32 s73, s71, -1
	s_cmp_eq_u32 s77, 28
	s_cselect_b32 s75, s34, s73
	s_cselect_b32 s74, s35, s72
	s_cselect_b32 s73, s61, s76
	s_cselect_b32 s72, s63, s69
	v_lshl_add_u64 v[150:151], s[70:71], 0, v[138:139]
	s_add_i32 m0, s25, 0xc000
	ds_read_b128 v[200:203], v157
	ds_read_b128 v[204:207], v157 offset:1024
	ds_read_b128 v[208:211], v157 offset:2048
	ds_read_b128 v[212:215], v157 offset:3072
	ds_read_b128 v[216:219], v157 offset:4096
	ds_read_b128 v[220:223], v157 offset:5120
	ds_read_b128 v[224:227], v157 offset:6144
	ds_read_b128 v[228:231], v157 offset:7168
	global_load_lds_dwordx4 v[150:151], off
	v_lshl_add_u64 v[150:151], s[70:71], 0, v[140:141]
	s_add_i32 m0, s25, 0xe000
	s_nop 0
	global_load_lds_dwordx4 v[150:151], off
	s_waitcnt vmcnt(8)
	s_waitcnt lgkmcnt(0)
	s_barrier
	v_mfma_f32_16x16x32_bf16 v[126:129], v[146:149], v[200:203], v[126:129]
	v_mfma_f32_16x16x32_bf16 v[126:129], v[158:161], v[204:207], v[126:129]
	v_mfma_f32_16x16x32_bf16 v[110:113], v[158:161], v[212:215], v[110:113]
	v_mfma_f32_16x16x32_bf16 v[110:113], v[146:149], v[208:211], v[110:113]
	v_mfma_f32_16x16x32_bf16 v[94:97], v[146:149], v[216:219], v[94:97]
	v_mfma_f32_16x16x32_bf16 v[94:97], v[158:161], v[220:223], v[94:97]
	v_mfma_f32_16x16x32_bf16 v[78:81], v[158:161], v[228:231], v[78:81]
	v_mfma_f32_16x16x32_bf16 v[78:81], v[146:149], v[224:227], v[78:81]
	v_mfma_f32_16x16x32_bf16 v[74:77], v[168:171], v[224:227], v[74:77]
	v_mfma_f32_16x16x32_bf16 v[74:77], v[172:175], v[228:231], v[74:77]
	v_mfma_f32_16x16x32_bf16 v[122:125], v[172:175], v[204:207], v[122:125]
	v_mfma_f32_16x16x32_bf16 v[122:125], v[168:171], v[200:203], v[122:125]
	v_mfma_f32_16x16x32_bf16 v[106:109], v[168:171], v[208:211], v[106:109]
	v_mfma_f32_16x16x32_bf16 v[106:109], v[172:175], v[212:215], v[106:109]
	v_mfma_f32_16x16x32_bf16 v[90:93], v[172:175], v[220:223], v[90:93]
	v_mfma_f32_16x16x32_bf16 v[90:93], v[168:171], v[216:219], v[90:93]
	v_mfma_f32_16x16x32_bf16 v[86:89], v[176:179], v[216:219], v[86:89]
	v_mfma_f32_16x16x32_bf16 v[86:89], v[180:183], v[220:223], v[86:89]
	v_mfma_f32_16x16x32_bf16 v[118:121], v[180:183], v[204:207], v[118:121]
	v_mfma_f32_16x16x32_bf16 v[118:121], v[176:179], v[200:203], v[118:121]
	v_mfma_f32_16x16x32_bf16 v[102:105], v[176:179], v[208:211], v[102:105]
	v_mfma_f32_16x16x32_bf16 v[102:105], v[180:183], v[212:215], v[102:105]
	v_mfma_f32_16x16x32_bf16 v[70:73], v[180:183], v[228:231], v[70:73]
	v_mfma_f32_16x16x32_bf16 v[70:73], v[176:179], v[224:227], v[70:73]
	v_mfma_f32_16x16x32_bf16 v[66:69], v[184:187], v[224:227], v[66:69]
	v_mfma_f32_16x16x32_bf16 v[66:69], v[188:191], v[228:231], v[66:69]
	v_mfma_f32_16x16x32_bf16 v[114:117], v[188:191], v[204:207], v[114:117]
	v_mfma_f32_16x16x32_bf16 v[114:117], v[184:187], v[200:203], v[114:117]
	v_mfma_f32_16x16x32_bf16 v[98:101], v[184:187], v[208:211], v[98:101]
	v_mfma_f32_16x16x32_bf16 v[98:101], v[188:191], v[212:215], v[98:101]
	v_mfma_f32_16x16x32_bf16 v[82:85], v[188:191], v[220:223], v[82:85]
	v_mfma_f32_16x16x32_bf16 v[82:85], v[184:187], v[216:219], v[82:85]
	s_barrier
	s_add_i32 s78, s31, s2
	v_lshl_add_u64 v[150:151], s[72:73], 0, v[134:135]
	s_mov_b32 m0, s78
	ds_read_b128 v[200:203], v157 offset:16384
	ds_read_b128 v[204:207], v157 offset:17408
	ds_read_b128 v[208:211], v157 offset:18432
	ds_read_b128 v[212:215], v157 offset:19456
	ds_read_b128 v[216:219], v157 offset:20480
	ds_read_b128 v[220:223], v157 offset:21504
	ds_read_b128 v[224:227], v157 offset:22528
	ds_read_b128 v[228:231], v157 offset:23552
	global_load_lds_dwordx4 v[150:151], off
	s_add_i32 m0, s78, 0x2000
	s_add_u32 s78, s72, 0x80000
	v_lshl_add_u64 v[162:163], s[72:73], 0, v[130:131]
	s_addc_u32 s79, s73, 0
	s_add_i32 s80, s40, s2
	global_load_lds_dwordx4 v[162:163], off
	v_lshl_add_u64 v[192:193], s[78:79], 0, v[134:135]
	s_mov_b32 m0, s80
	v_lshl_add_u64 v[232:233], s[74:75], 0, v[132:133]
	global_load_lds_dwordx4 v[192:193], off
	v_lshl_add_u64 v[192:193], s[78:79], 0, v[130:131]
	s_add_i32 m0, s80, 0x2000
	s_nop 0
	global_load_lds_dwordx4 v[192:193], off
	v_lshl_add_u64 v[192:193], s[74:75], 0, v[136:137]
	s_mov_b32 m0, s25
	s_nop 0
	global_load_lds_dwordx4 v[192:193], off
	s_mov_b32 m0, s26
	s_nop 0
	global_load_lds_dwordx4 v[232:233], off
	s_waitcnt vmcnt(8)
	s_waitcnt lgkmcnt(0)
	s_barrier
; #define PG8_STAGE(bufoff, gbase, voff) do { _Pragma("unroll") for (int _i = 0; _i < 2; ++_i) \
;         __builtin_amdgcn_global_load_lds((const unsigned*)((const char*)(gbase) + (voff)[_i]), (PG8_LAS unsigned*)(lds + (bufoff) + ldsw + _i * 8192), 16, 0, 0); } while (0)
; #define PG8_LDA(dst, b, h) do { _Pragma("unroll") for (int m = 0; m < 4; ++m) _Pragma("unroll") for (int k = 0; k < 2; ++k) dst[m][k] = *(const PG8_LAS bf16x8*)(lds + PG8_SA(b, h) + aoff + m * 2048 + k * 1024); } while (0)
; #define PG8_LDB(dst, b, h) do { _Pragma("unroll") for (int n = 0; n < 2; ++n) _Pragma("unroll") for (int k = 0; k < 2; ++k) dst[n][k] = *(const PG8_LAS bf16x8*)(lds + PG8_SB(b, h) + boff + n * 2048 + k * 1024); } while (0)
; #define PG8_MMA(ai, bj, At, Bt) do { __builtin_amdgcn_s_setprio(1); _Pragma("unroll") for (int m = 0; m < 4; ++m) _Pragma("unroll") for (int n = 0; n < 2; ++n) _Pragma("unroll") for (int k = 0; k < 2; ++k) \
;         acc[ai][bj][m][n] = __builtin_amdgcn_mfma_f32_16x16x32_bf16(Bt[n][k], At[m][k], acc[ai][bj][m][n], 0, 0, 0); __builtin_amdgcn_s_setprio(0); } while (0)
; #define PG8_WAIT_V(n) asm volatile("s_waitcnt vmcnt(" #n ")" ::: "memory")
; #define PG8_WAIT_L(n) asm volatile("s_waitcnt lgkmcnt(" #n ")" ::: "memory")
; #define PG8_BAR __builtin_amdgcn_s_barrier()
; #define PG8_SCHED __builtin_amdgcn_sched_barrier(0)
; template <class Epi, class Sched, bool ALIGN_EPI = false, bool SP2 = false>
; __device__ __forceinline__ void gemm_phase(PG8_LAS unsigned char* lds, const Gemm g, const Sched& S, const Epi& E) {
;     ...
;             PG8_WAIT_V(8); PG8_WAIT_L(0); PG8_BAR; PG8_MMA(1, 0, At, B0); PG8_MMA(1, 1, At, B1); PG8_BAR; PG8_SCHED;
;             PG8_LDB(B0, 1, 0); PG8_LDB(B1, 1, 1); PG8_SCHED; PG8_LDA(At, 1, 0); PG8_STAGE(PG8_SA(0, 1), a2 + hstep, voffA);
;             PG8_WAIT_V(8); PG8_WAIT_L(0); PG8_BAR; PG8_MMA(0, 0, At, B0); PG8_MMA(0, 1, At, B1); PG8_BAR; PG8_SCHED;
	v_mfma_f32_16x16x32_bf16 v[62:65], v[146:149], v[200:203], v[62:65]
	v_mfma_f32_16x16x32_bf16 v[62:65], v[158:161], v[204:207], v[62:65]
	v_mfma_f32_16x16x32_bf16 v[46:49], v[158:161], v[212:215], v[46:49]
	v_mfma_f32_16x16x32_bf16 v[46:49], v[146:149], v[208:211], v[46:49]
	v_mfma_f32_16x16x32_bf16 v[30:33], v[146:149], v[216:219], v[30:33]
	v_mfma_f32_16x16x32_bf16 v[30:33], v[158:161], v[220:223], v[30:33]
	v_mfma_f32_16x16x32_bf16 v[14:17], v[158:161], v[228:231], v[14:17]
	v_mfma_f32_16x16x32_bf16 v[14:17], v[146:149], v[224:227], v[14:17]
	v_mfma_f32_16x16x32_bf16 v[10:13], v[168:171], v[224:227], v[10:13]
	v_mfma_f32_16x16x32_bf16 v[10:13], v[172:175], v[228:231], v[10:13]
	v_mfma_f32_16x16x32_bf16 v[58:61], v[172:175], v[204:207], v[58:61]
	v_mfma_f32_16x16x32_bf16 v[58:61], v[168:171], v[200:203], v[58:61]
	v_mfma_f32_16x16x32_bf16 v[42:45], v[168:171], v[208:211], v[42:45]
	v_mfma_f32_16x16x32_bf16 v[42:45], v[172:175], v[212:215], v[42:45]
	v_mfma_f32_16x16x32_bf16 v[26:29], v[172:175], v[220:223], v[26:29]
	v_mfma_f32_16x16x32_bf16 v[26:29], v[168:171], v[216:219], v[26:29]
	v_mfma_f32_16x16x32_bf16 v[22:25], v[176:179], v[216:219], v[22:25]
	v_mfma_f32_16x16x32_bf16 v[22:25], v[180:183], v[220:223], v[22:25]
	v_mfma_f32_16x16x32_bf16 v[54:57], v[180:183], v[204:207], v[54:57]
	v_mfma_f32_16x16x32_bf16 v[54:57], v[176:179], v[200:203], v[54:57]
	v_mfma_f32_16x16x32_bf16 v[38:41], v[176:179], v[208:211], v[38:41]
	v_mfma_f32_16x16x32_bf16 v[38:41], v[180:183], v[212:215], v[38:41]
	v_mfma_f32_16x16x32_bf16 v[6:9], v[180:183], v[228:231], v[6:9]
	v_mfma_f32_16x16x32_bf16 v[6:9], v[176:179], v[224:227], v[6:9]
	v_mfma_f32_16x16x32_bf16 v[2:5], v[184:187], v[224:227], v[2:5]
	v_mfma_f32_16x16x32_bf16 v[2:5], v[188:191], v[228:231], v[2:5]
	v_mfma_f32_16x16x32_bf16 v[50:53], v[188:191], v[204:207], v[50:53]
	v_mfma_f32_16x16x32_bf16 v[50:53], v[184:187], v[200:203], v[50:53]
	v_mfma_f32_16x16x32_bf16 v[34:37], v[184:187], v[208:211], v[34:37]
	v_mfma_f32_16x16x32_bf16 v[34:37], v[188:191], v[212:215], v[34:37]
	v_mfma_f32_16x16x32_bf16 v[18:21], v[188:191], v[220:223], v[18:21]
	v_mfma_f32_16x16x32_bf16 v[18:21], v[184:187], v[216:219], v[18:21]
	s_barrier
	s_add_i32 s78, 0, 0x18000
	v_add_u32_e32 v166, s78, v153
	s_add_i32 s79, 0, 0x1c000
	ds_read_b128 v[146:149], v166
	ds_read_b128 v[158:161], v166 offset:1024
	ds_read_b128 v[168:171], v166 offset:2048
	ds_read_b128 v[172:175], v166 offset:3072
	v_add_u32_e32 v166, s79, v153
	ds_read_b128 v[176:179], v166
	ds_read_b128 v[180:183], v166 offset:1024
	ds_read_b128 v[184:187], v166 offset:2048
	ds_read_b128 v[188:191], v166 offset:3072
	s_add_u32 s74, s74, 0x80000
	s_addc_u32 s75, s75, 0
	s_mov_b32 m0, s27
	v_lshl_add_u64 v[240:241], s[74:75], 0, v[136:137]
	ds_read_b128 v[200:203], v157 offset:32768
	ds_read_b128 v[204:207], v157 offset:33792
	ds_read_b128 v[208:211], v157 offset:34816
	ds_read_b128 v[212:215], v157 offset:35840
	ds_read_b128 v[216:219], v157 offset:36864
	ds_read_b128 v[220:223], v157 offset:37888
	ds_read_b128 v[224:227], v157 offset:38912
	ds_read_b128 v[228:231], v157 offset:39936
	global_load_lds_dwordx4 v[240:241], off
	v_lshl_add_u64 v[240:241], s[74:75], 0, v[132:133]
	s_mov_b32 m0, s28
	s_nop 0
	global_load_lds_dwordx4 v[240:241], off
	s_waitcnt vmcnt(8)
	s_waitcnt lgkmcnt(0)
	s_barrier
	v_mfma_f32_16x16x32_bf16 v[126:129], v[146:149], v[200:203], v[126:129]
	v_mfma_f32_16x16x32_bf16 v[126:129], v[158:161], v[204:207], v[126:129]
	v_mfma_f32_16x16x32_bf16 v[110:113], v[158:161], v[212:215], v[110:113]
	v_mfma_f32_16x16x32_bf16 v[110:113], v[146:149], v[208:211], v[110:113]
	v_mfma_f32_16x16x32_bf16 v[94:97], v[146:149], v[216:219], v[94:97]
	v_mfma_f32_16x16x32_bf16 v[94:97], v[158:161], v[220:223], v[94:97]
	v_mfma_f32_16x16x32_bf16 v[78:81], v[158:161], v[228:231], v[78:81]
	v_mfma_f32_16x16x32_bf16 v[78:81], v[146:149], v[224:227], v[78:81]
	v_mfma_f32_16x16x32_bf16 v[74:77], v[168:171], v[224:227], v[74:77]
	v_mfma_f32_16x16x32_bf16 v[74:77], v[172:175], v[228:231], v[74:77]
	v_mfma_f32_16x16x32_bf16 v[122:125], v[172:175], v[204:207], v[122:125]
	v_mfma_f32_16x16x32_bf16 v[122:125], v[168:171], v[200:203], v[122:125]
	v_mfma_f32_16x16x32_bf16 v[106:109], v[168:171], v[208:211], v[106:109]
	v_mfma_f32_16x16x32_bf16 v[106:109], v[172:175], v[212:215], v[106:109]
	v_mfma_f32_16x16x32_bf16 v[90:93], v[172:175], v[220:223], v[90:93]
	v_mfma_f32_16x16x32_bf16 v[90:93], v[168:171], v[216:219], v[90:93]
	v_mfma_f32_16x16x32_bf16 v[86:89], v[176:179], v[216:219], v[86:89]
	v_mfma_f32_16x16x32_bf16 v[86:89], v[180:183], v[220:223], v[86:89]
	v_mfma_f32_16x16x32_bf16 v[118:121], v[180:183], v[204:207], v[118:121]
	v_mfma_f32_16x16x32_bf16 v[118:121], v[176:179], v[200:203], v[118:121]
	v_mfma_f32_16x16x32_bf16 v[102:105], v[176:179], v[208:211], v[102:105]
	v_mfma_f32_16x16x32_bf16 v[102:105], v[180:183], v[212:215], v[102:105]
	v_mfma_f32_16x16x32_bf16 v[70:73], v[180:183], v[228:231], v[70:73]
	v_mfma_f32_16x16x32_bf16 v[70:73], v[176:179], v[224:227], v[70:73]
	v_mfma_f32_16x16x32_bf16 v[66:69], v[184:187], v[224:227], v[66:69]
	v_mfma_f32_16x16x32_bf16 v[66:69], v[188:191], v[228:231], v[66:69]
	v_mfma_f32_16x16x32_bf16 v[114:117], v[188:191], v[204:207], v[114:117]
	v_mfma_f32_16x16x32_bf16 v[114:117], v[184:187], v[200:203], v[114:117]
	v_mfma_f32_16x16x32_bf16 v[98:101], v[184:187], v[208:211], v[98:101]
	v_mfma_f32_16x16x32_bf16 v[98:101], v[188:191], v[212:215], v[98:101]
	v_mfma_f32_16x16x32_bf16 v[82:85], v[188:191], v[220:223], v[82:85]
	v_mfma_f32_16x16x32_bf16 v[82:85], v[184:187], v[216:219], v[82:85]
	s_barrier
; #define PG8_STAGE(bufoff, gbase, voff) do { _Pragma("unroll") for (int _i = 0; _i < 2; ++_i) \
;         __builtin_amdgcn_global_load_lds((const unsigned*)((const char*)(gbase) + (voff)[_i]), (PG8_LAS unsigned*)(lds + (bufoff) + ldsw + _i * 8192), 16, 0, 0); } while (0)
; #define PG8_LDA(dst, b, h) do { _Pragma("unroll") for (int m = 0; m < 4; ++m) _Pragma("unroll") for (int k = 0; k < 2; ++k) dst[m][k] = *(const PG8_LAS bf16x8*)(lds + PG8_SA(b, h) + aoff + m * 2048 + k * 1024); } while (0)
; #define PG8_MMA(ai, bj, At, Bt) do { __builtin_amdgcn_s_setprio(1); _Pragma("unroll") for (int m = 0; m < 4; ++m) _Pragma("unroll") for (int n = 0; n < 2; ++n) _Pragma("unroll") for (int k = 0; k < 2; ++k) \
;         acc[ai][bj][m][n] = __builtin_amdgcn_mfma_f32_16x16x32_bf16(Bt[n][k], At[m][k], acc[ai][bj][m][n], 0, 0, 0); __builtin_amdgcn_s_setprio(0); } while (0)
; #define PG8_WAIT_V(n) asm volatile("s_waitcnt vmcnt(" #n ")" ::: "memory")
; #define PG8_WAIT_L(n) asm volatile("s_waitcnt lgkmcnt(" #n ")" ::: "memory")
; #define PG8_BAR __builtin_amdgcn_s_barrier()
; #define PG8_SCHED __builtin_amdgcn_sched_barrier(0)
; template <class Epi, class Sched, bool ALIGN_EPI = false, bool SP2 = false>
; __device__ __forceinline__ void gemm_phase(PG8_LAS unsigned char* lds, const Gemm g, const Sched& S, const Epi& E) {
;     ...
;         for (int t = 0; t < nt; t += 2) {
;     ...
;             PG8_LDA(At, 1, 1); PG8_STAGE(PG8_SB(1, 0), b3, voffB); PG8_STAGE(PG8_SB(1, 1), b3 + hstep, voffB); PG8_STAGE(PG8_SA(1, 0), a3, voffA);
;             PG8_WAIT_V(8); PG8_WAIT_L(0); PG8_BAR; PG8_MMA(1, 0, At, B0); PG8_MMA(1, 1, At, B1); PG8_BAR; PG8_SCHED;
	s_add_i32 s74, s78, s2
	v_lshl_add_u64 v[150:151], v[150:151], 0, s[10:11]
	s_mov_b32 m0, s74
	ds_read_b128 v[200:203], v157 offset:49152
	ds_read_b128 v[204:207], v157 offset:50176
	ds_read_b128 v[208:211], v157 offset:51200
	ds_read_b128 v[212:215], v157 offset:52224
	ds_read_b128 v[216:219], v157 offset:53248
	ds_read_b128 v[220:223], v157 offset:54272
	ds_read_b128 v[224:227], v157 offset:55296
	ds_read_b128 v[228:231], v157 offset:56320
	global_load_lds_dwordx4 v[150:151], off
	s_add_i32 m0, s74, 0x2000
	s_add_u32 s72, s72, 0x80080
	v_lshl_add_u64 v[150:151], v[162:163], 0, s[10:11]
	s_addc_u32 s73, s73, 0
	s_add_i32 s74, s79, s2
	global_load_lds_dwordx4 v[150:151], off
	v_lshl_add_u64 v[150:151], s[72:73], 0, v[134:135]
	s_mov_b32 m0, s74
	s_nop 0
	global_load_lds_dwordx4 v[150:151], off
	v_lshl_add_u64 v[150:151], s[72:73], 0, v[130:131]
	s_add_i32 m0, s74, 0x2000
	s_nop 0
	global_load_lds_dwordx4 v[150:151], off
	v_lshl_add_u64 v[150:151], v[192:193], 0, s[10:11]
	s_mov_b32 m0, s30
	s_nop 0
	global_load_lds_dwordx4 v[150:151], off
	v_lshl_add_u64 v[150:151], v[232:233], 0, s[10:11]
	s_mov_b32 m0, s33
	s_nop 0
	global_load_lds_dwordx4 v[150:151], off
	s_waitcnt vmcnt(8)
	s_waitcnt lgkmcnt(0)
	s_barrier
	v_mfma_f32_16x16x32_bf16 v[62:65], v[146:149], v[200:203], v[62:65]
	v_mfma_f32_16x16x32_bf16 v[62:65], v[158:161], v[204:207], v[62:65]
	v_mfma_f32_16x16x32_bf16 v[46:49], v[158:161], v[212:215], v[46:49]
	v_mfma_f32_16x16x32_bf16 v[46:49], v[146:149], v[208:211], v[46:49]
	v_mfma_f32_16x16x32_bf16 v[30:33], v[146:149], v[216:219], v[30:33]
	v_mfma_f32_16x16x32_bf16 v[30:33], v[158:161], v[220:223], v[30:33]
	v_mfma_f32_16x16x32_bf16 v[14:17], v[158:161], v[228:231], v[14:17]
	v_mfma_f32_16x16x32_bf16 v[14:17], v[146:149], v[224:227], v[14:17]
	v_mfma_f32_16x16x32_bf16 v[10:13], v[168:171], v[224:227], v[10:13]
	v_mfma_f32_16x16x32_bf16 v[10:13], v[172:175], v[228:231], v[10:13]
	v_mfma_f32_16x16x32_bf16 v[58:61], v[172:175], v[204:207], v[58:61]
	v_mfma_f32_16x16x32_bf16 v[58:61], v[168:171], v[200:203], v[58:61]
	v_mfma_f32_16x16x32_bf16 v[42:45], v[168:171], v[208:211], v[42:45]
	v_mfma_f32_16x16x32_bf16 v[42:45], v[172:175], v[212:215], v[42:45]
	v_mfma_f32_16x16x32_bf16 v[26:29], v[172:175], v[220:223], v[26:29]
	v_mfma_f32_16x16x32_bf16 v[26:29], v[168:171], v[216:219], v[26:29]
	v_mfma_f32_16x16x32_bf16 v[22:25], v[176:179], v[216:219], v[22:25]
	v_mfma_f32_16x16x32_bf16 v[22:25], v[180:183], v[220:223], v[22:25]
	v_mfma_f32_16x16x32_bf16 v[54:57], v[180:183], v[204:207], v[54:57]
	v_mfma_f32_16x16x32_bf16 v[54:57], v[176:179], v[200:203], v[54:57]
	v_mfma_f32_16x16x32_bf16 v[38:41], v[176:179], v[208:211], v[38:41]
	v_mfma_f32_16x16x32_bf16 v[38:41], v[180:183], v[212:215], v[38:41]
	v_mfma_f32_16x16x32_bf16 v[6:9], v[180:183], v[228:231], v[6:9]
	v_mfma_f32_16x16x32_bf16 v[6:9], v[176:179], v[224:227], v[6:9]
	v_mfma_f32_16x16x32_bf16 v[2:5], v[184:187], v[224:227], v[2:5]
	v_mfma_f32_16x16x32_bf16 v[2:5], v[188:191], v[228:231], v[2:5]
	v_mfma_f32_16x16x32_bf16 v[50:53], v[188:191], v[204:207], v[50:53]
	v_mfma_f32_16x16x32_bf16 v[50:53], v[184:187], v[200:203], v[50:53]
	v_mfma_f32_16x16x32_bf16 v[34:37], v[184:187], v[208:211], v[34:37]
	v_mfma_f32_16x16x32_bf16 v[34:37], v[188:191], v[212:215], v[34:37]
	v_mfma_f32_16x16x32_bf16 v[18:21], v[188:191], v[220:223], v[18:21]
	v_mfma_f32_16x16x32_bf16 v[18:21], v[184:187], v[216:219], v[18:21]
	s_barrier
	s_add_i32 s77, s77, 2
	s_add_u32 s70, s70, 0x100
	s_addc_u32 s71, s71, 0
	s_add_u32 s69, s69, 0x100
	s_addc_u32 s76, s76, 0
	s_cmp_gt_u32 s77, 29
	s_cbranch_scc0 .LBB0_1062
	s_and_b64 vcc, exec, s[48:49]
	s_cbranch_vccz .LBB0_1065
	s_barrier

; #define PG8_STAGE(bufoff, gbase, voff) do { _Pragma("unroll") for (int _i = 0; _i < 2; ++_i) \
;         __builtin_amdgcn_global_load_lds((const unsigned*)((const char*)(gbase) + (voff)[_i]), (PG8_LAS unsigned*)(lds + (bufoff) + ldsw + _i * 8192), 16, 0, 0); } while (0)
; #define PG8_LDA(dst, b, h) do { _Pragma("unroll") for (int m = 0; m < 4; ++m) _Pragma("unroll") for (int k = 0; k < 2; ++k) dst[m][k] = *(const PG8_LAS bf16x8*)(lds + PG8_SA(b, h) + aoff + m * 2048 + k * 1024); } while (0)
; #define PG8_LDB(dst, b, h) do { _Pragma("unroll") for (int n = 0; n < 2; ++n) _Pragma("unroll") for (int k = 0; k < 2; ++k) dst[n][k] = *(const PG8_LAS bf16x8*)(lds + PG8_SB(b, h) + boff + n * 2048 + k * 1024); } while (0)
; #define PG8_MMA(ai, bj, At, Bt) do { __builtin_amdgcn_s_setprio(1); _Pragma("unroll") for (int m = 0; m < 4; ++m) _Pragma("unroll") for (int n = 0; n < 2; ++n) _Pragma("unroll") for (int k = 0; k < 2; ++k) \
;         acc[ai][bj][m][n] = __builtin_amdgcn_mfma_f32_16x16x32_bf16(Bt[n][k], At[m][k], acc[ai][bj][m][n], 0, 0, 0); __builtin_amdgcn_s_setprio(0); } while (0)
; #define PG8_WAIT_V(n) asm volatile("s_waitcnt vmcnt(" #n ")" ::: "memory")
; #define PG8_WAIT_L(n) asm volatile("s_waitcnt lgkmcnt(" #n ")" ::: "memory")
; template <class Epi, class Sched, bool ALIGN_EPI = false, bool SP2 = false>
; __device__ __forceinline__ void gemm_phase(PG8_LAS unsigned char* lds, const Gemm g, const Sched& S, const Epi& E) {
;     ...
;             const bool last = (t == nt - 2);
;             const char* a1 = cA + (size_t)(t + 1) * kstep;
;             const char* a2 = last ? nA : cA + (size_t)(t + 2) * kstep; const char* b2 = last ? nB : cB + (size_t)(t + 2) * kstep;
;             const char* a3 = a2 + kstep; const char* b3 = b2 + kstep;
;             if (last && has_next) S.a_ready(nxt);
;             if constexpr (SP2) {
;             PG8_LDB(B0, 0, 0); PG8_LDB(B1, 0, 1); PG8_SCHED; PG8_LDA(At, 0, 0); PG8_STAGE(PG8_SA(1, 1), a1 + hstep, voffA);
;             PG8_WAIT_V(8); PG8_WAIT_L(0); PG8_BAR; PG8_MMA(0, 0, At, B0); PG8_MMA(0, 1, At, B1); PG8_BAR; PG8_SCHED;
;             PG8_LDA(At, 0, 1); PG8_STAGE(PG8_SB(0, 0), b2, voffB); PG8_STAGE(PG8_SB(0, 1), b2 + hstep, voffB); PG8_STAGE(PG8_SA(0, 0), a2, voffA);
;             PG8_WAIT_V(8); PG8_WAIT_L(0); PG8_BAR; PG8_MMA(1, 0, At, B0); PG8_MMA(1, 1, At, B1); PG8_BAR; PG8_SCHED;
.LBB0_1078:
	ds_read_b128 v[146:149], v155
	ds_read_b128 v[158:161], v155 offset:1024
	ds_read_b128 v[168:171], v155 offset:2048
	ds_read_b128 v[172:175], v155 offset:3072
	ds_read_b128 v[176:179], v156
	ds_read_b128 v[180:183], v156 offset:1024
	ds_read_b128 v[184:187], v156 offset:2048
	ds_read_b128 v[188:191], v156 offset:3072
	s_add_u32 s68, s66, 0xfff80080
	s_addc_u32 s69, s67, -1
	s_cmp_eq_u32 s73, 28
	s_cselect_b32 s71, s34, s69
	s_cselect_b32 s70, s35, s68
	s_cselect_b32 s69, s57, s72
	s_cselect_b32 s68, s59, s65
	v_lshl_add_u64 v[150:151], s[66:67], 0, v[138:139]
	s_add_i32 m0, s25, 0xc000
	ds_read_b128 v[200:203], v157
	ds_read_b128 v[204:207], v157 offset:1024
	ds_read_b128 v[208:211], v157 offset:2048
	ds_read_b128 v[212:215], v157 offset:3072
	ds_read_b128 v[216:219], v157 offset:4096
	ds_read_b128 v[220:223], v157 offset:5120
	ds_read_b128 v[224:227], v157 offset:6144
	ds_read_b128 v[228:231], v157 offset:7168
	global_load_lds_dwordx4 v[150:151], off
	v_lshl_add_u64 v[150:151], s[66:67], 0, v[140:141]
	s_add_i32 m0, s25, 0xe000
	s_nop 0
	global_load_lds_dwordx4 v[150:151], off
	s_waitcnt vmcnt(8)
	s_waitcnt lgkmcnt(0)
	s_barrier
	v_mfma_f32_16x16x32_bf16 v[126:129], v[146:149], v[200:203], v[126:129]
	v_mfma_f32_16x16x32_bf16 v[126:129], v[158:161], v[204:207], v[126:129]
	v_mfma_f32_16x16x32_bf16 v[110:113], v[158:161], v[212:215], v[110:113]
	v_mfma_f32_16x16x32_bf16 v[110:113], v[146:149], v[208:211], v[110:113]
	v_mfma_f32_16x16x32_bf16 v[94:97], v[146:149], v[216:219], v[94:97]
	v_mfma_f32_16x16x32_bf16 v[94:97], v[158:161], v[220:223], v[94:97]
	v_mfma_f32_16x16x32_bf16 v[78:81], v[158:161], v[228:231], v[78:81]
	v_mfma_f32_16x16x32_bf16 v[78:81], v[146:149], v[224:227], v[78:81]
	v_mfma_f32_16x16x32_bf16 v[74:77], v[168:171], v[224:227], v[74:77]
	v_mfma_f32_16x16x32_bf16 v[74:77], v[172:175], v[228:231], v[74:77]
	v_mfma_f32_16x16x32_bf16 v[122:125], v[172:175], v[204:207], v[122:125]
	v_mfma_f32_16x16x32_bf16 v[122:125], v[168:171], v[200:203], v[122:125]
	v_mfma_f32_16x16x32_bf16 v[106:109], v[168:171], v[208:211], v[106:109]
	v_mfma_f32_16x16x32_bf16 v[106:109], v[172:175], v[212:215], v[106:109]
	v_mfma_f32_16x16x32_bf16 v[90:93], v[172:175], v[220:223], v[90:93]
	v_mfma_f32_16x16x32_bf16 v[90:93], v[168:171], v[216:219], v[90:93]
	v_mfma_f32_16x16x32_bf16 v[86:89], v[176:179], v[216:219], v[86:89]
	v_mfma_f32_16x16x32_bf16 v[86:89], v[180:183], v[220:223], v[86:89]
	v_mfma_f32_16x16x32_bf16 v[118:121], v[180:183], v[204:207], v[118:121]
	v_mfma_f32_16x16x32_bf16 v[118:121], v[176:179], v[200:203], v[118:121]
	v_mfma_f32_16x16x32_bf16 v[102:105], v[176:179], v[208:211], v[102:105]
	v_mfma_f32_16x16x32_bf16 v[102:105], v[180:183], v[212:215], v[102:105]
	v_mfma_f32_16x16x32_bf16 v[70:73], v[180:183], v[228:231], v[70:73]
	v_mfma_f32_16x16x32_bf16 v[70:73], v[176:179], v[224:227], v[70:73]
	v_mfma_f32_16x16x32_bf16 v[66:69], v[184:187], v[224:227], v[66:69]
	v_mfma_f32_16x16x32_bf16 v[66:69], v[188:191], v[228:231], v[66:69]
	v_mfma_f32_16x16x32_bf16 v[114:117], v[188:191], v[204:207], v[114:117]
	v_mfma_f32_16x16x32_bf16 v[114:117], v[184:187], v[200:203], v[114:117]
	v_mfma_f32_16x16x32_bf16 v[98:101], v[184:187], v[208:211], v[98:101]
	v_mfma_f32_16x16x32_bf16 v[98:101], v[188:191], v[212:215], v[98:101]
	v_mfma_f32_16x16x32_bf16 v[82:85], v[188:191], v[220:223], v[82:85]
	v_mfma_f32_16x16x32_bf16 v[82:85], v[184:187], v[216:219], v[82:85]
	s_barrier
	s_add_i32 s74, s31, s2
	v_lshl_add_u64 v[150:151], s[68:69], 0, v[134:135]
	s_mov_b32 m0, s74
	ds_read_b128 v[200:203], v157 offset:16384
	ds_read_b128 v[204:207], v157 offset:17408
	ds_read_b128 v[208:211], v157 offset:18432
	ds_read_b128 v[212:215], v157 offset:19456
	ds_read_b128 v[216:219], v157 offset:20480
	ds_read_b128 v[220:223], v157 offset:21504
	ds_read_b128 v[224:227], v157 offset:22528
	ds_read_b128 v[228:231], v157 offset:23552
	global_load_lds_dwordx4 v[150:151], off
	s_add_i32 m0, s74, 0x2000
	s_add_u32 s74, s68, 0x80000
	v_lshl_add_u64 v[162:163], s[68:69], 0, v[130:131]
	s_addc_u32 s75, s69, 0
	s_add_i32 s76, s40, s2
	global_load_lds_dwordx4 v[162:163], off
	v_lshl_add_u64 v[192:193], s[74:75], 0, v[134:135]
	s_mov_b32 m0, s76
	v_lshl_add_u64 v[232:233], s[70:71], 0, v[132:133]
	global_load_lds_dwordx4 v[192:193], off
	v_lshl_add_u64 v[192:193], s[74:75], 0, v[130:131]
	s_add_i32 m0, s76, 0x2000
	s_nop 0
	global_load_lds_dwordx4 v[192:193], off
	v_lshl_add_u64 v[192:193], s[70:71], 0, v[136:137]
	s_mov_b32 m0, s25
	s_nop 0
	global_load_lds_dwordx4 v[192:193], off
	s_mov_b32 m0, s26
	s_nop 0
	global_load_lds_dwordx4 v[232:233], off
	s_waitcnt vmcnt(8)
	s_waitcnt lgkmcnt(0)
	s_barrier
; #define PG8_STAGE(bufoff, gbase, voff) do { _Pragma("unroll") for (int _i = 0; _i < 2; ++_i) \
;         __builtin_amdgcn_global_load_lds((const unsigned*)((const char*)(gbase) + (voff)[_i]), (PG8_LAS unsigned*)(lds + (bufoff) + ldsw + _i * 8192), 16, 0, 0); } while (0)
; #define PG8_LDA(dst, b, h) do { _Pragma("unroll") for (int m = 0; m < 4; ++m) _Pragma("unroll") for (int k = 0; k < 2; ++k) dst[m][k] = *(const PG8_LAS bf16x8*)(lds + PG8_SA(b, h) + aoff + m * 2048 + k * 1024); } while (0)
; #define PG8_LDB(dst, b, h) do { _Pragma("unroll") for (int n = 0; n < 2; ++n) _Pragma("unroll") for (int k = 0; k < 2; ++k) dst[n][k] = *(const PG8_LAS bf16x8*)(lds + PG8_SB(b, h) + boff + n * 2048 + k * 1024); } while (0)
; #define PG8_MMA(ai, bj, At, Bt) do { __builtin_amdgcn_s_setprio(1); _Pragma("unroll") for (int m = 0; m < 4; ++m) _Pragma("unroll") for (int n = 0; n < 2; ++n) _Pragma("unroll") for (int k = 0; k < 2; ++k) \
;         acc[ai][bj][m][n] = __builtin_amdgcn_mfma_f32_16x16x32_bf16(Bt[n][k], At[m][k], acc[ai][bj][m][n], 0, 0, 0); __builtin_amdgcn_s_setprio(0); } while (0)
; #define PG8_WAIT_V(n) asm volatile("s_waitcnt vmcnt(" #n ")" ::: "memory")
; #define PG8_WAIT_L(n) asm volatile("s_waitcnt lgkmcnt(" #n ")" ::: "memory")
; #define PG8_BAR __builtin_amdgcn_s_barrier()
; #define PG8_SCHED __builtin_amdgcn_sched_barrier(0)
; template <class Epi, class Sched, bool ALIGN_EPI = false, bool SP2 = false>
; __device__ __forceinline__ void gemm_phase(PG8_LAS unsigned char* lds, const Gemm g, const Sched& S, const Epi& E) {
;     ...
;             PG8_WAIT_V(8); PG8_WAIT_L(0); PG8_BAR; PG8_MMA(1, 0, At, B0); PG8_MMA(1, 1, At, B1); PG8_BAR; PG8_SCHED;
;             PG8_LDB(B0, 1, 0); PG8_LDB(B1, 1, 1); PG8_SCHED; PG8_LDA(At, 1, 0); PG8_STAGE(PG8_SA(0, 1), a2 + hstep, voffA);
;             PG8_WAIT_V(8); PG8_WAIT_L(0); PG8_BAR; PG8_MMA(0, 0, At, B0); PG8_MMA(0, 1, At, B1); PG8_BAR; PG8_SCHED;
	v_mfma_f32_16x16x32_bf16 v[62:65], v[146:149], v[200:203], v[62:65]
	v_mfma_f32_16x16x32_bf16 v[62:65], v[158:161], v[204:207], v[62:65]
	v_mfma_f32_16x16x32_bf16 v[46:49], v[158:161], v[212:215], v[46:49]
	v_mfma_f32_16x16x32_bf16 v[46:49], v[146:149], v[208:211], v[46:49]
	v_mfma_f32_16x16x32_bf16 v[30:33], v[146:149], v[216:219], v[30:33]
	v_mfma_f32_16x16x32_bf16 v[30:33], v[158:161], v[220:223], v[30:33]
	v_mfma_f32_16x16x32_bf16 v[14:17], v[158:161], v[228:231], v[14:17]
	v_mfma_f32_16x16x32_bf16 v[14:17], v[146:149], v[224:227], v[14:17]
	v_mfma_f32_16x16x32_bf16 v[10:13], v[168:171], v[224:227], v[10:13]
	v_mfma_f32_16x16x32_bf16 v[10:13], v[172:175], v[228:231], v[10:13]
	v_mfma_f32_16x16x32_bf16 v[58:61], v[172:175], v[204:207], v[58:61]
	v_mfma_f32_16x16x32_bf16 v[58:61], v[168:171], v[200:203], v[58:61]
	v_mfma_f32_16x16x32_bf16 v[42:45], v[168:171], v[208:211], v[42:45]
	v_mfma_f32_16x16x32_bf16 v[42:45], v[172:175], v[212:215], v[42:45]
	v_mfma_f32_16x16x32_bf16 v[26:29], v[172:175], v[220:223], v[26:29]
	v_mfma_f32_16x16x32_bf16 v[26:29], v[168:171], v[216:219], v[26:29]
	v_mfma_f32_16x16x32_bf16 v[22:25], v[176:179], v[216:219], v[22:25]
	v_mfma_f32_16x16x32_bf16 v[22:25], v[180:183], v[220:223], v[22:25]
	v_mfma_f32_16x16x32_bf16 v[54:57], v[180:183], v[204:207], v[54:57]
	v_mfma_f32_16x16x32_bf16 v[54:57], v[176:179], v[200:203], v[54:57]
	v_mfma_f32_16x16x32_bf16 v[38:41], v[176:179], v[208:211], v[38:41]
	v_mfma_f32_16x16x32_bf16 v[38:41], v[180:183], v[212:215], v[38:41]
	v_mfma_f32_16x16x32_bf16 v[6:9], v[180:183], v[228:231], v[6:9]
	v_mfma_f32_16x16x32_bf16 v[6:9], v[176:179], v[224:227], v[6:9]
	v_mfma_f32_16x16x32_bf16 v[2:5], v[184:187], v[224:227], v[2:5]
	v_mfma_f32_16x16x32_bf16 v[2:5], v[188:191], v[228:231], v[2:5]
	v_mfma_f32_16x16x32_bf16 v[50:53], v[188:191], v[204:207], v[50:53]
	v_mfma_f32_16x16x32_bf16 v[50:53], v[184:187], v[200:203], v[50:53]
	v_mfma_f32_16x16x32_bf16 v[34:37], v[184:187], v[208:211], v[34:37]
	v_mfma_f32_16x16x32_bf16 v[34:37], v[188:191], v[212:215], v[34:37]
	v_mfma_f32_16x16x32_bf16 v[18:21], v[188:191], v[220:223], v[18:21]
	v_mfma_f32_16x16x32_bf16 v[18:21], v[184:187], v[216:219], v[18:21]
	s_barrier
	s_add_i32 s74, 0, 0x18000
	v_add_u32_e32 v166, s74, v153
	s_add_i32 s75, 0, 0x1c000
	ds_read_b128 v[146:149], v166
	ds_read_b128 v[158:161], v166 offset:1024
	ds_read_b128 v[168:171], v166 offset:2048
	ds_read_b128 v[172:175], v166 offset:3072
	v_add_u32_e32 v166, s75, v153
	ds_read_b128 v[176:179], v166
	ds_read_b128 v[180:183], v166 offset:1024
	ds_read_b128 v[184:187], v166 offset:2048
	ds_read_b128 v[188:191], v166 offset:3072
	s_add_u32 s70, s70, 0x80000
	s_addc_u32 s71, s71, 0
	s_mov_b32 m0, s27
	v_lshl_add_u64 v[240:241], s[70:71], 0, v[136:137]
	ds_read_b128 v[200:203], v157 offset:32768
	ds_read_b128 v[204:207], v157 offset:33792
	ds_read_b128 v[208:211], v157 offset:34816
	ds_read_b128 v[212:215], v157 offset:35840
	ds_read_b128 v[216:219], v157 offset:36864
	ds_read_b128 v[220:223], v157 offset:37888
	ds_read_b128 v[224:227], v157 offset:38912
	ds_read_b128 v[228:231], v157 offset:39936
	global_load_lds_dwordx4 v[240:241], off
	v_lshl_add_u64 v[240:241], s[70:71], 0, v[132:133]
	s_mov_b32 m0, s28
	s_nop 0
	global_load_lds_dwordx4 v[240:241], off
	s_waitcnt vmcnt(8)
	s_waitcnt lgkmcnt(0)
	s_barrier
	v_mfma_f32_16x16x32_bf16 v[126:129], v[146:149], v[200:203], v[126:129]
	v_mfma_f32_16x16x32_bf16 v[126:129], v[158:161], v[204:207], v[126:129]
	v_mfma_f32_16x16x32_bf16 v[110:113], v[158:161], v[212:215], v[110:113]
	v_mfma_f32_16x16x32_bf16 v[110:113], v[146:149], v[208:211], v[110:113]
	v_mfma_f32_16x16x32_bf16 v[94:97], v[146:149], v[216:219], v[94:97]
	v_mfma_f32_16x16x32_bf16 v[94:97], v[158:161], v[220:223], v[94:97]
	v_mfma_f32_16x16x32_bf16 v[78:81], v[158:161], v[228:231], v[78:81]
	v_mfma_f32_16x16x32_bf16 v[78:81], v[146:149], v[224:227], v[78:81]
	v_mfma_f32_16x16x32_bf16 v[74:77], v[168:171], v[224:227], v[74:77]
	v_mfma_f32_16x16x32_bf16 v[74:77], v[172:175], v[228:231], v[74:77]
	v_mfma_f32_16x16x32_bf16 v[122:125], v[172:175], v[204:207], v[122:125]
	v_mfma_f32_16x16x32_bf16 v[122:125], v[168:171], v[200:203], v[122:125]
	v_mfma_f32_16x16x32_bf16 v[106:109], v[168:171], v[208:211], v[106:109]
	v_mfma_f32_16x16x32_bf16 v[106:109], v[172:175], v[212:215], v[106:109]
	v_mfma_f32_16x16x32_bf16 v[90:93], v[172:175], v[220:223], v[90:93]
	v_mfma_f32_16x16x32_bf16 v[90:93], v[168:171], v[216:219], v[90:93]
	v_mfma_f32_16x16x32_bf16 v[86:89], v[176:179], v[216:219], v[86:89]
	v_mfma_f32_16x16x32_bf16 v[86:89], v[180:183], v[220:223], v[86:89]
	v_mfma_f32_16x16x32_bf16 v[118:121], v[180:183], v[204:207], v[118:121]
	v_mfma_f32_16x16x32_bf16 v[118:121], v[176:179], v[200:203], v[118:121]
	v_mfma_f32_16x16x32_bf16 v[102:105], v[176:179], v[208:211], v[102:105]
	v_mfma_f32_16x16x32_bf16 v[102:105], v[180:183], v[212:215], v[102:105]
	v_mfma_f32_16x16x32_bf16 v[70:73], v[180:183], v[228:231], v[70:73]
	v_mfma_f32_16x16x32_bf16 v[70:73], v[176:179], v[224:227], v[70:73]
	v_mfma_f32_16x16x32_bf16 v[66:69], v[184:187], v[224:227], v[66:69]
	v_mfma_f32_16x16x32_bf16 v[66:69], v[188:191], v[228:231], v[66:69]
	v_mfma_f32_16x16x32_bf16 v[114:117], v[188:191], v[204:207], v[114:117]
	v_mfma_f32_16x16x32_bf16 v[114:117], v[184:187], v[200:203], v[114:117]
	v_mfma_f32_16x16x32_bf16 v[98:101], v[184:187], v[208:211], v[98:101]
	v_mfma_f32_16x16x32_bf16 v[98:101], v[188:191], v[212:215], v[98:101]
	v_mfma_f32_16x16x32_bf16 v[82:85], v[188:191], v[220:223], v[82:85]
	v_mfma_f32_16x16x32_bf16 v[82:85], v[184:187], v[216:219], v[82:85]
	s_barrier
; #define PG8_STAGE(bufoff, gbase, voff) do { _Pragma("unroll") for (int _i = 0; _i < 2; ++_i) \
;         __builtin_amdgcn_global_load_lds((const unsigned*)((const char*)(gbase) + (voff)[_i]), (PG8_LAS unsigned*)(lds + (bufoff) + ldsw + _i * 8192), 16, 0, 0); } while (0)
; #define PG8_LDA(dst, b, h) do { _Pragma("unroll") for (int m = 0; m < 4; ++m) _Pragma("unroll") for (int k = 0; k < 2; ++k) dst[m][k] = *(const PG8_LAS bf16x8*)(lds + PG8_SA(b, h) + aoff + m * 2048 + k * 1024); } while (0)
; #define PG8_MMA(ai, bj, At, Bt) do { __builtin_amdgcn_s_setprio(1); _Pragma("unroll") for (int m = 0; m < 4; ++m) _Pragma("unroll") for (int n = 0; n < 2; ++n) _Pragma("unroll") for (int k = 0; k < 2; ++k) \
;         acc[ai][bj][m][n] = __builtin_amdgcn_mfma_f32_16x16x32_bf16(Bt[n][k], At[m][k], acc[ai][bj][m][n], 0, 0, 0); __builtin_amdgcn_s_setprio(0); } while (0)
; #define PG8_WAIT_V(n) asm volatile("s_waitcnt vmcnt(" #n ")" ::: "memory")
; #define PG8_WAIT_L(n) asm volatile("s_waitcnt lgkmcnt(" #n ")" ::: "memory")
; #define PG8_BAR __builtin_amdgcn_s_barrier()
; #define PG8_SCHED __builtin_amdgcn_sched_barrier(0)
; template <class Epi, class Sched, bool ALIGN_EPI = false, bool SP2 = false>
; __device__ __forceinline__ void gemm_phase(PG8_LAS unsigned char* lds, const Gemm g, const Sched& S, const Epi& E) {
;     ...
;         for (int t = 0; t < nt; t += 2) {
;     ...
;             PG8_LDA(At, 1, 1); PG8_STAGE(PG8_SB(1, 0), b3, voffB); PG8_STAGE(PG8_SB(1, 1), b3 + hstep, voffB); PG8_STAGE(PG8_SA(1, 0), a3, voffA);
;             PG8_WAIT_V(8); PG8_WAIT_L(0); PG8_BAR; PG8_MMA(1, 0, At, B0); PG8_MMA(1, 1, At, B1); PG8_BAR; PG8_SCHED;
	s_add_i32 s70, s74, s2
	v_lshl_add_u64 v[150:151], v[150:151], 0, s[8:9]
	s_mov_b32 m0, s70
	ds_read_b128 v[200:203], v157 offset:49152
	ds_read_b128 v[204:207], v157 offset:50176
	ds_read_b128 v[208:211], v157 offset:51200
	ds_read_b128 v[212:215], v157 offset:52224
	ds_read_b128 v[216:219], v157 offset:53248
	ds_read_b128 v[220:223], v157 offset:54272
	ds_read_b128 v[224:227], v157 offset:55296
	ds_read_b128 v[228:231], v157 offset:56320
	global_load_lds_dwordx4 v[150:151], off
	s_add_i32 m0, s70, 0x2000
	s_add_u32 s68, s68, 0x80080
	v_lshl_add_u64 v[150:151], v[162:163], 0, s[8:9]
	s_addc_u32 s69, s69, 0
	s_add_i32 s70, s75, s2
	global_load_lds_dwordx4 v[150:151], off
	v_lshl_add_u64 v[150:151], s[68:69], 0, v[134:135]
	s_mov_b32 m0, s70
	s_nop 0
	global_load_lds_dwordx4 v[150:151], off
	v_lshl_add_u64 v[150:151], s[68:69], 0, v[130:131]
	s_add_i32 m0, s70, 0x2000
	s_nop 0
	global_load_lds_dwordx4 v[150:151], off
	v_lshl_add_u64 v[150:151], v[192:193], 0, s[8:9]
	s_mov_b32 m0, s30
	s_nop 0
	global_load_lds_dwordx4 v[150:151], off
	v_lshl_add_u64 v[150:151], v[232:233], 0, s[8:9]
	s_mov_b32 m0, s33
	s_nop 0
	global_load_lds_dwordx4 v[150:151], off
	s_waitcnt vmcnt(8)
	s_waitcnt lgkmcnt(0)
	s_barrier
	v_mfma_f32_16x16x32_bf16 v[62:65], v[146:149], v[200:203], v[62:65]
	v_mfma_f32_16x16x32_bf16 v[62:65], v[158:161], v[204:207], v[62:65]
	v_mfma_f32_16x16x32_bf16 v[46:49], v[158:161], v[212:215], v[46:49]
	v_mfma_f32_16x16x32_bf16 v[46:49], v[146:149], v[208:211], v[46:49]
	v_mfma_f32_16x16x32_bf16 v[30:33], v[146:149], v[216:219], v[30:33]
	v_mfma_f32_16x16x32_bf16 v[30:33], v[158:161], v[220:223], v[30:33]
	v_mfma_f32_16x16x32_bf16 v[14:17], v[158:161], v[228:231], v[14:17]
	v_mfma_f32_16x16x32_bf16 v[14:17], v[146:149], v[224:227], v[14:17]
	v_mfma_f32_16x16x32_bf16 v[10:13], v[168:171], v[224:227], v[10:13]
	v_mfma_f32_16x16x32_bf16 v[10:13], v[172:175], v[228:231], v[10:13]
	v_mfma_f32_16x16x32_bf16 v[58:61], v[172:175], v[204:207], v[58:61]
	v_mfma_f32_16x16x32_bf16 v[58:61], v[168:171], v[200:203], v[58:61]
	v_mfma_f32_16x16x32_bf16 v[42:45], v[168:171], v[208:211], v[42:45]
	v_mfma_f32_16x16x32_bf16 v[42:45], v[172:175], v[212:215], v[42:45]
	v_mfma_f32_16x16x32_bf16 v[26:29], v[172:175], v[220:223], v[26:29]
	v_mfma_f32_16x16x32_bf16 v[26:29], v[168:171], v[216:219], v[26:29]
	v_mfma_f32_16x16x32_bf16 v[22:25], v[176:179], v[216:219], v[22:25]
	v_mfma_f32_16x16x32_bf16 v[22:25], v[180:183], v[220:223], v[22:25]
	v_mfma_f32_16x16x32_bf16 v[54:57], v[180:183], v[204:207], v[54:57]
	v_mfma_f32_16x16x32_bf16 v[54:57], v[176:179], v[200:203], v[54:57]
	v_mfma_f32_16x16x32_bf16 v[38:41], v[176:179], v[208:211], v[38:41]
	v_mfma_f32_16x16x32_bf16 v[38:41], v[180:183], v[212:215], v[38:41]
	v_mfma_f32_16x16x32_bf16 v[6:9], v[180:183], v[228:231], v[6:9]
	v_mfma_f32_16x16x32_bf16 v[6:9], v[176:179], v[224:227], v[6:9]
	v_mfma_f32_16x16x32_bf16 v[2:5], v[184:187], v[224:227], v[2:5]
	v_mfma_f32_16x16x32_bf16 v[2:5], v[188:191], v[228:231], v[2:5]
	v_mfma_f32_16x16x32_bf16 v[50:53], v[188:191], v[204:207], v[50:53]
	v_mfma_f32_16x16x32_bf16 v[50:53], v[184:187], v[200:203], v[50:53]
	v_mfma_f32_16x16x32_bf16 v[34:37], v[184:187], v[208:211], v[34:37]
	v_mfma_f32_16x16x32_bf16 v[34:37], v[188:191], v[212:215], v[34:37]
	v_mfma_f32_16x16x32_bf16 v[18:21], v[188:191], v[220:223], v[18:21]
	v_mfma_f32_16x16x32_bf16 v[18:21], v[184:187], v[216:219], v[18:21]
	s_barrier
	s_add_i32 s73, s73, 2
	s_add_u32 s66, s66, 0x100
	s_addc_u32 s67, s67, 0
	s_add_u32 s65, s65, 0x100
	s_addc_u32 s72, s72, 0
	s_cmp_gt_u32 s73, 29
	s_cbranch_scc0 .LBB0_1078
	s_and_b64 vcc, exec, s[10:11]
	s_cbranch_vccz .LBB0_1081
	s_barrier

; #define PG8_STAGE(bufoff, gbase, voff) do { _Pragma("unroll") for (int _i = 0; _i < 2; ++_i) \
;         __builtin_amdgcn_global_load_lds((const unsigned*)((const char*)(gbase) + (voff)[_i]), (PG8_LAS unsigned*)(lds + (bufoff) + ldsw + _i * 8192), 16, 0, 0); } while (0)
; #define PG8_LDA(dst, b, h) do { _Pragma("unroll") for (int m = 0; m < 4; ++m) _Pragma("unroll") for (int k = 0; k < 2; ++k) dst[m][k] = *(const PG8_LAS bf16x8*)(lds + PG8_SA(b, h) + aoff + m * 2048 + k * 1024); } while (0)
; #define PG8_LDB(dst, b, h) do { _Pragma("unroll") for (int n = 0; n < 2; ++n) _Pragma("unroll") for (int k = 0; k < 2; ++k) dst[n][k] = *(const PG8_LAS bf16x8*)(lds + PG8_SB(b, h) + boff + n * 2048 + k * 1024); } while (0)
; #define PG8_MMA(ai, bj, At, Bt) do { __builtin_amdgcn_s_setprio(1); _Pragma("unroll") for (int m = 0; m < 4; ++m) _Pragma("unroll") for (int n = 0; n < 2; ++n) _Pragma("unroll") for (int k = 0; k < 2; ++k) \
;         acc[ai][bj][m][n] = __builtin_amdgcn_mfma_f32_16x16x32_bf16(Bt[n][k], At[m][k], acc[ai][bj][m][n], 0, 0, 0); __builtin_amdgcn_s_setprio(0); } while (0)
; #define PG8_WAIT_V(n) asm volatile("s_waitcnt vmcnt(" #n ")" ::: "memory")
; #define PG8_WAIT_L(n) asm volatile("s_waitcnt lgkmcnt(" #n ")" ::: "memory")
; template <class Epi, class Sched, bool ALIGN_EPI = false, bool SP2 = false>
; __device__ __forceinline__ void gemm_phase(PG8_LAS unsigned char* lds, const Gemm g, const Sched& S, const Epi& E) {
;     ...
;             const bool last = (t == nt - 2);
;             const char* a1 = cA + (size_t)(t + 1) * kstep;
;             const char* a2 = last ? nA : cA + (size_t)(t + 2) * kstep; const char* b2 = last ? nB : cB + (size_t)(t + 2) * kstep;
;             const char* a3 = a2 + kstep; const char* b3 = b2 + kstep;
;             if (last && has_next) S.a_ready(nxt);
;             if constexpr (SP2) {
;             PG8_LDB(B0, 0, 0); PG8_LDB(B1, 0, 1); PG8_SCHED; PG8_LDA(At, 0, 0); PG8_STAGE(PG8_SA(1, 1), a1 + hstep, voffA);
;             PG8_WAIT_V(8); PG8_WAIT_L(0); PG8_BAR; PG8_MMA(0, 0, At, B0); PG8_MMA(0, 1, At, B1); PG8_BAR; PG8_SCHED;
;             PG8_LDA(At, 0, 1); PG8_STAGE(PG8_SB(0, 0), b2, voffB); PG8_STAGE(PG8_SB(0, 1), b2 + hstep, voffB); PG8_STAGE(PG8_SA(0, 0), a2, voffA);
;             PG8_WAIT_V(8); PG8_WAIT_L(0); PG8_BAR; PG8_MMA(1, 0, At, B0); PG8_MMA(1, 1, At, B1); PG8_BAR; PG8_SCHED;
.LBB0_1203:
	ds_read_b128 v[146:149], v171
	ds_read_b128 v[176:179], v171 offset:1024
	ds_read_b128 v[180:183], v171 offset:2048
	ds_read_b128 v[184:187], v171 offset:3072
	ds_read_b128 v[188:191], v172
	ds_read_b128 v[200:203], v172 offset:1024
	ds_read_b128 v[204:207], v172 offset:2048
	ds_read_b128 v[208:211], v172 offset:3072
	s_add_u32 s63, s64, 0xfff00080
	s_addc_u32 s66, s65, -1
	s_cmp_eq_u32 s61, 60
	s_cselect_b32 s69, s34, s66
	s_cselect_b32 s68, s35, s63
	s_cselect_b32 s67, s40, s55
	s_cselect_b32 s66, s41, s53
	v_lshl_add_u64 v[150:151], s[64:65], 0, v[138:139]
	s_add_i32 m0, s4, 0xc000
	ds_read_b128 v[212:215], v173
	ds_read_b128 v[216:219], v173 offset:1024
	ds_read_b128 v[220:223], v173 offset:2048
	ds_read_b128 v[224:227], v173 offset:3072
	ds_read_b128 v[228:231], v173 offset:4096
	ds_read_b128 v[240:243], v173 offset:5120
	ds_read_b128 v[244:247], v173 offset:6144
	ds_read_b128 v[248:251], v173 offset:7168
	global_load_lds_dwordx4 v[150:151], off
	v_lshl_add_u64 v[150:151], s[64:65], 0, v[140:141]
	s_add_i32 m0, s4, 0xe000
	s_nop 0
	global_load_lds_dwordx4 v[150:151], off
	s_waitcnt vmcnt(8)
	s_waitcnt lgkmcnt(0)
	s_barrier
	v_mfma_f32_16x16x32_bf16 v[126:129], v[146:149], v[212:215], v[126:129]
	v_mfma_f32_16x16x32_bf16 v[126:129], v[176:179], v[216:219], v[126:129]
	v_mfma_f32_16x16x32_bf16 v[110:113], v[176:179], v[224:227], v[110:113]
	v_mfma_f32_16x16x32_bf16 v[110:113], v[146:149], v[220:223], v[110:113]
	v_mfma_f32_16x16x32_bf16 v[94:97], v[146:149], v[228:231], v[94:97]
	v_mfma_f32_16x16x32_bf16 v[94:97], v[176:179], v[240:243], v[94:97]
	v_mfma_f32_16x16x32_bf16 v[78:81], v[176:179], v[248:251], v[78:81]
	v_mfma_f32_16x16x32_bf16 v[78:81], v[146:149], v[244:247], v[78:81]
	v_mfma_f32_16x16x32_bf16 v[74:77], v[180:183], v[244:247], v[74:77]
	v_mfma_f32_16x16x32_bf16 v[74:77], v[184:187], v[248:251], v[74:77]
	v_mfma_f32_16x16x32_bf16 v[122:125], v[184:187], v[216:219], v[122:125]
	v_mfma_f32_16x16x32_bf16 v[122:125], v[180:183], v[212:215], v[122:125]
	v_mfma_f32_16x16x32_bf16 v[106:109], v[180:183], v[220:223], v[106:109]
	v_mfma_f32_16x16x32_bf16 v[106:109], v[184:187], v[224:227], v[106:109]
	v_mfma_f32_16x16x32_bf16 v[90:93], v[184:187], v[240:243], v[90:93]
	v_mfma_f32_16x16x32_bf16 v[90:93], v[180:183], v[228:231], v[90:93]
	v_mfma_f32_16x16x32_bf16 v[86:89], v[188:191], v[228:231], v[86:89]
	v_mfma_f32_16x16x32_bf16 v[86:89], v[200:203], v[240:243], v[86:89]
	v_mfma_f32_16x16x32_bf16 v[118:121], v[200:203], v[216:219], v[118:121]
	v_mfma_f32_16x16x32_bf16 v[118:121], v[188:191], v[212:215], v[118:121]
	v_mfma_f32_16x16x32_bf16 v[102:105], v[188:191], v[220:223], v[102:105]
	v_mfma_f32_16x16x32_bf16 v[102:105], v[200:203], v[224:227], v[102:105]
	v_mfma_f32_16x16x32_bf16 v[70:73], v[200:203], v[248:251], v[70:73]
	v_mfma_f32_16x16x32_bf16 v[70:73], v[188:191], v[244:247], v[70:73]
	v_mfma_f32_16x16x32_bf16 v[66:69], v[204:207], v[244:247], v[66:69]
	v_mfma_f32_16x16x32_bf16 v[66:69], v[208:211], v[248:251], v[66:69]
	v_mfma_f32_16x16x32_bf16 v[114:117], v[208:211], v[216:219], v[114:117]
	v_mfma_f32_16x16x32_bf16 v[114:117], v[204:207], v[212:215], v[114:117]
	v_mfma_f32_16x16x32_bf16 v[98:101], v[204:207], v[220:223], v[98:101]
	v_mfma_f32_16x16x32_bf16 v[98:101], v[208:211], v[224:227], v[98:101]
	v_mfma_f32_16x16x32_bf16 v[82:85], v[208:211], v[240:243], v[82:85]
	v_mfma_f32_16x16x32_bf16 v[82:85], v[204:207], v[228:231], v[82:85]
	s_barrier
	s_add_i32 s63, s31, s2
	v_lshl_add_u64 v[150:151], s[66:67], 0, v[132:133]
	s_mov_b32 m0, s63
	ds_read_b128 v[212:215], v173 offset:16384
	ds_read_b128 v[216:219], v173 offset:17408
	ds_read_b128 v[220:223], v173 offset:18432
	ds_read_b128 v[224:227], v173 offset:19456
	ds_read_b128 v[228:231], v173 offset:20480
	ds_read_b128 v[240:243], v173 offset:21504
	ds_read_b128 v[244:247], v173 offset:22528
	ds_read_b128 v[248:251], v173 offset:23552
	global_load_lds_dwordx4 v[150:151], off
	s_add_i32 m0, s63, 0x2000
	s_add_u32 s70, s66, 0x100000
	v_lshl_add_u64 v[192:193], s[66:67], 0, v[136:137]
	s_addc_u32 s71, s67, 0
	s_add_i32 s63, s39, s2
	global_load_lds_dwordx4 v[192:193], off
	v_lshl_add_u64 v[232:233], s[70:71], 0, v[132:133]
	s_mov_b32 m0, s63
	v_lshl_add_u64 v[252:253], s[68:69], 0, v[134:135]
	global_load_lds_dwordx4 v[232:233], off
	v_lshl_add_u64 v[232:233], s[70:71], 0, v[136:137]
	s_add_i32 m0, s63, 0x2000
	s_nop 0
	global_load_lds_dwordx4 v[232:233], off
	v_lshl_add_u64 v[232:233], s[68:69], 0, v[130:131]
	s_mov_b32 m0, s4
	s_nop 0
	global_load_lds_dwordx4 v[232:233], off
	s_mov_b32 m0, s5
	s_nop 0
	global_load_lds_dwordx4 v[252:253], off
	s_waitcnt vmcnt(8)
	s_waitcnt lgkmcnt(0)
	s_barrier
; #define PG8_STAGE(bufoff, gbase, voff) do { _Pragma("unroll") for (int _i = 0; _i < 2; ++_i) \
;         __builtin_amdgcn_global_load_lds((const unsigned*)((const char*)(gbase) + (voff)[_i]), (PG8_LAS unsigned*)(lds + (bufoff) + ldsw + _i * 8192), 16, 0, 0); } while (0)
; #define PG8_LDA(dst, b, h) do { _Pragma("unroll") for (int m = 0; m < 4; ++m) _Pragma("unroll") for (int k = 0; k < 2; ++k) dst[m][k] = *(const PG8_LAS bf16x8*)(lds + PG8_SA(b, h) + aoff + m * 2048 + k * 1024); } while (0)
; #define PG8_LDB(dst, b, h) do { _Pragma("unroll") for (int n = 0; n < 2; ++n) _Pragma("unroll") for (int k = 0; k < 2; ++k) dst[n][k] = *(const PG8_LAS bf16x8*)(lds + PG8_SB(b, h) + boff + n * 2048 + k * 1024); } while (0)
; #define PG8_MMA(ai, bj, At, Bt) do { __builtin_amdgcn_s_setprio(1); _Pragma("unroll") for (int m = 0; m < 4; ++m) _Pragma("unroll") for (int n = 0; n < 2; ++n) _Pragma("unroll") for (int k = 0; k < 2; ++k) \
;         acc[ai][bj][m][n] = __builtin_amdgcn_mfma_f32_16x16x32_bf16(Bt[n][k], At[m][k], acc[ai][bj][m][n], 0, 0, 0); __builtin_amdgcn_s_setprio(0); } while (0)
; #define PG8_WAIT_V(n) asm volatile("s_waitcnt vmcnt(" #n ")" ::: "memory")
; #define PG8_WAIT_L(n) asm volatile("s_waitcnt lgkmcnt(" #n ")" ::: "memory")
; #define PG8_BAR __builtin_amdgcn_s_barrier()
; #define PG8_SCHED __builtin_amdgcn_sched_barrier(0)
; template <class Epi, class Sched, bool ALIGN_EPI = false, bool SP2 = false>
; __device__ __forceinline__ void gemm_phase(PG8_LAS unsigned char* lds, const Gemm g, const Sched& S, const Epi& E) {
;     ...
;             PG8_WAIT_V(8); PG8_WAIT_L(0); PG8_BAR; PG8_MMA(1, 0, At, B0); PG8_MMA(1, 1, At, B1); PG8_BAR; PG8_SCHED;
;             PG8_LDB(B0, 1, 0); PG8_LDB(B1, 1, 1); PG8_SCHED; PG8_LDA(At, 1, 0); PG8_STAGE(PG8_SA(0, 1), a2 + hstep, voffA);
;             PG8_WAIT_V(8); PG8_WAIT_L(0); PG8_BAR; PG8_MMA(0, 0, At, B0); PG8_MMA(0, 1, At, B1); PG8_BAR; PG8_SCHED;
	v_mfma_f32_16x16x32_bf16 v[62:65], v[146:149], v[212:215], v[62:65]
	v_mfma_f32_16x16x32_bf16 v[62:65], v[176:179], v[216:219], v[62:65]
	v_mfma_f32_16x16x32_bf16 v[46:49], v[176:179], v[224:227], v[46:49]
	v_mfma_f32_16x16x32_bf16 v[46:49], v[146:149], v[220:223], v[46:49]
	v_mfma_f32_16x16x32_bf16 v[30:33], v[146:149], v[228:231], v[30:33]
	v_mfma_f32_16x16x32_bf16 v[30:33], v[176:179], v[240:243], v[30:33]
	v_mfma_f32_16x16x32_bf16 v[14:17], v[176:179], v[248:251], v[14:17]
	v_mfma_f32_16x16x32_bf16 v[14:17], v[146:149], v[244:247], v[14:17]
	v_mfma_f32_16x16x32_bf16 v[10:13], v[180:183], v[244:247], v[10:13]
	v_mfma_f32_16x16x32_bf16 v[10:13], v[184:187], v[248:251], v[10:13]
	v_mfma_f32_16x16x32_bf16 v[58:61], v[184:187], v[216:219], v[58:61]
	v_mfma_f32_16x16x32_bf16 v[58:61], v[180:183], v[212:215], v[58:61]
	v_mfma_f32_16x16x32_bf16 v[42:45], v[180:183], v[220:223], v[42:45]
	v_mfma_f32_16x16x32_bf16 v[42:45], v[184:187], v[224:227], v[42:45]
	v_mfma_f32_16x16x32_bf16 v[26:29], v[184:187], v[240:243], v[26:29]
	v_mfma_f32_16x16x32_bf16 v[26:29], v[180:183], v[228:231], v[26:29]
	v_mfma_f32_16x16x32_bf16 v[22:25], v[188:191], v[228:231], v[22:25]
	v_mfma_f32_16x16x32_bf16 v[22:25], v[200:203], v[240:243], v[22:25]
	v_mfma_f32_16x16x32_bf16 v[54:57], v[200:203], v[216:219], v[54:57]
	v_mfma_f32_16x16x32_bf16 v[54:57], v[188:191], v[212:215], v[54:57]
	v_mfma_f32_16x16x32_bf16 v[38:41], v[188:191], v[220:223], v[38:41]
	v_mfma_f32_16x16x32_bf16 v[38:41], v[200:203], v[224:227], v[38:41]
	v_mfma_f32_16x16x32_bf16 v[6:9], v[200:203], v[248:251], v[6:9]
	v_mfma_f32_16x16x32_bf16 v[6:9], v[188:191], v[244:247], v[6:9]
	v_mfma_f32_16x16x32_bf16 v[2:5], v[204:207], v[244:247], v[2:5]
	v_mfma_f32_16x16x32_bf16 v[2:5], v[208:211], v[248:251], v[2:5]
	v_mfma_f32_16x16x32_bf16 v[50:53], v[208:211], v[216:219], v[50:53]
	v_mfma_f32_16x16x32_bf16 v[50:53], v[204:207], v[212:215], v[50:53]
	v_mfma_f32_16x16x32_bf16 v[34:37], v[204:207], v[220:223], v[34:37]
	v_mfma_f32_16x16x32_bf16 v[34:37], v[208:211], v[224:227], v[34:37]
	v_mfma_f32_16x16x32_bf16 v[18:21], v[208:211], v[240:243], v[18:21]
	v_mfma_f32_16x16x32_bf16 v[18:21], v[204:207], v[228:231], v[18:21]
	s_barrier
	s_add_i32 s63, 0, 0x18000
	v_add_u32_e32 v175, s63, v153
	s_add_i32 s70, 0, 0x1c000
	ds_read_b128 v[146:149], v175
	ds_read_b128 v[176:179], v175 offset:1024
	ds_read_b128 v[180:183], v175 offset:2048
	ds_read_b128 v[184:187], v175 offset:3072
	v_add_u32_e32 v175, s70, v153
	ds_read_b128 v[188:191], v175
	ds_read_b128 v[200:203], v175 offset:1024
	ds_read_b128 v[204:207], v175 offset:2048
	ds_read_b128 v[208:211], v175 offset:3072
	s_add_u32 s68, s68, 0x100000
	s_addc_u32 s69, s69, 0
	s_mov_b32 m0, s16
	v_lshl_add_u64 v[194:195], s[68:69], 0, v[130:131]
	ds_read_b128 v[212:215], v173 offset:32768
	ds_read_b128 v[216:219], v173 offset:33792
	ds_read_b128 v[220:223], v173 offset:34816
	ds_read_b128 v[224:227], v173 offset:35840
	ds_read_b128 v[228:231], v173 offset:36864
	ds_read_b128 v[240:243], v173 offset:37888
	ds_read_b128 v[244:247], v173 offset:38912
	ds_read_b128 v[248:251], v173 offset:39936
	global_load_lds_dwordx4 v[194:195], off
	v_lshl_add_u64 v[194:195], s[68:69], 0, v[134:135]
	s_mov_b32 m0, s17
	s_nop 0
	global_load_lds_dwordx4 v[194:195], off
	s_waitcnt vmcnt(8)
	s_waitcnt lgkmcnt(0)
	s_barrier
	v_mfma_f32_16x16x32_bf16 v[126:129], v[146:149], v[212:215], v[126:129]
	v_mfma_f32_16x16x32_bf16 v[126:129], v[176:179], v[216:219], v[126:129]
	v_mfma_f32_16x16x32_bf16 v[110:113], v[176:179], v[224:227], v[110:113]
	v_mfma_f32_16x16x32_bf16 v[110:113], v[146:149], v[220:223], v[110:113]
	v_mfma_f32_16x16x32_bf16 v[94:97], v[146:149], v[228:231], v[94:97]
	v_mfma_f32_16x16x32_bf16 v[94:97], v[176:179], v[240:243], v[94:97]
	v_mfma_f32_16x16x32_bf16 v[78:81], v[176:179], v[248:251], v[78:81]
	v_mfma_f32_16x16x32_bf16 v[78:81], v[146:149], v[244:247], v[78:81]
	v_mfma_f32_16x16x32_bf16 v[74:77], v[180:183], v[244:247], v[74:77]
	v_mfma_f32_16x16x32_bf16 v[74:77], v[184:187], v[248:251], v[74:77]
	v_mfma_f32_16x16x32_bf16 v[122:125], v[184:187], v[216:219], v[122:125]
	v_mfma_f32_16x16x32_bf16 v[122:125], v[180:183], v[212:215], v[122:125]
	v_mfma_f32_16x16x32_bf16 v[106:109], v[180:183], v[220:223], v[106:109]
	v_mfma_f32_16x16x32_bf16 v[106:109], v[184:187], v[224:227], v[106:109]
	v_mfma_f32_16x16x32_bf16 v[90:93], v[184:187], v[240:243], v[90:93]
	v_mfma_f32_16x16x32_bf16 v[90:93], v[180:183], v[228:231], v[90:93]
	v_mfma_f32_16x16x32_bf16 v[86:89], v[188:191], v[228:231], v[86:89]
	v_mfma_f32_16x16x32_bf16 v[86:89], v[200:203], v[240:243], v[86:89]
	v_mfma_f32_16x16x32_bf16 v[118:121], v[200:203], v[216:219], v[118:121]
	v_mfma_f32_16x16x32_bf16 v[118:121], v[188:191], v[212:215], v[118:121]
	v_mfma_f32_16x16x32_bf16 v[102:105], v[188:191], v[220:223], v[102:105]
	v_mfma_f32_16x16x32_bf16 v[102:105], v[200:203], v[224:227], v[102:105]
	v_mfma_f32_16x16x32_bf16 v[70:73], v[200:203], v[248:251], v[70:73]
	v_mfma_f32_16x16x32_bf16 v[70:73], v[188:191], v[244:247], v[70:73]
	v_mfma_f32_16x16x32_bf16 v[66:69], v[204:207], v[244:247], v[66:69]
	v_mfma_f32_16x16x32_bf16 v[66:69], v[208:211], v[248:251], v[66:69]
	v_mfma_f32_16x16x32_bf16 v[114:117], v[208:211], v[216:219], v[114:117]
	v_mfma_f32_16x16x32_bf16 v[114:117], v[204:207], v[212:215], v[114:117]
	v_mfma_f32_16x16x32_bf16 v[98:101], v[204:207], v[220:223], v[98:101]
	v_mfma_f32_16x16x32_bf16 v[98:101], v[208:211], v[224:227], v[98:101]
	v_mfma_f32_16x16x32_bf16 v[82:85], v[208:211], v[240:243], v[82:85]
	v_mfma_f32_16x16x32_bf16 v[82:85], v[204:207], v[228:231], v[82:85]
	s_barrier
; #define PG8_STAGE(bufoff, gbase, voff) do { _Pragma("unroll") for (int _i = 0; _i < 2; ++_i) \
;         __builtin_amdgcn_global_load_lds((const unsigned*)((const char*)(gbase) + (voff)[_i]), (PG8_LAS unsigned*)(lds + (bufoff) + ldsw + _i * 8192), 16, 0, 0); } while (0)
; #define PG8_LDA(dst, b, h) do { _Pragma("unroll") for (int m = 0; m < 4; ++m) _Pragma("unroll") for (int k = 0; k < 2; ++k) dst[m][k] = *(const PG8_LAS bf16x8*)(lds + PG8_SA(b, h) + aoff + m * 2048 + k * 1024); } while (0)
; #define PG8_MMA(ai, bj, At, Bt) do { __builtin_amdgcn_s_setprio(1); _Pragma("unroll") for (int m = 0; m < 4; ++m) _Pragma("unroll") for (int n = 0; n < 2; ++n) _Pragma("unroll") for (int k = 0; k < 2; ++k) \
;         acc[ai][bj][m][n] = __builtin_amdgcn_mfma_f32_16x16x32_bf16(Bt[n][k], At[m][k], acc[ai][bj][m][n], 0, 0, 0); __builtin_amdgcn_s_setprio(0); } while (0)
; #define PG8_WAIT_V(n) asm volatile("s_waitcnt vmcnt(" #n ")" ::: "memory")
; #define PG8_WAIT_L(n) asm volatile("s_waitcnt lgkmcnt(" #n ")" ::: "memory")
; #define PG8_BAR __builtin_amdgcn_s_barrier()
; #define PG8_SCHED __builtin_amdgcn_sched_barrier(0)
; template <class Epi, class Sched, bool ALIGN_EPI = false, bool SP2 = false>
; __device__ __forceinline__ void gemm_phase(PG8_LAS unsigned char* lds, const Gemm g, const Sched& S, const Epi& E) {
;     ...
;         for (int t = 0; t < nt; t += 2) {
;     ...
;             PG8_LDA(At, 1, 1); PG8_STAGE(PG8_SB(1, 0), b3, voffB); PG8_STAGE(PG8_SB(1, 1), b3 + hstep, voffB); PG8_STAGE(PG8_SA(1, 0), a3, voffA);
;             PG8_WAIT_V(8); PG8_WAIT_L(0); PG8_BAR; PG8_MMA(1, 0, At, B0); PG8_MMA(1, 1, At, B1); PG8_BAR; PG8_SCHED;
	s_add_i32 s63, s63, s2
	v_lshl_add_u64 v[150:151], v[150:151], 0, s[44:45]
	s_mov_b32 m0, s63
	ds_read_b128 v[212:215], v173 offset:49152
	ds_read_b128 v[216:219], v173 offset:50176
	ds_read_b128 v[220:223], v173 offset:51200
	ds_read_b128 v[224:227], v173 offset:52224
	ds_read_b128 v[228:231], v173 offset:53248
	ds_read_b128 v[240:243], v173 offset:54272
	ds_read_b128 v[244:247], v173 offset:55296
	ds_read_b128 v[248:251], v173 offset:56320
	global_load_lds_dwordx4 v[150:151], off
	s_add_i32 m0, s63, 0x2000
	s_add_u32 s66, s66, 0x100080
	v_lshl_add_u64 v[150:151], v[192:193], 0, s[44:45]
	s_addc_u32 s67, s67, 0
	s_add_i32 s63, s70, s2
	global_load_lds_dwordx4 v[150:151], off
	v_lshl_add_u64 v[150:151], s[66:67], 0, v[132:133]
	s_mov_b32 m0, s63
	s_nop 0
	global_load_lds_dwordx4 v[150:151], off
	v_lshl_add_u64 v[150:151], s[66:67], 0, v[136:137]
	s_add_i32 m0, s63, 0x2000
	s_nop 0
	global_load_lds_dwordx4 v[150:151], off
	v_lshl_add_u64 v[150:151], v[232:233], 0, s[44:45]
	s_mov_b32 m0, s26
	s_nop 0
	global_load_lds_dwordx4 v[150:151], off
	v_lshl_add_u64 v[150:151], v[252:253], 0, s[44:45]
	s_mov_b32 m0, s27
	s_nop 0
	global_load_lds_dwordx4 v[150:151], off
	s_waitcnt vmcnt(8)
	s_waitcnt lgkmcnt(0)
	s_barrier
	v_mfma_f32_16x16x32_bf16 v[62:65], v[146:149], v[212:215], v[62:65]
	v_mfma_f32_16x16x32_bf16 v[62:65], v[176:179], v[216:219], v[62:65]
	v_mfma_f32_16x16x32_bf16 v[46:49], v[176:179], v[224:227], v[46:49]
	v_mfma_f32_16x16x32_bf16 v[46:49], v[146:149], v[220:223], v[46:49]
	v_mfma_f32_16x16x32_bf16 v[30:33], v[146:149], v[228:231], v[30:33]
	v_mfma_f32_16x16x32_bf16 v[30:33], v[176:179], v[240:243], v[30:33]
	v_mfma_f32_16x16x32_bf16 v[14:17], v[176:179], v[248:251], v[14:17]
	v_mfma_f32_16x16x32_bf16 v[14:17], v[146:149], v[244:247], v[14:17]
	v_mfma_f32_16x16x32_bf16 v[10:13], v[180:183], v[244:247], v[10:13]
	v_mfma_f32_16x16x32_bf16 v[10:13], v[184:187], v[248:251], v[10:13]
	v_mfma_f32_16x16x32_bf16 v[58:61], v[184:187], v[216:219], v[58:61]
	v_mfma_f32_16x16x32_bf16 v[58:61], v[180:183], v[212:215], v[58:61]
	v_mfma_f32_16x16x32_bf16 v[42:45], v[180:183], v[220:223], v[42:45]
	v_mfma_f32_16x16x32_bf16 v[42:45], v[184:187], v[224:227], v[42:45]
	v_mfma_f32_16x16x32_bf16 v[26:29], v[184:187], v[240:243], v[26:29]
	v_mfma_f32_16x16x32_bf16 v[26:29], v[180:183], v[228:231], v[26:29]
	v_mfma_f32_16x16x32_bf16 v[22:25], v[188:191], v[228:231], v[22:25]
	v_mfma_f32_16x16x32_bf16 v[22:25], v[200:203], v[240:243], v[22:25]
	v_mfma_f32_16x16x32_bf16 v[54:57], v[200:203], v[216:219], v[54:57]
	v_mfma_f32_16x16x32_bf16 v[54:57], v[188:191], v[212:215], v[54:57]
	v_mfma_f32_16x16x32_bf16 v[38:41], v[188:191], v[220:223], v[38:41]
	v_mfma_f32_16x16x32_bf16 v[38:41], v[200:203], v[224:227], v[38:41]
	v_mfma_f32_16x16x32_bf16 v[6:9], v[200:203], v[248:251], v[6:9]
	v_mfma_f32_16x16x32_bf16 v[6:9], v[188:191], v[244:247], v[6:9]
	v_mfma_f32_16x16x32_bf16 v[2:5], v[204:207], v[244:247], v[2:5]
	v_mfma_f32_16x16x32_bf16 v[2:5], v[208:211], v[248:251], v[2:5]
	v_mfma_f32_16x16x32_bf16 v[50:53], v[208:211], v[216:219], v[50:53]
	v_mfma_f32_16x16x32_bf16 v[50:53], v[204:207], v[212:215], v[50:53]
	v_mfma_f32_16x16x32_bf16 v[34:37], v[204:207], v[220:223], v[34:37]
	v_mfma_f32_16x16x32_bf16 v[34:37], v[208:211], v[224:227], v[34:37]
	v_mfma_f32_16x16x32_bf16 v[18:21], v[208:211], v[240:243], v[18:21]
	v_mfma_f32_16x16x32_bf16 v[18:21], v[204:207], v[228:231], v[18:21]
	s_barrier
	s_add_i32 s61, s61, 2
	s_add_u32 s64, s64, 0x100
	s_addc_u32 s65, s65, 0
	s_add_u32 s53, s53, 0x100
	s_addc_u32 s55, s55, 0
	s_cmp_gt_u32 s61, 61
	s_cbranch_scc0 .LBB0_1203
	s_and_b64 vcc, exec, s[46:47]
	s_cbranch_vccz .LBB0_1206
	s_barrier

; #define PG8_STAGE(bufoff, gbase, voff) do { _Pragma("unroll") for (int _i = 0; _i < 2; ++_i) \
;         __builtin_amdgcn_global_load_lds((const unsigned*)((const char*)(gbase) + (voff)[_i]), (PG8_LAS unsigned*)(lds + (bufoff) + ldsw + _i * 8192), 16, 0, 0); } while (0)
; #define PG8_LDA(dst, b, h) do { _Pragma("unroll") for (int m = 0; m < 4; ++m) _Pragma("unroll") for (int k = 0; k < 2; ++k) dst[m][k] = *(const PG8_LAS bf16x8*)(lds + PG8_SA(b, h) + aoff + m * 2048 + k * 1024); } while (0)
; #define PG8_LDB(dst, b, h) do { _Pragma("unroll") for (int n = 0; n < 2; ++n) _Pragma("unroll") for (int k = 0; k < 2; ++k) dst[n][k] = *(const PG8_LAS bf16x8*)(lds + PG8_SB(b, h) + boff + n * 2048 + k * 1024); } while (0)
; #define PG8_MMA(ai, bj, At, Bt) do { __builtin_amdgcn_s_setprio(1); _Pragma("unroll") for (int m = 0; m < 4; ++m) _Pragma("unroll") for (int n = 0; n < 2; ++n) _Pragma("unroll") for (int k = 0; k < 2; ++k) \
;         acc[ai][bj][m][n] = __builtin_amdgcn_mfma_f32_16x16x32_bf16(Bt[n][k], At[m][k], acc[ai][bj][m][n], 0, 0, 0); __builtin_amdgcn_s_setprio(0); } while (0)
; #define PG8_WAIT_V(n) asm volatile("s_waitcnt vmcnt(" #n ")" ::: "memory")
; #define PG8_WAIT_L(n) asm volatile("s_waitcnt lgkmcnt(" #n ")" ::: "memory")
; template <class Epi, class Sched, bool ALIGN_EPI = false, bool SP2 = false>
; __device__ __forceinline__ void gemm_phase(PG8_LAS unsigned char* lds, const Gemm g, const Sched& S, const Epi& E) {
;     ...
;             const bool last = (t == nt - 2);
;             const char* a1 = cA + (size_t)(t + 1) * kstep;
;             const char* a2 = last ? nA : cA + (size_t)(t + 2) * kstep; const char* b2 = last ? nB : cB + (size_t)(t + 2) * kstep;
;             const char* a3 = a2 + kstep; const char* b3 = b2 + kstep;
;             if (last && has_next) S.a_ready(nxt);
;             if constexpr (SP2) {
;             PG8_LDB(B0, 0, 0); PG8_LDB(B1, 0, 1); PG8_SCHED; PG8_LDA(At, 0, 0); PG8_STAGE(PG8_SA(1, 1), a1 + hstep, voffA);
;             PG8_WAIT_V(8); PG8_WAIT_L(0); PG8_BAR; PG8_MMA(0, 0, At, B0); PG8_MMA(0, 1, At, B1); PG8_BAR; PG8_SCHED;
;             PG8_LDA(At, 0, 1); PG8_STAGE(PG8_SB(0, 0), b2, voffB); PG8_STAGE(PG8_SB(0, 1), b2 + hstep, voffB); PG8_STAGE(PG8_SA(0, 0), a2, voffA);
;             PG8_WAIT_V(8); PG8_WAIT_L(0); PG8_BAR; PG8_MMA(1, 0, At, B0); PG8_MMA(1, 1, At, B1); PG8_BAR; PG8_SCHED;
.LBB0_1230:
	ds_read_b128 v[146:149], v140
	ds_read_b128 v[150:153], v140 offset:1024
	ds_read_b128 v[154:157], v140 offset:2048
	ds_read_b128 v[158:161], v140 offset:3072
	ds_read_b128 v[168:171], v141
	ds_read_b128 v[172:175], v141 offset:1024
	ds_read_b128 v[176:179], v141 offset:2048
	ds_read_b128 v[180:183], v141 offset:3072
	s_add_u32 s50, s46, 0x100
	s_addc_u32 s51, s47, 0
	s_cmp_lg_u32 s30, 12
	s_cselect_b32 s52, s50, 0
	s_cselect_b32 s53, s51, 0
	s_add_u32 s54, s10, s52
	s_addc_u32 s55, s11, s53
	s_add_u32 s52, s8, s52
	s_addc_u32 s53, s9, s53
	s_mov_b32 m0, s33
	v_lshl_add_u64 v[162:163], v[134:135], 0, s[46:47]
	ds_read_b128 v[184:187], v142
	ds_read_b128 v[188:191], v142 offset:1024
	ds_read_b128 v[200:203], v142 offset:2048
	ds_read_b128 v[204:207], v142 offset:3072
	ds_read_b128 v[208:211], v142 offset:4096
	ds_read_b128 v[212:215], v142 offset:5120
	ds_read_b128 v[216:219], v142 offset:6144
	ds_read_b128 v[220:223], v142 offset:7168
	global_load_lds_dwordx4 v[162:163], off
	v_lshl_add_u64 v[162:163], v[136:137], 0, s[46:47]
	s_mov_b32 m0, s34
	s_nop 0
	global_load_lds_dwordx4 v[162:163], off
	s_waitcnt vmcnt(8)
	s_waitcnt lgkmcnt(0)
	s_barrier
	v_mfma_f32_16x16x32_bf16 v[126:129], v[146:149], v[184:187], v[126:129]
	v_mfma_f32_16x16x32_bf16 v[126:129], v[150:153], v[188:191], v[126:129]
	v_mfma_f32_16x16x32_bf16 v[118:121], v[150:153], v[204:207], v[118:121]
	v_mfma_f32_16x16x32_bf16 v[118:121], v[146:149], v[200:203], v[118:121]
	v_mfma_f32_16x16x32_bf16 v[106:109], v[146:149], v[208:211], v[106:109]
	v_mfma_f32_16x16x32_bf16 v[106:109], v[150:153], v[212:215], v[106:109]
	v_mfma_f32_16x16x32_bf16 v[90:93], v[150:153], v[220:223], v[90:93]
	v_mfma_f32_16x16x32_bf16 v[90:93], v[146:149], v[216:219], v[90:93]
	v_mfma_f32_16x16x32_bf16 v[82:85], v[154:157], v[216:219], v[82:85]
	v_mfma_f32_16x16x32_bf16 v[82:85], v[158:161], v[220:223], v[82:85]
	v_mfma_f32_16x16x32_bf16 v[122:125], v[158:161], v[188:191], v[122:125]
	v_mfma_f32_16x16x32_bf16 v[122:125], v[154:157], v[184:187], v[122:125]
	v_mfma_f32_16x16x32_bf16 v[114:117], v[154:157], v[200:203], v[114:117]
	v_mfma_f32_16x16x32_bf16 v[114:117], v[158:161], v[204:207], v[114:117]
	v_mfma_f32_16x16x32_bf16 v[98:101], v[158:161], v[212:215], v[98:101]
	v_mfma_f32_16x16x32_bf16 v[98:101], v[154:157], v[208:211], v[98:101]
	v_mfma_f32_16x16x32_bf16 v[78:81], v[168:171], v[208:211], v[78:81]
	v_mfma_f32_16x16x32_bf16 v[78:81], v[172:175], v[212:215], v[78:81]
	v_mfma_f32_16x16x32_bf16 v[110:113], v[172:175], v[188:191], v[110:113]
	v_mfma_f32_16x16x32_bf16 v[110:113], v[168:171], v[184:187], v[110:113]
	v_mfma_f32_16x16x32_bf16 v[94:97], v[168:171], v[200:203], v[94:97]
	v_mfma_f32_16x16x32_bf16 v[94:97], v[172:175], v[204:207], v[94:97]
	v_mfma_f32_16x16x32_bf16 v[70:73], v[172:175], v[220:223], v[70:73]
	v_mfma_f32_16x16x32_bf16 v[70:73], v[168:171], v[216:219], v[70:73]
	v_mfma_f32_16x16x32_bf16 v[66:69], v[176:179], v[216:219], v[66:69]
	v_mfma_f32_16x16x32_bf16 v[66:69], v[180:183], v[220:223], v[66:69]
	v_mfma_f32_16x16x32_bf16 v[102:105], v[180:183], v[188:191], v[102:105]
	v_mfma_f32_16x16x32_bf16 v[102:105], v[176:179], v[184:187], v[102:105]
	v_mfma_f32_16x16x32_bf16 v[86:89], v[176:179], v[200:203], v[86:89]
	v_mfma_f32_16x16x32_bf16 v[86:89], v[180:183], v[204:207], v[86:89]
	v_mfma_f32_16x16x32_bf16 v[74:77], v[180:183], v[212:215], v[74:77]
	v_mfma_f32_16x16x32_bf16 v[74:77], v[176:179], v[208:211], v[74:77]
	s_barrier
	s_mov_b32 m0, s35
	v_lshl_add_u64 v[162:163], s[52:53], 0, v[130:131]
	s_add_u32 s46, s52, 0x100000
	ds_read_b128 v[184:187], v142 offset:16384
	ds_read_b128 v[188:191], v142 offset:17408
	ds_read_b128 v[200:203], v142 offset:18432
	ds_read_b128 v[204:207], v142 offset:19456
	ds_read_b128 v[208:211], v142 offset:20480
	ds_read_b128 v[212:215], v142 offset:21504
	ds_read_b128 v[216:219], v142 offset:22528
	ds_read_b128 v[220:223], v142 offset:23552
	global_load_lds_dwordx4 v[162:163], off
	v_lshl_add_u64 v[192:193], s[52:53], 0, v[132:133]
	s_mov_b32 m0, s39
	s_addc_u32 s47, s53, 0
	global_load_lds_dwordx4 v[192:193], off
	v_lshl_add_u64 v[194:195], s[46:47], 0, v[130:131]
	s_mov_b32 m0, s40
	v_lshl_add_u64 v[224:225], s[54:55], 0, v[132:133]
	global_load_lds_dwordx4 v[194:195], off
	v_lshl_add_u64 v[194:195], s[46:47], 0, v[132:133]
	s_mov_b32 m0, s41
	s_nop 0
	global_load_lds_dwordx4 v[194:195], off
	v_lshl_add_u64 v[194:195], s[54:55], 0, v[130:131]
	s_mov_b32 m0, s7
	s_nop 0
	global_load_lds_dwordx4 v[194:195], off
	s_mov_b32 m0, s16
	s_nop 0
	global_load_lds_dwordx4 v[224:225], off
	s_waitcnt vmcnt(8)
	s_waitcnt lgkmcnt(0)
	s_barrier
; #define PG8_STAGE(bufoff, gbase, voff) do { _Pragma("unroll") for (int _i = 0; _i < 2; ++_i) \
;         __builtin_amdgcn_global_load_lds((const unsigned*)((const char*)(gbase) + (voff)[_i]), (PG8_LAS unsigned*)(lds + (bufoff) + ldsw + _i * 8192), 16, 0, 0); } while (0)
; #define PG8_LDA(dst, b, h) do { _Pragma("unroll") for (int m = 0; m < 4; ++m) _Pragma("unroll") for (int k = 0; k < 2; ++k) dst[m][k] = *(const PG8_LAS bf16x8*)(lds + PG8_SA(b, h) + aoff + m * 2048 + k * 1024); } while (0)
; #define PG8_LDB(dst, b, h) do { _Pragma("unroll") for (int n = 0; n < 2; ++n) _Pragma("unroll") for (int k = 0; k < 2; ++k) dst[n][k] = *(const PG8_LAS bf16x8*)(lds + PG8_SB(b, h) + boff + n * 2048 + k * 1024); } while (0)
; #define PG8_MMA(ai, bj, At, Bt) do { __builtin_amdgcn_s_setprio(1); _Pragma("unroll") for (int m = 0; m < 4; ++m) _Pragma("unroll") for (int n = 0; n < 2; ++n) _Pragma("unroll") for (int k = 0; k < 2; ++k) \
;         acc[ai][bj][m][n] = __builtin_amdgcn_mfma_f32_16x16x32_bf16(Bt[n][k], At[m][k], acc[ai][bj][m][n], 0, 0, 0); __builtin_amdgcn_s_setprio(0); } while (0)
; #define PG8_WAIT_V(n) asm volatile("s_waitcnt vmcnt(" #n ")" ::: "memory")
; #define PG8_WAIT_L(n) asm volatile("s_waitcnt lgkmcnt(" #n ")" ::: "memory")
; #define PG8_BAR __builtin_amdgcn_s_barrier()
; #define PG8_SCHED __builtin_amdgcn_sched_barrier(0)
; template <class Epi, class Sched, bool ALIGN_EPI = false, bool SP2 = false>
; __device__ __forceinline__ void gemm_phase(PG8_LAS unsigned char* lds, const Gemm g, const Sched& S, const Epi& E) {
;     ...
;             PG8_WAIT_V(8); PG8_WAIT_L(0); PG8_BAR; PG8_MMA(1, 0, At, B0); PG8_MMA(1, 1, At, B1); PG8_BAR; PG8_SCHED;
;             PG8_LDB(B0, 1, 0); PG8_LDB(B1, 1, 1); PG8_SCHED; PG8_LDA(At, 1, 0); PG8_STAGE(PG8_SA(0, 1), a2 + hstep, voffA);
;             PG8_WAIT_V(8); PG8_WAIT_L(0); PG8_BAR; PG8_MMA(0, 0, At, B0); PG8_MMA(0, 1, At, B1); PG8_BAR; PG8_SCHED;
	v_mfma_f32_16x16x32_bf16 v[62:65], v[146:149], v[184:187], v[62:65]
	v_mfma_f32_16x16x32_bf16 v[62:65], v[150:153], v[188:191], v[62:65]
	v_mfma_f32_16x16x32_bf16 v[54:57], v[150:153], v[204:207], v[54:57]
	v_mfma_f32_16x16x32_bf16 v[54:57], v[146:149], v[200:203], v[54:57]
	v_mfma_f32_16x16x32_bf16 v[42:45], v[146:149], v[208:211], v[42:45]
	v_mfma_f32_16x16x32_bf16 v[42:45], v[150:153], v[212:215], v[42:45]
	v_mfma_f32_16x16x32_bf16 v[26:29], v[150:153], v[220:223], v[26:29]
	v_mfma_f32_16x16x32_bf16 v[26:29], v[146:149], v[216:219], v[26:29]
	v_mfma_f32_16x16x32_bf16 v[18:21], v[154:157], v[216:219], v[18:21]
	v_mfma_f32_16x16x32_bf16 v[18:21], v[158:161], v[220:223], v[18:21]
	v_mfma_f32_16x16x32_bf16 v[58:61], v[158:161], v[188:191], v[58:61]
	v_mfma_f32_16x16x32_bf16 v[58:61], v[154:157], v[184:187], v[58:61]
	v_mfma_f32_16x16x32_bf16 v[50:53], v[154:157], v[200:203], v[50:53]
	v_mfma_f32_16x16x32_bf16 v[50:53], v[158:161], v[204:207], v[50:53]
	v_mfma_f32_16x16x32_bf16 v[34:37], v[158:161], v[212:215], v[34:37]
	v_mfma_f32_16x16x32_bf16 v[34:37], v[154:157], v[208:211], v[34:37]
	v_mfma_f32_16x16x32_bf16 v[14:17], v[168:171], v[208:211], v[14:17]
	v_mfma_f32_16x16x32_bf16 v[14:17], v[172:175], v[212:215], v[14:17]
	v_mfma_f32_16x16x32_bf16 v[46:49], v[172:175], v[188:191], v[46:49]
	v_mfma_f32_16x16x32_bf16 v[46:49], v[168:171], v[184:187], v[46:49]
	v_mfma_f32_16x16x32_bf16 v[30:33], v[168:171], v[200:203], v[30:33]
	v_mfma_f32_16x16x32_bf16 v[30:33], v[172:175], v[204:207], v[30:33]
	v_mfma_f32_16x16x32_bf16 v[6:9], v[172:175], v[220:223], v[6:9]
	v_mfma_f32_16x16x32_bf16 v[6:9], v[168:171], v[216:219], v[6:9]
	v_mfma_f32_16x16x32_bf16 v[2:5], v[176:179], v[216:219], v[2:5]
	v_mfma_f32_16x16x32_bf16 v[2:5], v[180:183], v[220:223], v[2:5]
	v_mfma_f32_16x16x32_bf16 v[38:41], v[180:183], v[188:191], v[38:41]
	v_mfma_f32_16x16x32_bf16 v[38:41], v[176:179], v[184:187], v[38:41]
	v_mfma_f32_16x16x32_bf16 v[22:25], v[176:179], v[200:203], v[22:25]
	v_mfma_f32_16x16x32_bf16 v[22:25], v[180:183], v[204:207], v[22:25]
	v_mfma_f32_16x16x32_bf16 v[10:13], v[180:183], v[212:215], v[10:13]
	v_mfma_f32_16x16x32_bf16 v[10:13], v[176:179], v[208:211], v[10:13]
	s_barrier
	ds_read_b128 v[146:149], v143
	ds_read_b128 v[150:153], v143 offset:1024
	ds_read_b128 v[154:157], v143 offset:2048
	ds_read_b128 v[158:161], v143 offset:3072
	ds_read_b128 v[168:171], v144
	ds_read_b128 v[172:175], v144 offset:1024
	ds_read_b128 v[176:179], v144 offset:2048
	ds_read_b128 v[180:183], v144 offset:3072
	s_add_u32 s46, s54, 0x100000
	s_addc_u32 s47, s55, 0
	s_mov_b32 m0, s17
	v_lshl_add_u64 v[226:227], s[46:47], 0, v[130:131]
	ds_read_b128 v[184:187], v142 offset:32768
	ds_read_b128 v[188:191], v142 offset:33792
	ds_read_b128 v[200:203], v142 offset:34816
	ds_read_b128 v[204:207], v142 offset:35840
	ds_read_b128 v[208:211], v142 offset:36864
	ds_read_b128 v[212:215], v142 offset:37888
	ds_read_b128 v[216:219], v142 offset:38912
	ds_read_b128 v[220:223], v142 offset:39936
	global_load_lds_dwordx4 v[226:227], off
	v_lshl_add_u64 v[226:227], s[46:47], 0, v[132:133]
	s_mov_b32 m0, s26
	s_nop 0
	global_load_lds_dwordx4 v[226:227], off
	s_waitcnt vmcnt(8)
	s_waitcnt lgkmcnt(0)
	s_barrier
	v_mfma_f32_16x16x32_bf16 v[126:129], v[146:149], v[184:187], v[126:129]
	v_mfma_f32_16x16x32_bf16 v[126:129], v[150:153], v[188:191], v[126:129]
	v_mfma_f32_16x16x32_bf16 v[118:121], v[150:153], v[204:207], v[118:121]
	v_mfma_f32_16x16x32_bf16 v[118:121], v[146:149], v[200:203], v[118:121]
	v_mfma_f32_16x16x32_bf16 v[106:109], v[146:149], v[208:211], v[106:109]
	v_mfma_f32_16x16x32_bf16 v[106:109], v[150:153], v[212:215], v[106:109]
	v_mfma_f32_16x16x32_bf16 v[90:93], v[150:153], v[220:223], v[90:93]
	v_mfma_f32_16x16x32_bf16 v[90:93], v[146:149], v[216:219], v[90:93]
	v_mfma_f32_16x16x32_bf16 v[82:85], v[154:157], v[216:219], v[82:85]
	v_mfma_f32_16x16x32_bf16 v[82:85], v[158:161], v[220:223], v[82:85]
	v_mfma_f32_16x16x32_bf16 v[122:125], v[158:161], v[188:191], v[122:125]
	v_mfma_f32_16x16x32_bf16 v[122:125], v[154:157], v[184:187], v[122:125]
	v_mfma_f32_16x16x32_bf16 v[114:117], v[154:157], v[200:203], v[114:117]
	v_mfma_f32_16x16x32_bf16 v[114:117], v[158:161], v[204:207], v[114:117]
	v_mfma_f32_16x16x32_bf16 v[98:101], v[158:161], v[212:215], v[98:101]
	v_mfma_f32_16x16x32_bf16 v[98:101], v[154:157], v[208:211], v[98:101]
	v_mfma_f32_16x16x32_bf16 v[78:81], v[168:171], v[208:211], v[78:81]
	v_mfma_f32_16x16x32_bf16 v[78:81], v[172:175], v[212:215], v[78:81]
	v_mfma_f32_16x16x32_bf16 v[110:113], v[172:175], v[188:191], v[110:113]
	v_mfma_f32_16x16x32_bf16 v[110:113], v[168:171], v[184:187], v[110:113]
	v_mfma_f32_16x16x32_bf16 v[94:97], v[168:171], v[200:203], v[94:97]
	v_mfma_f32_16x16x32_bf16 v[94:97], v[172:175], v[204:207], v[94:97]
	v_mfma_f32_16x16x32_bf16 v[70:73], v[172:175], v[220:223], v[70:73]
	v_mfma_f32_16x16x32_bf16 v[70:73], v[168:171], v[216:219], v[70:73]
	v_mfma_f32_16x16x32_bf16 v[66:69], v[176:179], v[216:219], v[66:69]
	v_mfma_f32_16x16x32_bf16 v[66:69], v[180:183], v[220:223], v[66:69]
	v_mfma_f32_16x16x32_bf16 v[102:105], v[180:183], v[188:191], v[102:105]
	v_mfma_f32_16x16x32_bf16 v[102:105], v[176:179], v[184:187], v[102:105]
	v_mfma_f32_16x16x32_bf16 v[86:89], v[176:179], v[200:203], v[86:89]
	v_mfma_f32_16x16x32_bf16 v[86:89], v[180:183], v[204:207], v[86:89]
	v_mfma_f32_16x16x32_bf16 v[74:77], v[180:183], v[212:215], v[74:77]
	v_mfma_f32_16x16x32_bf16 v[74:77], v[176:179], v[208:211], v[74:77]
	s_barrier
; #define PG8_STAGE(bufoff, gbase, voff) do { _Pragma("unroll") for (int _i = 0; _i < 2; ++_i) \
;         __builtin_amdgcn_global_load_lds((const unsigned*)((const char*)(gbase) + (voff)[_i]), (PG8_LAS unsigned*)(lds + (bufoff) + ldsw + _i * 8192), 16, 0, 0); } while (0)
; #define PG8_LDA(dst, b, h) do { _Pragma("unroll") for (int m = 0; m < 4; ++m) _Pragma("unroll") for (int k = 0; k < 2; ++k) dst[m][k] = *(const PG8_LAS bf16x8*)(lds + PG8_SA(b, h) + aoff + m * 2048 + k * 1024); } while (0)
; #define PG8_MMA(ai, bj, At, Bt) do { __builtin_amdgcn_s_setprio(1); _Pragma("unroll") for (int m = 0; m < 4; ++m) _Pragma("unroll") for (int n = 0; n < 2; ++n) _Pragma("unroll") for (int k = 0; k < 2; ++k) \
;         acc[ai][bj][m][n] = __builtin_amdgcn_mfma_f32_16x16x32_bf16(Bt[n][k], At[m][k], acc[ai][bj][m][n], 0, 0, 0); __builtin_amdgcn_s_setprio(0); } while (0)
; #define PG8_WAIT_V(n) asm volatile("s_waitcnt vmcnt(" #n ")" ::: "memory")
; #define PG8_WAIT_L(n) asm volatile("s_waitcnt lgkmcnt(" #n ")" ::: "memory")
; #define PG8_BAR __builtin_amdgcn_s_barrier()
; #define PG8_SCHED __builtin_amdgcn_sched_barrier(0)
; template <class Epi, class Sched, bool ALIGN_EPI = false, bool SP2 = false>
; __device__ __forceinline__ void gemm_phase(PG8_LAS unsigned char* lds, const Gemm g, const Sched& S, const Epi& E) {
;     ...
;             PG8_LDA(At, 1, 1); PG8_STAGE(PG8_SB(1, 0), b3, voffB); PG8_STAGE(PG8_SB(1, 1), b3 + hstep, voffB); PG8_STAGE(PG8_SA(1, 0), a3, voffA);
;             PG8_WAIT_V(8); PG8_WAIT_L(0); PG8_BAR; PG8_MMA(1, 0, At, B0); PG8_MMA(1, 1, At, B1); PG8_BAR; PG8_SCHED;
;     ...
;         if constexpr (ALIGN_EPI) { if (wr == 0) PG8_BAR; }
	s_mov_b32 m0, s44
	v_lshl_add_u64 v[162:163], v[162:163], 0, s[12:13]
	s_add_u32 s46, s52, 0x100080
	ds_read_b128 v[184:187], v142 offset:49152
	ds_read_b128 v[188:191], v142 offset:50176
	ds_read_b128 v[200:203], v142 offset:51200
	ds_read_b128 v[204:207], v142 offset:52224
	ds_read_b128 v[208:211], v142 offset:53248
	ds_read_b128 v[212:215], v142 offset:54272
	ds_read_b128 v[216:219], v142 offset:55296
	ds_read_b128 v[220:223], v142 offset:56320
	global_load_lds_dwordx4 v[162:163], off
	v_lshl_add_u64 v[162:163], v[192:193], 0, s[12:13]
	s_mov_b32 m0, s45
	s_addc_u32 s47, s53, 0
	global_load_lds_dwordx4 v[162:163], off
	v_lshl_add_u64 v[162:163], s[46:47], 0, v[130:131]
	s_mov_b32 m0, s56
	s_nop 0
	global_load_lds_dwordx4 v[162:163], off
	v_lshl_add_u64 v[162:163], s[46:47], 0, v[132:133]
	s_mov_b32 m0, s57
	s_nop 0
	global_load_lds_dwordx4 v[162:163], off
	v_lshl_add_u64 v[162:163], v[194:195], 0, s[12:13]
	s_mov_b32 m0, s28
	s_nop 0
	global_load_lds_dwordx4 v[162:163], off
	v_lshl_add_u64 v[162:163], v[224:225], 0, s[12:13]
	s_mov_b32 m0, s29
	s_nop 0
	global_load_lds_dwordx4 v[162:163], off
	s_waitcnt vmcnt(8)
	s_waitcnt lgkmcnt(0)
	s_barrier
	v_mfma_f32_16x16x32_bf16 v[62:65], v[146:149], v[184:187], v[62:65]
	v_mfma_f32_16x16x32_bf16 v[62:65], v[150:153], v[188:191], v[62:65]
	v_mfma_f32_16x16x32_bf16 v[54:57], v[150:153], v[204:207], v[54:57]
	v_mfma_f32_16x16x32_bf16 v[54:57], v[146:149], v[200:203], v[54:57]
	v_mfma_f32_16x16x32_bf16 v[42:45], v[146:149], v[208:211], v[42:45]
	v_mfma_f32_16x16x32_bf16 v[42:45], v[150:153], v[212:215], v[42:45]
	v_mfma_f32_16x16x32_bf16 v[26:29], v[150:153], v[220:223], v[26:29]
	v_mfma_f32_16x16x32_bf16 v[26:29], v[146:149], v[216:219], v[26:29]
	v_mfma_f32_16x16x32_bf16 v[18:21], v[154:157], v[216:219], v[18:21]
	v_mfma_f32_16x16x32_bf16 v[18:21], v[158:161], v[220:223], v[18:21]
	v_mfma_f32_16x16x32_bf16 v[58:61], v[158:161], v[188:191], v[58:61]
	v_mfma_f32_16x16x32_bf16 v[58:61], v[154:157], v[184:187], v[58:61]
	v_mfma_f32_16x16x32_bf16 v[50:53], v[154:157], v[200:203], v[50:53]
	v_mfma_f32_16x16x32_bf16 v[50:53], v[158:161], v[204:207], v[50:53]
	v_mfma_f32_16x16x32_bf16 v[34:37], v[158:161], v[212:215], v[34:37]
	v_mfma_f32_16x16x32_bf16 v[34:37], v[154:157], v[208:211], v[34:37]
	v_mfma_f32_16x16x32_bf16 v[14:17], v[168:171], v[208:211], v[14:17]
	v_mfma_f32_16x16x32_bf16 v[14:17], v[172:175], v[212:215], v[14:17]
	v_mfma_f32_16x16x32_bf16 v[46:49], v[172:175], v[188:191], v[46:49]
	v_mfma_f32_16x16x32_bf16 v[46:49], v[168:171], v[184:187], v[46:49]
	v_mfma_f32_16x16x32_bf16 v[30:33], v[168:171], v[200:203], v[30:33]
	v_mfma_f32_16x16x32_bf16 v[30:33], v[172:175], v[204:207], v[30:33]
	v_mfma_f32_16x16x32_bf16 v[6:9], v[172:175], v[220:223], v[6:9]
	v_mfma_f32_16x16x32_bf16 v[6:9], v[168:171], v[216:219], v[6:9]
	v_mfma_f32_16x16x32_bf16 v[2:5], v[176:179], v[216:219], v[2:5]
	v_mfma_f32_16x16x32_bf16 v[2:5], v[180:183], v[220:223], v[2:5]
	v_mfma_f32_16x16x32_bf16 v[38:41], v[180:183], v[188:191], v[38:41]
	v_mfma_f32_16x16x32_bf16 v[38:41], v[176:179], v[184:187], v[38:41]
	v_mfma_f32_16x16x32_bf16 v[22:25], v[176:179], v[200:203], v[22:25]
	v_mfma_f32_16x16x32_bf16 v[22:25], v[180:183], v[204:207], v[22:25]
	v_mfma_f32_16x16x32_bf16 v[10:13], v[180:183], v[212:215], v[10:13]
	v_mfma_f32_16x16x32_bf16 v[10:13], v[176:179], v[208:211], v[10:13]
	s_barrier
	s_add_i32 s30, s30, 2
	s_cmp_gt_u32 s30, 13
	s_mov_b64 s[46:47], s[50:51]
	s_cbranch_scc0 .LBB0_1230
	s_cmpk_lt_u32 s2, 0x100
	s_cbranch_scc0 .LBB0_1233
	s_barrier

; #define PG8_STAGE(bufoff, gbase, voff) do { _Pragma("unroll") for (int _i = 0; _i < 2; ++_i) \
;         __builtin_amdgcn_global_load_lds((const unsigned*)((const char*)(gbase) + (voff)[_i]), (PG8_LAS unsigned*)(lds + (bufoff) + ldsw + _i * 8192), 16, 0, 0); } while (0)
; #define PG8_LDA(dst, b, h) do { _Pragma("unroll") for (int m = 0; m < 4; ++m) _Pragma("unroll") for (int k = 0; k < 2; ++k) dst[m][k] = *(const PG8_LAS bf16x8*)(lds + PG8_SA(b, h) + aoff + m * 2048 + k * 1024); } while (0)
; #define PG8_LDB(dst, b, h) do { _Pragma("unroll") for (int n = 0; n < 2; ++n) _Pragma("unroll") for (int k = 0; k < 2; ++k) dst[n][k] = *(const PG8_LAS bf16x8*)(lds + PG8_SB(b, h) + boff + n * 2048 + k * 1024); } while (0)
; #define PG8_MMA(ai, bj, At, Bt) do { __builtin_amdgcn_s_setprio(1); _Pragma("unroll") for (int m = 0; m < 4; ++m) _Pragma("unroll") for (int n = 0; n < 2; ++n) _Pragma("unroll") for (int k = 0; k < 2; ++k) \
;         acc[ai][bj][m][n] = __builtin_amdgcn_mfma_f32_16x16x32_bf16(Bt[n][k], At[m][k], acc[ai][bj][m][n], 0, 0, 0); __builtin_amdgcn_s_setprio(0); } while (0)
; #define PG8_WAIT_V(n) asm volatile("s_waitcnt vmcnt(" #n ")" ::: "memory")
; #define PG8_BAR __builtin_amdgcn_s_barrier()
; template <class Epi, class Sched, bool ALIGN_EPI = false, bool SP2 = false>
; __device__ __forceinline__ void gemm_phase(PG8_LAS unsigned char* lds, const Gemm g, const Sched& S, const Epi& E) {
;     ...
;         for (int t = 0; t < nt; t += 2) {
;             const bool last = (t == nt - 2);
;             const char* a1 = cA + (size_t)(t + 1) * kstep;
;             const char* a2 = last ? nA : cA + (size_t)(t + 2) * kstep; const char* b2 = last ? nB : cB + (size_t)(t + 2) * kstep;
;             const char* a3 = a2 + kstep; const char* b3 = b2 + kstep;
;             if (last && has_next) S.a_ready(nxt);
;             if constexpr (SP2) {
;             PG8_LDB(B0, 0, 0); PG8_LDB(B1, 0, 1); PG8_SCHED; PG8_LDA(At, 0, 0); PG8_STAGE(PG8_SA(1, 1), a1 + hstep, voffA);
;             PG8_WAIT_V(8); PG8_WAIT_L(0); PG8_BAR; PG8_MMA(0, 0, At, B0); PG8_MMA(0, 1, At, B1); PG8_BAR; PG8_SCHED;
;             PG8_LDA(At, 0, 1); PG8_STAGE(PG8_SB(0, 0), b2, voffB); PG8_STAGE(PG8_SB(0, 1), b2 + hstep, voffB); PG8_STAGE(PG8_SA(0, 0), a2, voffA);
;             PG8_WAIT_V(8); PG8_WAIT_L(0); PG8_BAR; PG8_MMA(1, 0, At, B0); PG8_MMA(1, 1, At, B1); PG8_BAR; PG8_SCHED;
.LBB0_1478:
	v_add_u32_e32 v144, s31, v201
	v_add_u32_e32 v160, s52, v201
	ds_read_b128 v[132:135], v144
	ds_read_b128 v[136:139], v144 offset:1024
	ds_read_b128 v[140:143], v144 offset:2048
	ds_read_b128 v[144:147], v144 offset:3072
	ds_read_b128 v[148:151], v160
	ds_read_b128 v[152:155], v160 offset:1024
	ds_read_b128 v[156:159], v160 offset:2048
	ds_read_b128 v[160:163], v160 offset:3072
	s_add_u32 s50, s82, 0xfff00080
	s_addc_u32 s56, s83, -1
	s_and_b64 s[34:35], s[84:85], exec
	s_cselect_b32 s87, s65, s56
	s_cselect_b32 s86, s69, s50
	s_cselect_b32 s85, s67, s88
	s_cselect_b32 s84, s77, s79
	v_lshl_add_u64 v[192:193], s[82:83], 0, v[220:221]
	s_add_i32 m0, s28, 0xc000
	ds_read_b128 v[164:167], v242
	ds_read_b128 v[168:171], v242 offset:1024
	ds_read_b128 v[172:175], v242 offset:2048
	ds_read_b128 v[176:179], v242 offset:3072
	ds_read_b128 v[180:183], v242 offset:4096
	ds_read_b128 v[184:187], v242 offset:5120
	ds_read_b128 v[188:191], v242 offset:6144
	ds_read_b128 v[226:229], v242 offset:7168
	global_load_lds_dwordx4 v[192:193], off
	v_lshl_add_u64 v[192:193], s[82:83], 0, v[222:223]
	s_add_i32 m0, s28, 0xe000
	s_nop 0
	global_load_lds_dwordx4 v[192:193], off
	s_waitcnt vmcnt(8)
	s_waitcnt lgkmcnt(0)
	s_barrier
	v_mfma_f32_16x16x32_bf16 v[126:129], v[132:135], v[164:167], v[126:129]
	v_mfma_f32_16x16x32_bf16 v[126:129], v[136:139], v[168:171], v[126:129]
	v_mfma_f32_16x16x32_bf16 v[118:121], v[136:139], v[176:179], v[118:121]
	v_mfma_f32_16x16x32_bf16 v[118:121], v[132:135], v[172:175], v[118:121]
	v_mfma_f32_16x16x32_bf16 v[110:113], v[132:135], v[180:183], v[110:113]
	v_mfma_f32_16x16x32_bf16 v[110:113], v[136:139], v[184:187], v[110:113]
	v_mfma_f32_16x16x32_bf16 v[102:105], v[136:139], v[226:229], v[102:105]
	v_mfma_f32_16x16x32_bf16 v[102:105], v[132:135], v[188:191], v[102:105]
	v_mfma_f32_16x16x32_bf16 v[106:109], v[140:143], v[188:191], v[106:109]
	v_mfma_f32_16x16x32_bf16 v[106:109], v[144:147], v[226:229], v[106:109]
	v_mfma_f32_16x16x32_bf16 v[46:49], v[144:147], v[168:171], v[46:49]
	v_mfma_f32_16x16x32_bf16 v[46:49], v[140:143], v[164:167], v[46:49]
	v_mfma_f32_16x16x32_bf16 v[122:125], v[140:143], v[172:175], v[122:125]
	v_mfma_f32_16x16x32_bf16 v[122:125], v[144:147], v[176:179], v[122:125]
	v_mfma_f32_16x16x32_bf16 v[114:117], v[144:147], v[184:187], v[114:117]
	v_mfma_f32_16x16x32_bf16 v[114:117], v[140:143], v[180:183], v[114:117]
	v_mfma_f32_16x16x32_bf16 v[62:65], v[148:151], v[180:183], v[62:65]
	v_mfma_f32_16x16x32_bf16 v[62:65], v[152:155], v[184:187], v[62:65]
	v_mfma_f32_16x16x32_bf16 v[54:57], v[152:155], v[168:171], v[54:57]
	v_mfma_f32_16x16x32_bf16 v[54:57], v[148:151], v[164:167], v[54:57]
	v_mfma_f32_16x16x32_bf16 v[58:61], v[148:151], v[172:175], v[58:61]
	v_mfma_f32_16x16x32_bf16 v[58:61], v[152:155], v[176:179], v[58:61]
	v_mfma_f32_16x16x32_bf16 v[98:101], v[152:155], v[226:229], v[98:101]
	v_mfma_f32_16x16x32_bf16 v[98:101], v[148:151], v[188:191], v[98:101]
	v_mfma_f32_16x16x32_bf16 v[50:53], v[156:159], v[188:191], v[50:53]
	v_mfma_f32_16x16x32_bf16 v[50:53], v[160:163], v[226:229], v[50:53]
	v_mfma_f32_16x16x32_bf16 v[38:41], v[160:163], v[168:171], v[38:41]
	v_mfma_f32_16x16x32_bf16 v[38:41], v[156:159], v[164:167], v[38:41]
	v_mfma_f32_16x16x32_bf16 v[30:33], v[156:159], v[172:175], v[30:33]
	v_mfma_f32_16x16x32_bf16 v[30:33], v[160:163], v[176:179], v[30:33]
	v_mfma_f32_16x16x32_bf16 v[22:25], v[160:163], v[184:187], v[22:25]
	v_mfma_f32_16x16x32_bf16 v[22:25], v[156:159], v[180:183], v[22:25]
	s_barrier
	s_add_i32 s34, s31, s45
	v_lshl_add_u64 v[192:193], s[84:85], 0, v[208:209]
	s_mov_b32 m0, s34
	ds_read_b128 v[164:167], v242 offset:16384
	ds_read_b128 v[168:171], v242 offset:17408
	ds_read_b128 v[172:175], v242 offset:18432
	ds_read_b128 v[176:179], v242 offset:19456
	ds_read_b128 v[180:183], v242 offset:20480
	ds_read_b128 v[184:187], v242 offset:21504
	ds_read_b128 v[188:191], v242 offset:22528
	ds_read_b128 v[226:229], v242 offset:23552
	global_load_lds_dwordx4 v[192:193], off
	s_add_i32 m0, s34, 0x2000
	s_add_u32 s34, s84, 0x100000
	v_lshl_add_u64 v[194:195], s[84:85], 0, v[212:213]
	s_addc_u32 s35, s85, 0
	s_add_i32 s50, s52, s45
	global_load_lds_dwordx4 v[194:195], off
	v_lshl_add_u64 v[230:231], s[34:35], 0, v[208:209]
	s_mov_b32 m0, s50
	v_lshl_add_u64 v[232:233], s[86:87], 0, v[210:211]
	global_load_lds_dwordx4 v[230:231], off
	v_lshl_add_u64 v[230:231], s[34:35], 0, v[212:213]
	s_add_i32 m0, s50, 0x2000
	s_nop 0
	global_load_lds_dwordx4 v[230:231], off
	v_lshl_add_u64 v[230:231], s[86:87], 0, v[206:207]
	s_mov_b32 m0, s28
	s_nop 0
	global_load_lds_dwordx4 v[230:231], off
	s_mov_b32 m0, s29
	s_nop 0
	global_load_lds_dwordx4 v[232:233], off
	s_waitcnt vmcnt(8)
	s_waitcnt lgkmcnt(0)
	s_barrier
; #define PG8_STAGE(bufoff, gbase, voff) do { _Pragma("unroll") for (int _i = 0; _i < 2; ++_i) \
;         __builtin_amdgcn_global_load_lds((const unsigned*)((const char*)(gbase) + (voff)[_i]), (PG8_LAS unsigned*)(lds + (bufoff) + ldsw + _i * 8192), 16, 0, 0); } while (0)
; #define PG8_LDA(dst, b, h) do { _Pragma("unroll") for (int m = 0; m < 4; ++m) _Pragma("unroll") for (int k = 0; k < 2; ++k) dst[m][k] = *(const PG8_LAS bf16x8*)(lds + PG8_SA(b, h) + aoff + m * 2048 + k * 1024); } while (0)
; #define PG8_LDB(dst, b, h) do { _Pragma("unroll") for (int n = 0; n < 2; ++n) _Pragma("unroll") for (int k = 0; k < 2; ++k) dst[n][k] = *(const PG8_LAS bf16x8*)(lds + PG8_SB(b, h) + boff + n * 2048 + k * 1024); } while (0)
; #define PG8_MMA(ai, bj, At, Bt) do { __builtin_amdgcn_s_setprio(1); _Pragma("unroll") for (int m = 0; m < 4; ++m) _Pragma("unroll") for (int n = 0; n < 2; ++n) _Pragma("unroll") for (int k = 0; k < 2; ++k) \
;         acc[ai][bj][m][n] = __builtin_amdgcn_mfma_f32_16x16x32_bf16(Bt[n][k], At[m][k], acc[ai][bj][m][n], 0, 0, 0); __builtin_amdgcn_s_setprio(0); } while (0)
; #define PG8_WAIT_V(n) asm volatile("s_waitcnt vmcnt(" #n ")" ::: "memory")
; #define PG8_WAIT_L(n) asm volatile("s_waitcnt lgkmcnt(" #n ")" ::: "memory")
; #define PG8_BAR __builtin_amdgcn_s_barrier()
; #define PG8_SCHED __builtin_amdgcn_sched_barrier(0)
; template <class Epi, class Sched, bool ALIGN_EPI = false, bool SP2 = false>
; __device__ __forceinline__ void gemm_phase(PG8_LAS unsigned char* lds, const Gemm g, const Sched& S, const Epi& E) {
;     ...
;             PG8_WAIT_V(8); PG8_WAIT_L(0); PG8_BAR; PG8_MMA(1, 0, At, B0); PG8_MMA(1, 1, At, B1); PG8_BAR; PG8_SCHED;
;             PG8_LDB(B0, 1, 0); PG8_LDB(B1, 1, 1); PG8_SCHED; PG8_LDA(At, 1, 0); PG8_STAGE(PG8_SA(0, 1), a2 + hstep, voffA);
;             PG8_WAIT_V(8); PG8_WAIT_L(0); PG8_BAR; PG8_MMA(0, 0, At, B0); PG8_MMA(0, 1, At, B1); PG8_BAR; PG8_SCHED;
	v_mfma_f32_16x16x32_bf16 v[78:81], v[132:135], v[164:167], v[78:81]
	v_mfma_f32_16x16x32_bf16 v[78:81], v[136:139], v[168:171], v[78:81]
	v_mfma_f32_16x16x32_bf16 v[66:69], v[136:139], v[176:179], v[66:69]
	v_mfma_f32_16x16x32_bf16 v[66:69], v[132:135], v[172:175], v[66:69]
	v_mfma_f32_16x16x32_bf16 v[70:73], v[132:135], v[180:183], v[70:73]
	v_mfma_f32_16x16x32_bf16 v[70:73], v[136:139], v[184:187], v[70:73]
	v_mfma_f32_16x16x32_bf16 v[74:77], v[136:139], v[226:229], v[74:77]
	v_mfma_f32_16x16x32_bf16 v[74:77], v[132:135], v[188:191], v[74:77]
	v_mfma_f32_16x16x32_bf16 v[10:13], v[140:143], v[188:191], v[10:13]
	v_mfma_f32_16x16x32_bf16 v[10:13], v[144:147], v[226:229], v[10:13]
	v_mfma_f32_16x16x32_bf16 v[14:17], v[144:147], v[168:171], v[14:17]
	v_mfma_f32_16x16x32_bf16 v[14:17], v[140:143], v[164:167], v[14:17]
	v_mfma_f32_16x16x32_bf16 v[94:97], v[140:143], v[172:175], v[94:97]
	v_mfma_f32_16x16x32_bf16 v[94:97], v[144:147], v[176:179], v[94:97]
	v_mfma_f32_16x16x32_bf16 v[90:93], v[144:147], v[184:187], v[90:93]
	v_mfma_f32_16x16x32_bf16 v[90:93], v[140:143], v[180:183], v[90:93]
	v_mfma_f32_16x16x32_bf16 v[86:89], v[148:151], v[180:183], v[86:89]
	v_mfma_f32_16x16x32_bf16 v[86:89], v[152:155], v[184:187], v[86:89]
	v_mfma_f32_16x16x32_bf16 v[42:45], v[152:155], v[168:171], v[42:45]
	v_mfma_f32_16x16x32_bf16 v[42:45], v[148:151], v[164:167], v[42:45]
	v_mfma_f32_16x16x32_bf16 v[34:37], v[148:151], v[172:175], v[34:37]
	v_mfma_f32_16x16x32_bf16 v[34:37], v[152:155], v[176:179], v[34:37]
	v_mfma_f32_16x16x32_bf16 v[82:85], v[152:155], v[226:229], v[82:85]
	v_mfma_f32_16x16x32_bf16 v[82:85], v[148:151], v[188:191], v[82:85]
	v_mfma_f32_16x16x32_bf16 v[18:21], v[156:159], v[188:191], v[18:21]
	v_mfma_f32_16x16x32_bf16 v[18:21], v[160:163], v[226:229], v[18:21]
	v_mfma_f32_16x16x32_bf16 v[2:5], v[160:163], v[168:171], v[2:5]
	v_mfma_f32_16x16x32_bf16 v[2:5], v[156:159], v[164:167], v[2:5]
	v_mfma_f32_16x16x32_bf16 v[6:9], v[156:159], v[172:175], v[6:9]
	v_mfma_f32_16x16x32_bf16 v[6:9], v[160:163], v[176:179], v[6:9]
	v_mfma_f32_16x16x32_bf16 v[26:29], v[160:163], v[184:187], v[26:29]
	v_mfma_f32_16x16x32_bf16 v[26:29], v[156:159], v[180:183], v[26:29]
	s_barrier
	s_add_i32 s50, 0, 0x18000
	s_add_i32 s56, 0, 0x1c000
	v_add_u32_e32 v144, s50, v201
	v_add_u32_e32 v160, s56, v201
	ds_read_b128 v[132:135], v144
	ds_read_b128 v[136:139], v144 offset:1024
	ds_read_b128 v[140:143], v144 offset:2048
	ds_read_b128 v[144:147], v144 offset:3072
	ds_read_b128 v[148:151], v160
	ds_read_b128 v[152:155], v160 offset:1024
	ds_read_b128 v[156:159], v160 offset:2048
	ds_read_b128 v[160:163], v160 offset:3072
	s_add_u32 s34, s86, 0x100000
	s_addc_u32 s35, s87, 0
	s_mov_b32 m0, s16
	v_lshl_add_u64 v[246:247], s[34:35], 0, v[206:207]
	ds_read_b128 v[164:167], v242 offset:32768
	ds_read_b128 v[168:171], v242 offset:33792
	ds_read_b128 v[172:175], v242 offset:34816
	ds_read_b128 v[176:179], v242 offset:35840
	ds_read_b128 v[180:183], v242 offset:36864
	ds_read_b128 v[184:187], v242 offset:37888
	ds_read_b128 v[188:191], v242 offset:38912
	ds_read_b128 v[226:229], v242 offset:39936
	global_load_lds_dwordx4 v[246:247], off
	v_lshl_add_u64 v[246:247], s[34:35], 0, v[210:211]
	s_mov_b32 m0, s17
	s_nop 0
	global_load_lds_dwordx4 v[246:247], off
	s_waitcnt vmcnt(8)
	s_waitcnt lgkmcnt(0)
	s_barrier
	v_mfma_f32_16x16x32_bf16 v[126:129], v[132:135], v[164:167], v[126:129]
	v_mfma_f32_16x16x32_bf16 v[126:129], v[136:139], v[168:171], v[126:129]
	v_mfma_f32_16x16x32_bf16 v[118:121], v[136:139], v[176:179], v[118:121]
	v_mfma_f32_16x16x32_bf16 v[118:121], v[132:135], v[172:175], v[118:121]
	v_mfma_f32_16x16x32_bf16 v[110:113], v[132:135], v[180:183], v[110:113]
	v_mfma_f32_16x16x32_bf16 v[110:113], v[136:139], v[184:187], v[110:113]
	v_mfma_f32_16x16x32_bf16 v[102:105], v[136:139], v[226:229], v[102:105]
	v_mfma_f32_16x16x32_bf16 v[102:105], v[132:135], v[188:191], v[102:105]
	v_mfma_f32_16x16x32_bf16 v[106:109], v[140:143], v[188:191], v[106:109]
	v_mfma_f32_16x16x32_bf16 v[106:109], v[144:147], v[226:229], v[106:109]
	v_mfma_f32_16x16x32_bf16 v[46:49], v[144:147], v[168:171], v[46:49]
	v_mfma_f32_16x16x32_bf16 v[46:49], v[140:143], v[164:167], v[46:49]
	v_mfma_f32_16x16x32_bf16 v[122:125], v[140:143], v[172:175], v[122:125]
	v_mfma_f32_16x16x32_bf16 v[122:125], v[144:147], v[176:179], v[122:125]
	v_mfma_f32_16x16x32_bf16 v[114:117], v[144:147], v[184:187], v[114:117]
	v_mfma_f32_16x16x32_bf16 v[114:117], v[140:143], v[180:183], v[114:117]
	v_mfma_f32_16x16x32_bf16 v[62:65], v[148:151], v[180:183], v[62:65]
	v_mfma_f32_16x16x32_bf16 v[62:65], v[152:155], v[184:187], v[62:65]
	v_mfma_f32_16x16x32_bf16 v[54:57], v[152:155], v[168:171], v[54:57]
	v_mfma_f32_16x16x32_bf16 v[54:57], v[148:151], v[164:167], v[54:57]
	v_mfma_f32_16x16x32_bf16 v[58:61], v[148:151], v[172:175], v[58:61]
	v_mfma_f32_16x16x32_bf16 v[58:61], v[152:155], v[176:179], v[58:61]
	v_mfma_f32_16x16x32_bf16 v[98:101], v[152:155], v[226:229], v[98:101]
	v_mfma_f32_16x16x32_bf16 v[98:101], v[148:151], v[188:191], v[98:101]
	v_mfma_f32_16x16x32_bf16 v[50:53], v[156:159], v[188:191], v[50:53]
	v_mfma_f32_16x16x32_bf16 v[50:53], v[160:163], v[226:229], v[50:53]
	v_mfma_f32_16x16x32_bf16 v[38:41], v[160:163], v[168:171], v[38:41]
	v_mfma_f32_16x16x32_bf16 v[38:41], v[156:159], v[164:167], v[38:41]
	v_mfma_f32_16x16x32_bf16 v[30:33], v[156:159], v[172:175], v[30:33]
	v_mfma_f32_16x16x32_bf16 v[30:33], v[160:163], v[176:179], v[30:33]
	v_mfma_f32_16x16x32_bf16 v[22:25], v[160:163], v[184:187], v[22:25]
	v_mfma_f32_16x16x32_bf16 v[22:25], v[156:159], v[180:183], v[22:25]
	s_barrier
; #define PG8_STAGE(bufoff, gbase, voff) do { _Pragma("unroll") for (int _i = 0; _i < 2; ++_i) \
;         __builtin_amdgcn_global_load_lds((const unsigned*)((const char*)(gbase) + (voff)[_i]), (PG8_LAS unsigned*)(lds + (bufoff) + ldsw + _i * 8192), 16, 0, 0); } while (0)
; #define PG8_LDA(dst, b, h) do { _Pragma("unroll") for (int m = 0; m < 4; ++m) _Pragma("unroll") for (int k = 0; k < 2; ++k) dst[m][k] = *(const PG8_LAS bf16x8*)(lds + PG8_SA(b, h) + aoff + m * 2048 + k * 1024); } while (0)
; #define PG8_MMA(ai, bj, At, Bt) do { __builtin_amdgcn_s_setprio(1); _Pragma("unroll") for (int m = 0; m < 4; ++m) _Pragma("unroll") for (int n = 0; n < 2; ++n) _Pragma("unroll") for (int k = 0; k < 2; ++k) \
;         acc[ai][bj][m][n] = __builtin_amdgcn_mfma_f32_16x16x32_bf16(Bt[n][k], At[m][k], acc[ai][bj][m][n], 0, 0, 0); __builtin_amdgcn_s_setprio(0); } while (0)
; #define PG8_WAIT_V(n) asm volatile("s_waitcnt vmcnt(" #n ")" ::: "memory")
; #define PG8_WAIT_L(n) asm volatile("s_waitcnt lgkmcnt(" #n ")" ::: "memory")
; #define PG8_BAR __builtin_amdgcn_s_barrier()
; #define PG8_SCHED __builtin_amdgcn_sched_barrier(0)
; template <class Epi, class Sched, bool ALIGN_EPI = false, bool SP2 = false>
; __device__ __forceinline__ void gemm_phase(PG8_LAS unsigned char* lds, const Gemm g, const Sched& S, const Epi& E) {
;     ...
;         for (int t = 0; t < nt; t += 2) {
;     ...
;             PG8_LDA(At, 1, 1); PG8_STAGE(PG8_SB(1, 0), b3, voffB); PG8_STAGE(PG8_SB(1, 1), b3 + hstep, voffB); PG8_STAGE(PG8_SA(1, 0), a3, voffA);
;             PG8_WAIT_V(8); PG8_WAIT_L(0); PG8_BAR; PG8_MMA(1, 0, At, B0); PG8_MMA(1, 1, At, B1); PG8_BAR; PG8_SCHED;
	s_add_i32 s34, s50, s45
	v_lshl_add_u64 v[192:193], v[192:193], 0, s[54:55]
	s_mov_b32 m0, s34
	ds_read_b128 v[164:167], v242 offset:49152
	ds_read_b128 v[168:171], v242 offset:50176
	ds_read_b128 v[172:175], v242 offset:51200
	ds_read_b128 v[176:179], v242 offset:52224
	ds_read_b128 v[180:183], v242 offset:53248
	ds_read_b128 v[184:187], v242 offset:54272
	ds_read_b128 v[188:191], v242 offset:55296
	ds_read_b128 v[226:229], v242 offset:56320
	global_load_lds_dwordx4 v[192:193], off
	s_add_i32 m0, s34, 0x2000
	s_add_u32 s34, s84, 0x100080
	v_lshl_add_u64 v[192:193], v[194:195], 0, s[54:55]
	s_addc_u32 s35, s85, 0
	s_add_i32 s50, s56, s45
	global_load_lds_dwordx4 v[192:193], off
	v_lshl_add_u64 v[192:193], s[34:35], 0, v[208:209]
	s_mov_b32 m0, s50
	s_nop 0
	global_load_lds_dwordx4 v[192:193], off
	v_lshl_add_u64 v[192:193], s[34:35], 0, v[212:213]
	s_add_i32 m0, s50, 0x2000
	s_nop 0
	global_load_lds_dwordx4 v[192:193], off
	v_lshl_add_u64 v[192:193], v[230:231], 0, s[54:55]
	s_mov_b32 m0, s39
	s_nop 0
	global_load_lds_dwordx4 v[192:193], off
	v_lshl_add_u64 v[192:193], v[232:233], 0, s[54:55]
	s_mov_b32 m0, s46
	s_nop 0
	global_load_lds_dwordx4 v[192:193], off
	s_waitcnt vmcnt(8)
	s_waitcnt lgkmcnt(0)
	s_barrier
	v_mfma_f32_16x16x32_bf16 v[78:81], v[132:135], v[164:167], v[78:81]
	v_mfma_f32_16x16x32_bf16 v[78:81], v[136:139], v[168:171], v[78:81]
	v_mfma_f32_16x16x32_bf16 v[66:69], v[136:139], v[176:179], v[66:69]
	v_mfma_f32_16x16x32_bf16 v[66:69], v[132:135], v[172:175], v[66:69]
	v_mfma_f32_16x16x32_bf16 v[70:73], v[132:135], v[180:183], v[70:73]
	v_mfma_f32_16x16x32_bf16 v[70:73], v[136:139], v[184:187], v[70:73]
	v_mfma_f32_16x16x32_bf16 v[74:77], v[136:139], v[226:229], v[74:77]
	v_mfma_f32_16x16x32_bf16 v[74:77], v[132:135], v[188:191], v[74:77]
	v_mfma_f32_16x16x32_bf16 v[10:13], v[140:143], v[188:191], v[10:13]
	v_mfma_f32_16x16x32_bf16 v[10:13], v[144:147], v[226:229], v[10:13]
	v_mfma_f32_16x16x32_bf16 v[14:17], v[144:147], v[168:171], v[14:17]
	v_mfma_f32_16x16x32_bf16 v[14:17], v[140:143], v[164:167], v[14:17]
	v_mfma_f32_16x16x32_bf16 v[94:97], v[140:143], v[172:175], v[94:97]
	v_mfma_f32_16x16x32_bf16 v[94:97], v[144:147], v[176:179], v[94:97]
	v_mfma_f32_16x16x32_bf16 v[90:93], v[144:147], v[184:187], v[90:93]
	v_mfma_f32_16x16x32_bf16 v[90:93], v[140:143], v[180:183], v[90:93]
	v_mfma_f32_16x16x32_bf16 v[86:89], v[148:151], v[180:183], v[86:89]
	v_mfma_f32_16x16x32_bf16 v[86:89], v[152:155], v[184:187], v[86:89]
	v_mfma_f32_16x16x32_bf16 v[42:45], v[152:155], v[168:171], v[42:45]
	v_mfma_f32_16x16x32_bf16 v[42:45], v[148:151], v[164:167], v[42:45]
	v_mfma_f32_16x16x32_bf16 v[34:37], v[148:151], v[172:175], v[34:37]
	v_mfma_f32_16x16x32_bf16 v[34:37], v[152:155], v[176:179], v[34:37]
	v_mfma_f32_16x16x32_bf16 v[82:85], v[152:155], v[226:229], v[82:85]
	v_mfma_f32_16x16x32_bf16 v[82:85], v[148:151], v[188:191], v[82:85]
	v_mfma_f32_16x16x32_bf16 v[18:21], v[156:159], v[188:191], v[18:21]
	v_mfma_f32_16x16x32_bf16 v[18:21], v[160:163], v[226:229], v[18:21]
	v_mfma_f32_16x16x32_bf16 v[2:5], v[160:163], v[168:171], v[2:5]
	v_mfma_f32_16x16x32_bf16 v[2:5], v[156:159], v[164:167], v[2:5]
	v_mfma_f32_16x16x32_bf16 v[6:9], v[156:159], v[172:175], v[6:9]
	v_mfma_f32_16x16x32_bf16 v[6:9], v[160:163], v[176:179], v[6:9]
	v_mfma_f32_16x16x32_bf16 v[26:29], v[160:163], v[184:187], v[26:29]
	v_mfma_f32_16x16x32_bf16 v[26:29], v[156:159], v[180:183], v[26:29]
	s_barrier
	s_add_i32 s89, s89, 2
	s_add_u32 s82, s82, 0x100
	s_addc_u32 s83, s83, 0
	s_add_u32 s79, s79, 0x100
	s_addc_u32 s88, s88, 0
	s_cmp_gt_u32 s89, 61
	s_cbranch_scc1 .LBB0_1490

; #define PG8_STAGE(bufoff, gbase, voff) do { _Pragma("unroll") for (int _i = 0; _i < 2; ++_i) \
;         __builtin_amdgcn_global_load_lds((const unsigned*)((const char*)(gbase) + (voff)[_i]), (PG8_LAS unsigned*)(lds + (bufoff) + ldsw + _i * 8192), 16, 0, 0); } while (0)
; #define PG8_LDA(dst, b, h) do { _Pragma("unroll") for (int m = 0; m < 4; ++m) _Pragma("unroll") for (int k = 0; k < 2; ++k) dst[m][k] = *(const PG8_LAS bf16x8*)(lds + PG8_SA(b, h) + aoff + m * 2048 + k * 1024); } while (0)
; #define PG8_LDB(dst, b, h) do { _Pragma("unroll") for (int n = 0; n < 2; ++n) _Pragma("unroll") for (int k = 0; k < 2; ++k) dst[n][k] = *(const PG8_LAS bf16x8*)(lds + PG8_SB(b, h) + boff + n * 2048 + k * 1024); } while (0)
; #define PG8_MMA(ai, bj, At, Bt) do { __builtin_amdgcn_s_setprio(1); _Pragma("unroll") for (int m = 0; m < 4; ++m) _Pragma("unroll") for (int n = 0; n < 2; ++n) _Pragma("unroll") for (int k = 0; k < 2; ++k) \
;         acc[ai][bj][m][n] = __builtin_amdgcn_mfma_f32_16x16x32_bf16(Bt[n][k], At[m][k], acc[ai][bj][m][n], 0, 0, 0); __builtin_amdgcn_s_setprio(0); } while (0)
; #define PG8_WAIT_V(n) asm volatile("s_waitcnt vmcnt(" #n ")" ::: "memory")
; #define PG8_BAR __builtin_amdgcn_s_barrier()
; template <class Epi, class Sched, bool ALIGN_EPI = false, bool SP2 = false>
; __device__ __forceinline__ void gemm_phase(PG8_LAS unsigned char* lds, const Gemm g, const Sched& S, const Epi& E) {
;     ...
;         for (int t = 0; t < nt; t += 2) {
;             const bool last = (t == nt - 2);
;             const char* a1 = cA + (size_t)(t + 1) * kstep;
;             const char* a2 = last ? nA : cA + (size_t)(t + 2) * kstep; const char* b2 = last ? nB : cB + (size_t)(t + 2) * kstep;
;             const char* a3 = a2 + kstep; const char* b3 = b2 + kstep;
;             if (last && has_next) S.a_ready(nxt);
;             if constexpr (SP2) {
;             PG8_LDB(B0, 0, 0); PG8_LDB(B1, 0, 1); PG8_SCHED; PG8_LDA(At, 0, 0); PG8_STAGE(PG8_SA(1, 1), a1 + hstep, voffA);
;             PG8_WAIT_V(8); PG8_WAIT_L(0); PG8_BAR; PG8_MMA(0, 0, At, B0); PG8_MMA(0, 1, At, B1); PG8_BAR; PG8_SCHED;
;             PG8_LDA(At, 0, 1); PG8_STAGE(PG8_SB(0, 0), b2, voffB); PG8_STAGE(PG8_SB(0, 1), b2 + hstep, voffB); PG8_STAGE(PG8_SA(0, 0), a2, voffA);
;             PG8_WAIT_V(8); PG8_WAIT_L(0); PG8_BAR; PG8_MMA(1, 0, At, B0); PG8_MMA(1, 1, At, B1); PG8_BAR; PG8_SCHED;
.LBB0_1731:
	ds_read_b128 v[170:173], v166
	ds_read_b128 v[174:177], v166 offset:1024
	ds_read_b128 v[178:181], v166 offset:2048
	ds_read_b128 v[182:185], v166 offset:3072
	ds_read_b128 v[186:189], v167
	ds_read_b128 v[190:193], v167 offset:1024
	ds_read_b128 v[196:199], v167 offset:2048
	ds_read_b128 v[202:205], v167 offset:3072
	s_add_u32 s48, s40, 0x100
	s_addc_u32 s49, s41, 0
	s_cmpk_eq_i32 s56, 0xa8
	s_cselect_b32 s53, s7, s49
	s_cselect_b32 s52, s6, s48
	s_cselect_b32 s51, s39, s55
	s_cselect_b32 s50, s38, s54
	v_lshl_add_u64 v[146:147], s[40:41], 0, v[138:139]
	s_add_i32 m0, s16, 0xc000
	ds_read_b128 v[206:209], v168
	ds_read_b128 v[210:213], v168 offset:1024
	ds_read_b128 v[214:217], v168 offset:2048
	ds_read_b128 v[218:221], v168 offset:3072
	ds_read_b128 v[222:225], v168 offset:4096
	ds_read_b128 v[226:229], v168 offset:5120
	ds_read_b128 v[230:233], v168 offset:6144
	ds_read_b128 v[234:237], v168 offset:7168
	global_load_lds_dwordx4 v[146:147], off
	v_lshl_add_u64 v[146:147], s[40:41], 0, v[140:141]
	s_add_i32 m0, s16, 0xe000
	s_nop 0
	global_load_lds_dwordx4 v[146:147], off
	s_waitcnt vmcnt(8)
	s_waitcnt lgkmcnt(0)
	s_barrier
	v_mfma_f32_16x16x32_bf16 v[126:129], v[170:173], v[206:209], v[126:129]
	v_mfma_f32_16x16x32_bf16 v[126:129], v[174:177], v[210:213], v[126:129]
	v_mfma_f32_16x16x32_bf16 v[110:113], v[174:177], v[218:221], v[110:113]
	v_mfma_f32_16x16x32_bf16 v[110:113], v[170:173], v[214:217], v[110:113]
	v_mfma_f32_16x16x32_bf16 v[94:97], v[170:173], v[222:225], v[94:97]
	v_mfma_f32_16x16x32_bf16 v[94:97], v[174:177], v[226:229], v[94:97]
	v_mfma_f32_16x16x32_bf16 v[78:81], v[174:177], v[234:237], v[78:81]
	v_mfma_f32_16x16x32_bf16 v[78:81], v[170:173], v[230:233], v[78:81]
	v_mfma_f32_16x16x32_bf16 v[74:77], v[178:181], v[230:233], v[74:77]
	v_mfma_f32_16x16x32_bf16 v[74:77], v[182:185], v[234:237], v[74:77]
	v_mfma_f32_16x16x32_bf16 v[122:125], v[182:185], v[210:213], v[122:125]
	v_mfma_f32_16x16x32_bf16 v[122:125], v[178:181], v[206:209], v[122:125]
	v_mfma_f32_16x16x32_bf16 v[106:109], v[178:181], v[214:217], v[106:109]
	v_mfma_f32_16x16x32_bf16 v[106:109], v[182:185], v[218:221], v[106:109]
	v_mfma_f32_16x16x32_bf16 v[90:93], v[182:185], v[226:229], v[90:93]
	v_mfma_f32_16x16x32_bf16 v[90:93], v[178:181], v[222:225], v[90:93]
	v_mfma_f32_16x16x32_bf16 v[86:89], v[186:189], v[222:225], v[86:89]
	v_mfma_f32_16x16x32_bf16 v[86:89], v[190:193], v[226:229], v[86:89]
	v_mfma_f32_16x16x32_bf16 v[118:121], v[190:193], v[210:213], v[118:121]
	v_mfma_f32_16x16x32_bf16 v[118:121], v[186:189], v[206:209], v[118:121]
	v_mfma_f32_16x16x32_bf16 v[102:105], v[186:189], v[214:217], v[102:105]
	v_mfma_f32_16x16x32_bf16 v[102:105], v[190:193], v[218:221], v[102:105]
	v_mfma_f32_16x16x32_bf16 v[70:73], v[190:193], v[234:237], v[70:73]
	v_mfma_f32_16x16x32_bf16 v[70:73], v[186:189], v[230:233], v[70:73]
	v_mfma_f32_16x16x32_bf16 v[66:69], v[196:199], v[230:233], v[66:69]
	v_mfma_f32_16x16x32_bf16 v[66:69], v[202:205], v[234:237], v[66:69]
	v_mfma_f32_16x16x32_bf16 v[114:117], v[202:205], v[210:213], v[114:117]
	v_mfma_f32_16x16x32_bf16 v[114:117], v[196:199], v[206:209], v[114:117]
	v_mfma_f32_16x16x32_bf16 v[98:101], v[196:199], v[214:217], v[98:101]
	v_mfma_f32_16x16x32_bf16 v[98:101], v[202:205], v[218:221], v[98:101]
	v_mfma_f32_16x16x32_bf16 v[82:85], v[202:205], v[226:229], v[82:85]
	v_mfma_f32_16x16x32_bf16 v[82:85], v[196:199], v[222:225], v[82:85]
	s_barrier
	s_add_i32 s40, s31, s3
	v_lshl_add_u64 v[146:147], s[50:51], 0, v[132:133]
	s_mov_b32 m0, s40
	ds_read_b128 v[206:209], v168 offset:16384
	ds_read_b128 v[210:213], v168 offset:17408
	ds_read_b128 v[214:217], v168 offset:18432
	ds_read_b128 v[218:221], v168 offset:19456
	ds_read_b128 v[222:225], v168 offset:20480
	ds_read_b128 v[226:229], v168 offset:21504
	ds_read_b128 v[230:233], v168 offset:22528
	ds_read_b128 v[234:237], v168 offset:23552
	global_load_lds_dwordx4 v[146:147], off
	s_add_i32 m0, s40, 0x2000
	s_add_u32 s40, s50, 0x2b0000
	v_lshl_add_u64 v[194:195], s[50:51], 0, v[136:137]
	s_addc_u32 s41, s51, 0
	s_add_i32 s57, s35, s3
	global_load_lds_dwordx4 v[194:195], off
	v_lshl_add_u64 v[238:239], s[40:41], 0, v[132:133]
	s_mov_b32 m0, s57
	v_lshl_add_u64 v[240:241], s[52:53], 0, v[134:135]
	global_load_lds_dwordx4 v[238:239], off
	v_lshl_add_u64 v[238:239], s[40:41], 0, v[136:137]
	s_add_i32 m0, s57, 0x2000
	s_nop 0
	global_load_lds_dwordx4 v[238:239], off
	v_lshl_add_u64 v[238:239], s[52:53], 0, v[130:131]
	s_mov_b32 m0, s16
	s_nop 0
	global_load_lds_dwordx4 v[238:239], off
	s_mov_b32 m0, s17
	s_nop 0
	global_load_lds_dwordx4 v[240:241], off
	s_waitcnt vmcnt(8)
	s_waitcnt lgkmcnt(0)
	s_barrier
; #define PG8_STAGE(bufoff, gbase, voff) do { _Pragma("unroll") for (int _i = 0; _i < 2; ++_i) \
;         __builtin_amdgcn_global_load_lds((const unsigned*)((const char*)(gbase) + (voff)[_i]), (PG8_LAS unsigned*)(lds + (bufoff) + ldsw + _i * 8192), 16, 0, 0); } while (0)
; #define PG8_LDA(dst, b, h) do { _Pragma("unroll") for (int m = 0; m < 4; ++m) _Pragma("unroll") for (int k = 0; k < 2; ++k) dst[m][k] = *(const PG8_LAS bf16x8*)(lds + PG8_SA(b, h) + aoff + m * 2048 + k * 1024); } while (0)
; #define PG8_LDB(dst, b, h) do { _Pragma("unroll") for (int n = 0; n < 2; ++n) _Pragma("unroll") for (int k = 0; k < 2; ++k) dst[n][k] = *(const PG8_LAS bf16x8*)(lds + PG8_SB(b, h) + boff + n * 2048 + k * 1024); } while (0)
; #define PG8_MMA(ai, bj, At, Bt) do { __builtin_amdgcn_s_setprio(1); _Pragma("unroll") for (int m = 0; m < 4; ++m) _Pragma("unroll") for (int n = 0; n < 2; ++n) _Pragma("unroll") for (int k = 0; k < 2; ++k) \
;         acc[ai][bj][m][n] = __builtin_amdgcn_mfma_f32_16x16x32_bf16(Bt[n][k], At[m][k], acc[ai][bj][m][n], 0, 0, 0); __builtin_amdgcn_s_setprio(0); } while (0)
; #define PG8_WAIT_V(n) asm volatile("s_waitcnt vmcnt(" #n ")" ::: "memory")
; #define PG8_WAIT_L(n) asm volatile("s_waitcnt lgkmcnt(" #n ")" ::: "memory")
; #define PG8_BAR __builtin_amdgcn_s_barrier()
; #define PG8_SCHED __builtin_amdgcn_sched_barrier(0)
; template <class Epi, class Sched, bool ALIGN_EPI = false, bool SP2 = false>
; __device__ __forceinline__ void gemm_phase(PG8_LAS unsigned char* lds, const Gemm g, const Sched& S, const Epi& E) {
;     ...
;             PG8_WAIT_V(8); PG8_WAIT_L(0); PG8_BAR; PG8_MMA(1, 0, At, B0); PG8_MMA(1, 1, At, B1); PG8_BAR; PG8_SCHED;
;             PG8_LDB(B0, 1, 0); PG8_LDB(B1, 1, 1); PG8_SCHED; PG8_LDA(At, 1, 0); PG8_STAGE(PG8_SA(0, 1), a2 + hstep, voffA);
;             PG8_WAIT_V(8); PG8_WAIT_L(0); PG8_BAR; PG8_MMA(0, 0, At, B0); PG8_MMA(0, 1, At, B1); PG8_BAR; PG8_SCHED;
	v_mfma_f32_16x16x32_bf16 v[62:65], v[170:173], v[206:209], v[62:65]
	v_mfma_f32_16x16x32_bf16 v[62:65], v[174:177], v[210:213], v[62:65]
	v_mfma_f32_16x16x32_bf16 v[46:49], v[174:177], v[218:221], v[46:49]
	v_mfma_f32_16x16x32_bf16 v[46:49], v[170:173], v[214:217], v[46:49]
	v_mfma_f32_16x16x32_bf16 v[30:33], v[170:173], v[222:225], v[30:33]
	v_mfma_f32_16x16x32_bf16 v[30:33], v[174:177], v[226:229], v[30:33]
	v_mfma_f32_16x16x32_bf16 v[14:17], v[174:177], v[234:237], v[14:17]
	v_mfma_f32_16x16x32_bf16 v[14:17], v[170:173], v[230:233], v[14:17]
	v_mfma_f32_16x16x32_bf16 v[10:13], v[178:181], v[230:233], v[10:13]
	v_mfma_f32_16x16x32_bf16 v[10:13], v[182:185], v[234:237], v[10:13]
	v_mfma_f32_16x16x32_bf16 v[58:61], v[182:185], v[210:213], v[58:61]
	v_mfma_f32_16x16x32_bf16 v[58:61], v[178:181], v[206:209], v[58:61]
	v_mfma_f32_16x16x32_bf16 v[42:45], v[178:181], v[214:217], v[42:45]
	v_mfma_f32_16x16x32_bf16 v[42:45], v[182:185], v[218:221], v[42:45]
	v_mfma_f32_16x16x32_bf16 v[26:29], v[182:185], v[226:229], v[26:29]
	v_mfma_f32_16x16x32_bf16 v[26:29], v[178:181], v[222:225], v[26:29]
	v_mfma_f32_16x16x32_bf16 v[22:25], v[186:189], v[222:225], v[22:25]
	v_mfma_f32_16x16x32_bf16 v[22:25], v[190:193], v[226:229], v[22:25]
	v_mfma_f32_16x16x32_bf16 v[54:57], v[190:193], v[210:213], v[54:57]
	v_mfma_f32_16x16x32_bf16 v[54:57], v[186:189], v[206:209], v[54:57]
	v_mfma_f32_16x16x32_bf16 v[38:41], v[186:189], v[214:217], v[38:41]
	v_mfma_f32_16x16x32_bf16 v[38:41], v[190:193], v[218:221], v[38:41]
	v_mfma_f32_16x16x32_bf16 v[6:9], v[190:193], v[234:237], v[6:9]
	v_mfma_f32_16x16x32_bf16 v[6:9], v[186:189], v[230:233], v[6:9]
	v_mfma_f32_16x16x32_bf16 v[2:5], v[196:199], v[230:233], v[2:5]
	v_mfma_f32_16x16x32_bf16 v[2:5], v[202:205], v[234:237], v[2:5]
	v_mfma_f32_16x16x32_bf16 v[50:53], v[202:205], v[210:213], v[50:53]
	v_mfma_f32_16x16x32_bf16 v[50:53], v[196:199], v[206:209], v[50:53]
	v_mfma_f32_16x16x32_bf16 v[34:37], v[196:199], v[214:217], v[34:37]
	v_mfma_f32_16x16x32_bf16 v[34:37], v[202:205], v[218:221], v[34:37]
	v_mfma_f32_16x16x32_bf16 v[18:21], v[202:205], v[226:229], v[18:21]
	v_mfma_f32_16x16x32_bf16 v[18:21], v[196:199], v[222:225], v[18:21]
	s_barrier
	s_add_i32 s57, 0, 0x18000
	v_add_u32_e32 v169, s57, v148
	s_add_i32 s58, 0, 0x1c000
	ds_read_b128 v[170:173], v169
	ds_read_b128 v[174:177], v169 offset:1024
	ds_read_b128 v[178:181], v169 offset:2048
	ds_read_b128 v[182:185], v169 offset:3072
	v_add_u32_e32 v169, s58, v148
	ds_read_b128 v[186:189], v169
	ds_read_b128 v[190:193], v169 offset:1024
	ds_read_b128 v[196:199], v169 offset:2048
	ds_read_b128 v[202:205], v169 offset:3072
	s_add_u32 s40, s52, 0x2b0000
	s_addc_u32 s41, s53, 0
	s_mov_b32 m0, s25
	v_lshl_add_u64 v[242:243], s[40:41], 0, v[130:131]
	ds_read_b128 v[206:209], v168 offset:32768
	ds_read_b128 v[210:213], v168 offset:33792
	ds_read_b128 v[214:217], v168 offset:34816
	ds_read_b128 v[218:221], v168 offset:35840
	ds_read_b128 v[222:225], v168 offset:36864
	ds_read_b128 v[226:229], v168 offset:37888
	ds_read_b128 v[230:233], v168 offset:38912
	ds_read_b128 v[234:237], v168 offset:39936
	global_load_lds_dwordx4 v[242:243], off
	v_lshl_add_u64 v[242:243], s[40:41], 0, v[134:135]
	s_mov_b32 m0, s26
	s_nop 0
	global_load_lds_dwordx4 v[242:243], off
	s_waitcnt vmcnt(8)
	s_waitcnt lgkmcnt(0)
	s_barrier
	v_mfma_f32_16x16x32_bf16 v[126:129], v[170:173], v[206:209], v[126:129]
	v_mfma_f32_16x16x32_bf16 v[126:129], v[174:177], v[210:213], v[126:129]
	v_mfma_f32_16x16x32_bf16 v[110:113], v[174:177], v[218:221], v[110:113]
	v_mfma_f32_16x16x32_bf16 v[110:113], v[170:173], v[214:217], v[110:113]
	v_mfma_f32_16x16x32_bf16 v[94:97], v[170:173], v[222:225], v[94:97]
	v_mfma_f32_16x16x32_bf16 v[94:97], v[174:177], v[226:229], v[94:97]
	v_mfma_f32_16x16x32_bf16 v[78:81], v[174:177], v[234:237], v[78:81]
	v_mfma_f32_16x16x32_bf16 v[78:81], v[170:173], v[230:233], v[78:81]
	v_mfma_f32_16x16x32_bf16 v[74:77], v[178:181], v[230:233], v[74:77]
	v_mfma_f32_16x16x32_bf16 v[74:77], v[182:185], v[234:237], v[74:77]
	v_mfma_f32_16x16x32_bf16 v[122:125], v[182:185], v[210:213], v[122:125]
	v_mfma_f32_16x16x32_bf16 v[122:125], v[178:181], v[206:209], v[122:125]
	v_mfma_f32_16x16x32_bf16 v[106:109], v[178:181], v[214:217], v[106:109]
	v_mfma_f32_16x16x32_bf16 v[106:109], v[182:185], v[218:221], v[106:109]
	v_mfma_f32_16x16x32_bf16 v[90:93], v[182:185], v[226:229], v[90:93]
	v_mfma_f32_16x16x32_bf16 v[90:93], v[178:181], v[222:225], v[90:93]
	v_mfma_f32_16x16x32_bf16 v[86:89], v[186:189], v[222:225], v[86:89]
	v_mfma_f32_16x16x32_bf16 v[86:89], v[190:193], v[226:229], v[86:89]
	v_mfma_f32_16x16x32_bf16 v[118:121], v[190:193], v[210:213], v[118:121]
	v_mfma_f32_16x16x32_bf16 v[118:121], v[186:189], v[206:209], v[118:121]
	v_mfma_f32_16x16x32_bf16 v[102:105], v[186:189], v[214:217], v[102:105]
	v_mfma_f32_16x16x32_bf16 v[102:105], v[190:193], v[218:221], v[102:105]
	v_mfma_f32_16x16x32_bf16 v[70:73], v[190:193], v[234:237], v[70:73]
	v_mfma_f32_16x16x32_bf16 v[70:73], v[186:189], v[230:233], v[70:73]
	v_mfma_f32_16x16x32_bf16 v[66:69], v[196:199], v[230:233], v[66:69]
	v_mfma_f32_16x16x32_bf16 v[66:69], v[202:205], v[234:237], v[66:69]
	v_mfma_f32_16x16x32_bf16 v[114:117], v[202:205], v[210:213], v[114:117]
	v_mfma_f32_16x16x32_bf16 v[114:117], v[196:199], v[206:209], v[114:117]
	v_mfma_f32_16x16x32_bf16 v[98:101], v[196:199], v[214:217], v[98:101]
	v_mfma_f32_16x16x32_bf16 v[98:101], v[202:205], v[218:221], v[98:101]
	v_mfma_f32_16x16x32_bf16 v[82:85], v[202:205], v[226:229], v[82:85]
	v_mfma_f32_16x16x32_bf16 v[82:85], v[196:199], v[222:225], v[82:85]
	s_barrier
; #define PG8_STAGE(bufoff, gbase, voff) do { _Pragma("unroll") for (int _i = 0; _i < 2; ++_i) \
;         __builtin_amdgcn_global_load_lds((const unsigned*)((const char*)(gbase) + (voff)[_i]), (PG8_LAS unsigned*)(lds + (bufoff) + ldsw + _i * 8192), 16, 0, 0); } while (0)
; #define PG8_LDA(dst, b, h) do { _Pragma("unroll") for (int m = 0; m < 4; ++m) _Pragma("unroll") for (int k = 0; k < 2; ++k) dst[m][k] = *(const PG8_LAS bf16x8*)(lds + PG8_SA(b, h) + aoff + m * 2048 + k * 1024); } while (0)
; #define PG8_MMA(ai, bj, At, Bt) do { __builtin_amdgcn_s_setprio(1); _Pragma("unroll") for (int m = 0; m < 4; ++m) _Pragma("unroll") for (int n = 0; n < 2; ++n) _Pragma("unroll") for (int k = 0; k < 2; ++k) \
;         acc[ai][bj][m][n] = __builtin_amdgcn_mfma_f32_16x16x32_bf16(Bt[n][k], At[m][k], acc[ai][bj][m][n], 0, 0, 0); __builtin_amdgcn_s_setprio(0); } while (0)
; #define PG8_WAIT_V(n) asm volatile("s_waitcnt vmcnt(" #n ")" ::: "memory")
; #define PG8_WAIT_L(n) asm volatile("s_waitcnt lgkmcnt(" #n ")" ::: "memory")
; #define PG8_BAR __builtin_amdgcn_s_barrier()
; #define PG8_SCHED __builtin_amdgcn_sched_barrier(0)
; template <class Epi, class Sched, bool ALIGN_EPI = false, bool SP2 = false>
; __device__ __forceinline__ void gemm_phase(PG8_LAS unsigned char* lds, const Gemm g, const Sched& S, const Epi& E) {
;     ...
;             PG8_LDA(At, 1, 1); PG8_STAGE(PG8_SB(1, 0), b3, voffB); PG8_STAGE(PG8_SB(1, 1), b3 + hstep, voffB); PG8_STAGE(PG8_SA(1, 0), a3, voffA);
;             PG8_WAIT_V(8); PG8_WAIT_L(0); PG8_BAR; PG8_MMA(1, 0, At, B0); PG8_MMA(1, 1, At, B1); PG8_BAR; PG8_SCHED;
;     ...
;         if constexpr (ALIGN_EPI) { if (wr == 0) PG8_BAR; }
	s_add_i32 s40, s57, s3
	v_lshl_add_u64 v[146:147], v[146:147], 0, s[10:11]
	s_mov_b32 m0, s40
	ds_read_b128 v[206:209], v168 offset:49152
	ds_read_b128 v[210:213], v168 offset:50176
	ds_read_b128 v[214:217], v168 offset:51200
	ds_read_b128 v[218:221], v168 offset:52224
	ds_read_b128 v[222:225], v168 offset:53248
	ds_read_b128 v[226:229], v168 offset:54272
	ds_read_b128 v[230:233], v168 offset:55296
	ds_read_b128 v[234:237], v168 offset:56320
	global_load_lds_dwordx4 v[146:147], off
	s_add_i32 m0, s40, 0x2000
	s_add_u32 s40, s50, 0x2b0080
	v_lshl_add_u64 v[146:147], v[194:195], 0, s[10:11]
	s_addc_u32 s41, s51, 0
	s_add_i32 s50, s58, s3
	global_load_lds_dwordx4 v[146:147], off
	v_lshl_add_u64 v[146:147], s[40:41], 0, v[132:133]
	s_mov_b32 m0, s50
	s_nop 0
	global_load_lds_dwordx4 v[146:147], off
	v_lshl_add_u64 v[146:147], s[40:41], 0, v[136:137]
	s_add_i32 m0, s50, 0x2000
	s_nop 0
	global_load_lds_dwordx4 v[146:147], off
	v_lshl_add_u64 v[146:147], v[238:239], 0, s[10:11]
	s_mov_b32 m0, s28
	s_nop 0
	global_load_lds_dwordx4 v[146:147], off
	v_lshl_add_u64 v[146:147], v[240:241], 0, s[10:11]
	s_mov_b32 m0, s29
	s_nop 0
	global_load_lds_dwordx4 v[146:147], off
	s_waitcnt vmcnt(8)
	s_waitcnt lgkmcnt(0)
	s_barrier
	v_mfma_f32_16x16x32_bf16 v[62:65], v[170:173], v[206:209], v[62:65]
	v_mfma_f32_16x16x32_bf16 v[62:65], v[174:177], v[210:213], v[62:65]
	v_mfma_f32_16x16x32_bf16 v[46:49], v[174:177], v[218:221], v[46:49]
	v_mfma_f32_16x16x32_bf16 v[46:49], v[170:173], v[214:217], v[46:49]
	v_mfma_f32_16x16x32_bf16 v[30:33], v[170:173], v[222:225], v[30:33]
	v_mfma_f32_16x16x32_bf16 v[30:33], v[174:177], v[226:229], v[30:33]
	v_mfma_f32_16x16x32_bf16 v[14:17], v[174:177], v[234:237], v[14:17]
	v_mfma_f32_16x16x32_bf16 v[14:17], v[170:173], v[230:233], v[14:17]
	v_mfma_f32_16x16x32_bf16 v[10:13], v[178:181], v[230:233], v[10:13]
	v_mfma_f32_16x16x32_bf16 v[10:13], v[182:185], v[234:237], v[10:13]
	v_mfma_f32_16x16x32_bf16 v[58:61], v[182:185], v[210:213], v[58:61]
	v_mfma_f32_16x16x32_bf16 v[58:61], v[178:181], v[206:209], v[58:61]
	v_mfma_f32_16x16x32_bf16 v[42:45], v[178:181], v[214:217], v[42:45]
	v_mfma_f32_16x16x32_bf16 v[42:45], v[182:185], v[218:221], v[42:45]
	v_mfma_f32_16x16x32_bf16 v[26:29], v[182:185], v[226:229], v[26:29]
	v_mfma_f32_16x16x32_bf16 v[26:29], v[178:181], v[222:225], v[26:29]
	v_mfma_f32_16x16x32_bf16 v[22:25], v[186:189], v[222:225], v[22:25]
	v_mfma_f32_16x16x32_bf16 v[22:25], v[190:193], v[226:229], v[22:25]
	v_mfma_f32_16x16x32_bf16 v[54:57], v[190:193], v[210:213], v[54:57]
	v_mfma_f32_16x16x32_bf16 v[54:57], v[186:189], v[206:209], v[54:57]
	v_mfma_f32_16x16x32_bf16 v[38:41], v[186:189], v[214:217], v[38:41]
	v_mfma_f32_16x16x32_bf16 v[38:41], v[190:193], v[218:221], v[38:41]
	v_mfma_f32_16x16x32_bf16 v[6:9], v[190:193], v[234:237], v[6:9]
	v_mfma_f32_16x16x32_bf16 v[6:9], v[186:189], v[230:233], v[6:9]
	v_mfma_f32_16x16x32_bf16 v[2:5], v[196:199], v[230:233], v[2:5]
	v_mfma_f32_16x16x32_bf16 v[2:5], v[202:205], v[234:237], v[2:5]
	v_mfma_f32_16x16x32_bf16 v[50:53], v[202:205], v[210:213], v[50:53]
	v_mfma_f32_16x16x32_bf16 v[50:53], v[196:199], v[206:209], v[50:53]
	v_mfma_f32_16x16x32_bf16 v[34:37], v[196:199], v[214:217], v[34:37]
	v_mfma_f32_16x16x32_bf16 v[34:37], v[202:205], v[218:221], v[34:37]
	v_mfma_f32_16x16x32_bf16 v[18:21], v[202:205], v[226:229], v[18:21]
	v_mfma_f32_16x16x32_bf16 v[18:21], v[196:199], v[222:225], v[18:21]
	s_barrier
	s_add_i32 s56, s56, 2
	s_add_u32 s54, s54, 0x100
	s_addc_u32 s55, s55, 0
	s_cmpk_gt_u32 s56, 0xa9
	s_mov_b64 s[40:41], s[48:49]
	s_cbranch_scc0 .LBB0_1731
	s_and_b64 vcc, exec, s[12:13]
	s_cbranch_vccz .LBB0_1734
	s_barrier

; #define PG8_STAGE(bufoff, gbase, voff) do { _Pragma("unroll") for (int _i = 0; _i < 2; ++_i) \
;         __builtin_amdgcn_global_load_lds((const unsigned*)((const char*)(gbase) + (voff)[_i]), (PG8_LAS unsigned*)(lds + (bufoff) + ldsw + _i * 8192), 16, 0, 0); } while (0)
; #define PG8_LDA(dst, b, h) do { _Pragma("unroll") for (int m = 0; m < 4; ++m) _Pragma("unroll") for (int k = 0; k < 2; ++k) dst[m][k] = *(const PG8_LAS bf16x8*)(lds + PG8_SA(b, h) + aoff + m * 2048 + k * 1024); } while (0)
; #define PG8_LDB(dst, b, h) do { _Pragma("unroll") for (int n = 0; n < 2; ++n) _Pragma("unroll") for (int k = 0; k < 2; ++k) dst[n][k] = *(const PG8_LAS bf16x8*)(lds + PG8_SB(b, h) + boff + n * 2048 + k * 1024); } while (0)
; #define PG8_MMA(ai, bj, At, Bt) do { __builtin_amdgcn_s_setprio(1); _Pragma("unroll") for (int m = 0; m < 4; ++m) _Pragma("unroll") for (int n = 0; n < 2; ++n) _Pragma("unroll") for (int k = 0; k < 2; ++k) \
;         acc[ai][bj][m][n] = __builtin_amdgcn_mfma_f32_16x16x32_bf16(Bt[n][k], At[m][k], acc[ai][bj][m][n], 0, 0, 0); __builtin_amdgcn_s_setprio(0); } while (0)
; #define PG8_WAIT_V(n) asm volatile("s_waitcnt vmcnt(" #n ")" ::: "memory")
; #define PG8_BAR __builtin_amdgcn_s_barrier()
; template <class Epi, class Sched, bool ALIGN_EPI = false, bool SP2 = false>
; __device__ __forceinline__ void gemm_phase(PG8_LAS unsigned char* lds, const Gemm g, const Sched& S, const Epi& E) {
;     ...
;         for (int t = 0; t < nt; t += 2) {
;             const bool last = (t == nt - 2);
;             const char* a1 = cA + (size_t)(t + 1) * kstep;
;             const char* a2 = last ? nA : cA + (size_t)(t + 2) * kstep; const char* b2 = last ? nB : cB + (size_t)(t + 2) * kstep;
;             const char* a3 = a2 + kstep; const char* b3 = b2 + kstep;
;             if (last && has_next) S.a_ready(nxt);
;             if constexpr (SP2) {
;             PG8_LDB(B0, 0, 0); PG8_LDB(B1, 0, 1); PG8_SCHED; PG8_LDA(At, 0, 0); PG8_STAGE(PG8_SA(1, 1), a1 + hstep, voffA);
;             PG8_WAIT_V(8); PG8_WAIT_L(0); PG8_BAR; PG8_MMA(0, 0, At, B0); PG8_MMA(0, 1, At, B1); PG8_BAR; PG8_SCHED;
;             PG8_LDA(At, 0, 1); PG8_STAGE(PG8_SB(0, 0), b2, voffB); PG8_STAGE(PG8_SB(0, 1), b2 + hstep, voffB); PG8_STAGE(PG8_SA(0, 0), a2, voffA);
;             PG8_WAIT_V(8); PG8_WAIT_L(0); PG8_BAR; PG8_MMA(1, 0, At, B0); PG8_MMA(1, 1, At, B1); PG8_BAR; PG8_SCHED;
.LBB0_1746:
	ds_read_b128 v[140:143], v134
	ds_read_b128 v[144:147], v134 offset:1024
	ds_read_b128 v[148:151], v134 offset:2048
	ds_read_b128 v[152:155], v134 offset:3072
	ds_read_b128 v[156:159], v135
	ds_read_b128 v[160:163], v135 offset:1024
	ds_read_b128 v[164:167], v135 offset:2048
	ds_read_b128 v[168:171], v135 offset:3072
	s_add_i32 s36, s38, 2
	s_mov_b32 s37, s11
	s_or_b32 s10, s38, 1
	s_lshl_b64 s[40:41], s[36:37], 7
	s_cmp_lg_u32 s38, s42
	s_cselect_b32 s38, s40, 0
	s_cselect_b32 s37, s41, 0
	s_add_u32 s40, s6, s38
	s_addc_u32 s41, s7, s37
	s_add_u32 s38, s2, s38
	s_addc_u32 s39, s3, s37
	s_lshl_b64 s[52:53], s[10:11], 7
	s_add_u32 s52, s8, s52
	s_addc_u32 s53, s9, s53
	s_mov_b32 m0, s43
	v_lshl_add_u64 v[192:193], s[52:53], 0, v[128:129]
	ds_read_b128 v[172:175], v136
	ds_read_b128 v[176:179], v136 offset:1024
	ds_read_b128 v[180:183], v136 offset:2048
	ds_read_b128 v[184:187], v136 offset:3072
	ds_read_b128 v[188:191], v136 offset:4096
	ds_read_b128 v[196:199], v136 offset:5120
	ds_read_b128 v[202:205], v136 offset:6144
	ds_read_b128 v[206:209], v136 offset:7168
	global_load_lds_dwordx4 v[192:193], off
	v_lshl_add_u64 v[192:193], s[52:53], 0, v[130:131]
	s_mov_b32 m0, s44
	s_nop 0
	global_load_lds_dwordx4 v[192:193], off
	s_waitcnt vmcnt(8)
	s_waitcnt lgkmcnt(0)
	s_barrier
	v_mfma_f32_16x16x32_bf16 v[124:127], v[140:143], v[172:175], v[124:127]
	v_mfma_f32_16x16x32_bf16 v[124:127], v[144:147], v[176:179], v[124:127]
	v_mfma_f32_16x16x32_bf16 v[116:119], v[144:147], v[184:187], v[116:119]
	v_mfma_f32_16x16x32_bf16 v[116:119], v[140:143], v[180:183], v[116:119]
	v_mfma_f32_16x16x32_bf16 v[104:107], v[140:143], v[188:191], v[104:107]
	v_mfma_f32_16x16x32_bf16 v[104:107], v[144:147], v[196:199], v[104:107]
	v_mfma_f32_16x16x32_bf16 v[88:91], v[144:147], v[206:209], v[88:91]
	v_mfma_f32_16x16x32_bf16 v[88:91], v[140:143], v[202:205], v[88:91]
	v_mfma_f32_16x16x32_bf16 v[80:83], v[148:151], v[202:205], v[80:83]
	v_mfma_f32_16x16x32_bf16 v[80:83], v[152:155], v[206:209], v[80:83]
	v_mfma_f32_16x16x32_bf16 v[120:123], v[152:155], v[176:179], v[120:123]
	v_mfma_f32_16x16x32_bf16 v[120:123], v[148:151], v[172:175], v[120:123]
	v_mfma_f32_16x16x32_bf16 v[112:115], v[148:151], v[180:183], v[112:115]
	v_mfma_f32_16x16x32_bf16 v[112:115], v[152:155], v[184:187], v[112:115]
	v_mfma_f32_16x16x32_bf16 v[96:99], v[152:155], v[196:199], v[96:99]
	v_mfma_f32_16x16x32_bf16 v[96:99], v[148:151], v[188:191], v[96:99]
	v_mfma_f32_16x16x32_bf16 v[76:79], v[156:159], v[188:191], v[76:79]
	v_mfma_f32_16x16x32_bf16 v[76:79], v[160:163], v[196:199], v[76:79]
	v_mfma_f32_16x16x32_bf16 v[108:111], v[160:163], v[176:179], v[108:111]
	v_mfma_f32_16x16x32_bf16 v[108:111], v[156:159], v[172:175], v[108:111]
	v_mfma_f32_16x16x32_bf16 v[92:95], v[156:159], v[180:183], v[92:95]
	v_mfma_f32_16x16x32_bf16 v[92:95], v[160:163], v[184:187], v[92:95]
	v_mfma_f32_16x16x32_bf16 v[68:71], v[160:163], v[206:209], v[68:71]
	v_mfma_f32_16x16x32_bf16 v[68:71], v[156:159], v[202:205], v[68:71]
	v_mfma_f32_16x16x32_bf16 v[64:67], v[164:167], v[202:205], v[64:67]
	v_mfma_f32_16x16x32_bf16 v[64:67], v[168:171], v[206:209], v[64:67]
	v_mfma_f32_16x16x32_bf16 v[100:103], v[168:171], v[176:179], v[100:103]
	v_mfma_f32_16x16x32_bf16 v[100:103], v[164:167], v[172:175], v[100:103]
	v_mfma_f32_16x16x32_bf16 v[84:87], v[164:167], v[180:183], v[84:87]
	v_mfma_f32_16x16x32_bf16 v[84:87], v[168:171], v[184:187], v[84:87]
	v_mfma_f32_16x16x32_bf16 v[72:75], v[168:171], v[196:199], v[72:75]
	v_mfma_f32_16x16x32_bf16 v[72:75], v[164:167], v[188:191], v[72:75]
	s_barrier
	s_mov_b32 m0, s31
	v_lshl_add_u64 v[192:193], s[38:39], 0, v[128:129]
	s_add_u32 s52, s38, 0x2b0000
	ds_read_b128 v[172:175], v136 offset:16384
	ds_read_b128 v[176:179], v136 offset:17408
	ds_read_b128 v[180:183], v136 offset:18432
	ds_read_b128 v[184:187], v136 offset:19456
	ds_read_b128 v[188:191], v136 offset:20480
	ds_read_b128 v[196:199], v136 offset:21504
	ds_read_b128 v[202:205], v136 offset:22528
	ds_read_b128 v[206:209], v136 offset:23552
	global_load_lds_dwordx4 v[192:193], off
	v_lshl_add_u64 v[194:195], s[38:39], 0, v[130:131]
	s_mov_b32 m0, s45
	s_addc_u32 s53, s39, 0
	global_load_lds_dwordx4 v[194:195], off
	v_lshl_add_u64 v[210:211], s[52:53], 0, v[128:129]
	s_mov_b32 m0, s46
	v_lshl_add_u64 v[212:213], s[40:41], 0, v[130:131]
	global_load_lds_dwordx4 v[210:211], off
	v_lshl_add_u64 v[210:211], s[52:53], 0, v[130:131]
	s_mov_b32 m0, s47
	s_nop 0
	global_load_lds_dwordx4 v[210:211], off
	v_lshl_add_u64 v[210:211], s[40:41], 0, v[128:129]
	s_mov_b32 m0, s26
	s_nop 0
	global_load_lds_dwordx4 v[210:211], off
	s_mov_b32 m0, s27
	s_nop 0
	global_load_lds_dwordx4 v[212:213], off
	s_waitcnt vmcnt(8)
	s_waitcnt lgkmcnt(0)
	s_barrier
; #define PG8_STAGE(bufoff, gbase, voff) do { _Pragma("unroll") for (int _i = 0; _i < 2; ++_i) \
;         __builtin_amdgcn_global_load_lds((const unsigned*)((const char*)(gbase) + (voff)[_i]), (PG8_LAS unsigned*)(lds + (bufoff) + ldsw + _i * 8192), 16, 0, 0); } while (0)
; #define PG8_LDA(dst, b, h) do { _Pragma("unroll") for (int m = 0; m < 4; ++m) _Pragma("unroll") for (int k = 0; k < 2; ++k) dst[m][k] = *(const PG8_LAS bf16x8*)(lds + PG8_SA(b, h) + aoff + m * 2048 + k * 1024); } while (0)
; #define PG8_LDB(dst, b, h) do { _Pragma("unroll") for (int n = 0; n < 2; ++n) _Pragma("unroll") for (int k = 0; k < 2; ++k) dst[n][k] = *(const PG8_LAS bf16x8*)(lds + PG8_SB(b, h) + boff + n * 2048 + k * 1024); } while (0)
; #define PG8_MMA(ai, bj, At, Bt) do { __builtin_amdgcn_s_setprio(1); _Pragma("unroll") for (int m = 0; m < 4; ++m) _Pragma("unroll") for (int n = 0; n < 2; ++n) _Pragma("unroll") for (int k = 0; k < 2; ++k) \
;         acc[ai][bj][m][n] = __builtin_amdgcn_mfma_f32_16x16x32_bf16(Bt[n][k], At[m][k], acc[ai][bj][m][n], 0, 0, 0); __builtin_amdgcn_s_setprio(0); } while (0)
; #define PG8_WAIT_V(n) asm volatile("s_waitcnt vmcnt(" #n ")" ::: "memory")
; #define PG8_WAIT_L(n) asm volatile("s_waitcnt lgkmcnt(" #n ")" ::: "memory")
; #define PG8_BAR __builtin_amdgcn_s_barrier()
; #define PG8_SCHED __builtin_amdgcn_sched_barrier(0)
; template <class Epi, class Sched, bool ALIGN_EPI = false, bool SP2 = false>
; __device__ __forceinline__ void gemm_phase(PG8_LAS unsigned char* lds, const Gemm g, const Sched& S, const Epi& E) {
;     ...
;             PG8_WAIT_V(8); PG8_WAIT_L(0); PG8_BAR; PG8_MMA(1, 0, At, B0); PG8_MMA(1, 1, At, B1); PG8_BAR; PG8_SCHED;
;             PG8_LDB(B0, 1, 0); PG8_LDB(B1, 1, 1); PG8_SCHED; PG8_LDA(At, 1, 0); PG8_STAGE(PG8_SA(0, 1), a2 + hstep, voffA);
;             PG8_WAIT_V(8); PG8_WAIT_L(0); PG8_BAR; PG8_MMA(0, 0, At, B0); PG8_MMA(0, 1, At, B1); PG8_BAR; PG8_SCHED;
	v_mfma_f32_16x16x32_bf16 v[60:63], v[140:143], v[172:175], v[60:63]
	v_mfma_f32_16x16x32_bf16 v[60:63], v[144:147], v[176:179], v[60:63]
	v_mfma_f32_16x16x32_bf16 v[52:55], v[144:147], v[184:187], v[52:55]
	v_mfma_f32_16x16x32_bf16 v[52:55], v[140:143], v[180:183], v[52:55]
	v_mfma_f32_16x16x32_bf16 v[40:43], v[140:143], v[188:191], v[40:43]
	v_mfma_f32_16x16x32_bf16 v[40:43], v[144:147], v[196:199], v[40:43]
	v_mfma_f32_16x16x32_bf16 v[24:27], v[144:147], v[206:209], v[24:27]
	v_mfma_f32_16x16x32_bf16 v[24:27], v[140:143], v[202:205], v[24:27]
	v_mfma_f32_16x16x32_bf16 v[16:19], v[148:151], v[202:205], v[16:19]
	v_mfma_f32_16x16x32_bf16 v[16:19], v[152:155], v[206:209], v[16:19]
	v_mfma_f32_16x16x32_bf16 v[56:59], v[152:155], v[176:179], v[56:59]
	v_mfma_f32_16x16x32_bf16 v[56:59], v[148:151], v[172:175], v[56:59]
	v_mfma_f32_16x16x32_bf16 v[48:51], v[148:151], v[180:183], v[48:51]
	v_mfma_f32_16x16x32_bf16 v[48:51], v[152:155], v[184:187], v[48:51]
	v_mfma_f32_16x16x32_bf16 v[32:35], v[152:155], v[196:199], v[32:35]
	v_mfma_f32_16x16x32_bf16 v[32:35], v[148:151], v[188:191], v[32:35]
	v_mfma_f32_16x16x32_bf16 v[12:15], v[156:159], v[188:191], v[12:15]
	v_mfma_f32_16x16x32_bf16 v[12:15], v[160:163], v[196:199], v[12:15]
	v_mfma_f32_16x16x32_bf16 v[44:47], v[160:163], v[176:179], v[44:47]
	v_mfma_f32_16x16x32_bf16 v[44:47], v[156:159], v[172:175], v[44:47]
	v_mfma_f32_16x16x32_bf16 v[28:31], v[156:159], v[180:183], v[28:31]
	v_mfma_f32_16x16x32_bf16 v[28:31], v[160:163], v[184:187], v[28:31]
	v_mfma_f32_16x16x32_bf16 v[4:7], v[160:163], v[206:209], v[4:7]
	v_mfma_f32_16x16x32_bf16 v[4:7], v[156:159], v[202:205], v[4:7]
	v_mfma_f32_16x16x32_bf16 v[0:3], v[164:167], v[202:205], v[0:3]
	v_mfma_f32_16x16x32_bf16 v[0:3], v[168:171], v[206:209], v[0:3]
	v_mfma_f32_16x16x32_bf16 v[36:39], v[168:171], v[176:179], v[36:39]
	v_mfma_f32_16x16x32_bf16 v[36:39], v[164:167], v[172:175], v[36:39]
	v_mfma_f32_16x16x32_bf16 v[20:23], v[164:167], v[180:183], v[20:23]
	v_mfma_f32_16x16x32_bf16 v[20:23], v[168:171], v[184:187], v[20:23]
	v_mfma_f32_16x16x32_bf16 v[8:11], v[168:171], v[196:199], v[8:11]
	v_mfma_f32_16x16x32_bf16 v[8:11], v[164:167], v[188:191], v[8:11]
	s_barrier
	ds_read_b128 v[140:143], v137
	ds_read_b128 v[144:147], v137 offset:1024
	ds_read_b128 v[148:151], v137 offset:2048
	ds_read_b128 v[152:155], v137 offset:3072
	ds_read_b128 v[156:159], v138
	ds_read_b128 v[160:163], v138 offset:1024
	ds_read_b128 v[164:167], v138 offset:2048
	ds_read_b128 v[168:171], v138 offset:3072
	s_add_u32 s40, s40, 0x2b0000
	s_addc_u32 s41, s41, 0
	s_mov_b32 m0, s28
	v_lshl_add_u64 v[214:215], s[40:41], 0, v[128:129]
	ds_read_b128 v[172:175], v136 offset:32768
	ds_read_b128 v[176:179], v136 offset:33792
	ds_read_b128 v[180:183], v136 offset:34816
	ds_read_b128 v[184:187], v136 offset:35840
	ds_read_b128 v[188:191], v136 offset:36864
	ds_read_b128 v[196:199], v136 offset:37888
	ds_read_b128 v[202:205], v136 offset:38912
	ds_read_b128 v[206:209], v136 offset:39936
	global_load_lds_dwordx4 v[214:215], off
	v_lshl_add_u64 v[214:215], s[40:41], 0, v[130:131]
	s_mov_b32 m0, s30
	s_nop 0
	global_load_lds_dwordx4 v[214:215], off
	s_waitcnt vmcnt(8)
	s_waitcnt lgkmcnt(0)
	s_barrier
	v_mfma_f32_16x16x32_bf16 v[124:127], v[140:143], v[172:175], v[124:127]
	v_mfma_f32_16x16x32_bf16 v[124:127], v[144:147], v[176:179], v[124:127]
	v_mfma_f32_16x16x32_bf16 v[116:119], v[144:147], v[184:187], v[116:119]
	v_mfma_f32_16x16x32_bf16 v[116:119], v[140:143], v[180:183], v[116:119]
	v_mfma_f32_16x16x32_bf16 v[104:107], v[140:143], v[188:191], v[104:107]
	v_mfma_f32_16x16x32_bf16 v[104:107], v[144:147], v[196:199], v[104:107]
	v_mfma_f32_16x16x32_bf16 v[88:91], v[144:147], v[206:209], v[88:91]
	v_mfma_f32_16x16x32_bf16 v[88:91], v[140:143], v[202:205], v[88:91]
	v_mfma_f32_16x16x32_bf16 v[80:83], v[148:151], v[202:205], v[80:83]
	v_mfma_f32_16x16x32_bf16 v[80:83], v[152:155], v[206:209], v[80:83]
	v_mfma_f32_16x16x32_bf16 v[120:123], v[152:155], v[176:179], v[120:123]
	v_mfma_f32_16x16x32_bf16 v[120:123], v[148:151], v[172:175], v[120:123]
	v_mfma_f32_16x16x32_bf16 v[112:115], v[148:151], v[180:183], v[112:115]
	v_mfma_f32_16x16x32_bf16 v[112:115], v[152:155], v[184:187], v[112:115]
	v_mfma_f32_16x16x32_bf16 v[96:99], v[152:155], v[196:199], v[96:99]
	v_mfma_f32_16x16x32_bf16 v[96:99], v[148:151], v[188:191], v[96:99]
	v_mfma_f32_16x16x32_bf16 v[76:79], v[156:159], v[188:191], v[76:79]
	v_mfma_f32_16x16x32_bf16 v[76:79], v[160:163], v[196:199], v[76:79]
	v_mfma_f32_16x16x32_bf16 v[108:111], v[160:163], v[176:179], v[108:111]
	v_mfma_f32_16x16x32_bf16 v[108:111], v[156:159], v[172:175], v[108:111]
	v_mfma_f32_16x16x32_bf16 v[92:95], v[156:159], v[180:183], v[92:95]
	v_mfma_f32_16x16x32_bf16 v[92:95], v[160:163], v[184:187], v[92:95]
	v_mfma_f32_16x16x32_bf16 v[68:71], v[160:163], v[206:209], v[68:71]
	v_mfma_f32_16x16x32_bf16 v[68:71], v[156:159], v[202:205], v[68:71]
	v_mfma_f32_16x16x32_bf16 v[64:67], v[164:167], v[202:205], v[64:67]
	v_mfma_f32_16x16x32_bf16 v[64:67], v[168:171], v[206:209], v[64:67]
	v_mfma_f32_16x16x32_bf16 v[100:103], v[168:171], v[176:179], v[100:103]
	v_mfma_f32_16x16x32_bf16 v[100:103], v[164:167], v[172:175], v[100:103]
	v_mfma_f32_16x16x32_bf16 v[84:87], v[164:167], v[180:183], v[84:87]
	v_mfma_f32_16x16x32_bf16 v[84:87], v[168:171], v[184:187], v[84:87]
	v_mfma_f32_16x16x32_bf16 v[72:75], v[168:171], v[196:199], v[72:75]
	v_mfma_f32_16x16x32_bf16 v[72:75], v[164:167], v[188:191], v[72:75]
	s_barrier
; #define PG8_STAGE(bufoff, gbase, voff) do { _Pragma("unroll") for (int _i = 0; _i < 2; ++_i) \
;         __builtin_amdgcn_global_load_lds((const unsigned*)((const char*)(gbase) + (voff)[_i]), (PG8_LAS unsigned*)(lds + (bufoff) + ldsw + _i * 8192), 16, 0, 0); } while (0)
; #define PG8_LDA(dst, b, h) do { _Pragma("unroll") for (int m = 0; m < 4; ++m) _Pragma("unroll") for (int k = 0; k < 2; ++k) dst[m][k] = *(const PG8_LAS bf16x8*)(lds + PG8_SA(b, h) + aoff + m * 2048 + k * 1024); } while (0)
; #define PG8_MMA(ai, bj, At, Bt) do { __builtin_amdgcn_s_setprio(1); _Pragma("unroll") for (int m = 0; m < 4; ++m) _Pragma("unroll") for (int n = 0; n < 2; ++n) _Pragma("unroll") for (int k = 0; k < 2; ++k) \
;         acc[ai][bj][m][n] = __builtin_amdgcn_mfma_f32_16x16x32_bf16(Bt[n][k], At[m][k], acc[ai][bj][m][n], 0, 0, 0); __builtin_amdgcn_s_setprio(0); } while (0)
; #define PG8_WAIT_V(n) asm volatile("s_waitcnt vmcnt(" #n ")" ::: "memory")
; #define PG8_WAIT_L(n) asm volatile("s_waitcnt lgkmcnt(" #n ")" ::: "memory")
; #define PG8_BAR __builtin_amdgcn_s_barrier()
; #define PG8_SCHED __builtin_amdgcn_sched_barrier(0)
; template <class Epi, class Sched, bool ALIGN_EPI = false, bool SP2 = false>
; __device__ __forceinline__ void gemm_phase(PG8_LAS unsigned char* lds, const Gemm g, const Sched& S, const Epi& E) {
;     ...
;             PG8_LDA(At, 1, 1); PG8_STAGE(PG8_SB(1, 0), b3, voffB); PG8_STAGE(PG8_SB(1, 1), b3 + hstep, voffB); PG8_STAGE(PG8_SA(1, 0), a3, voffA);
;             PG8_WAIT_V(8); PG8_WAIT_L(0); PG8_BAR; PG8_MMA(1, 0, At, B0); PG8_MMA(1, 1, At, B1); PG8_BAR; PG8_SCHED;
;     ...
;         if constexpr (ALIGN_EPI) { if (wr == 0) PG8_BAR; }
	s_mov_b32 m0, s48
	v_lshl_add_u64 v[192:193], v[192:193], 0, s[12:13]
	s_add_u32 s38, s38, 0x2b0080
	ds_read_b128 v[172:175], v136 offset:49152
	ds_read_b128 v[176:179], v136 offset:50176
	ds_read_b128 v[180:183], v136 offset:51200
	ds_read_b128 v[184:187], v136 offset:52224
	ds_read_b128 v[188:191], v136 offset:53248
	ds_read_b128 v[196:199], v136 offset:54272
	ds_read_b128 v[202:205], v136 offset:55296
	ds_read_b128 v[206:209], v136 offset:56320
	global_load_lds_dwordx4 v[192:193], off
	v_lshl_add_u64 v[192:193], v[194:195], 0, s[12:13]
	s_mov_b32 m0, s49
	s_addc_u32 s39, s39, 0
	global_load_lds_dwordx4 v[192:193], off
	v_lshl_add_u64 v[192:193], s[38:39], 0, v[128:129]
	s_mov_b32 m0, s50
	s_nop 0
	global_load_lds_dwordx4 v[192:193], off
	v_lshl_add_u64 v[192:193], s[38:39], 0, v[130:131]
	s_mov_b32 m0, s51
	s_nop 0
	global_load_lds_dwordx4 v[192:193], off
	v_lshl_add_u64 v[192:193], v[210:211], 0, s[12:13]
	s_mov_b32 m0, s34
	s_nop 0
	global_load_lds_dwordx4 v[192:193], off
	v_lshl_add_u64 v[192:193], v[212:213], 0, s[12:13]
	s_mov_b32 m0, s35
	s_nop 0
	global_load_lds_dwordx4 v[192:193], off
	s_waitcnt vmcnt(8)
	s_waitcnt lgkmcnt(0)
	s_barrier
	v_mfma_f32_16x16x32_bf16 v[60:63], v[140:143], v[172:175], v[60:63]
	v_mfma_f32_16x16x32_bf16 v[60:63], v[144:147], v[176:179], v[60:63]
	v_mfma_f32_16x16x32_bf16 v[52:55], v[144:147], v[184:187], v[52:55]
	v_mfma_f32_16x16x32_bf16 v[52:55], v[140:143], v[180:183], v[52:55]
	v_mfma_f32_16x16x32_bf16 v[40:43], v[140:143], v[188:191], v[40:43]
	v_mfma_f32_16x16x32_bf16 v[40:43], v[144:147], v[196:199], v[40:43]
	v_mfma_f32_16x16x32_bf16 v[24:27], v[144:147], v[206:209], v[24:27]
	v_mfma_f32_16x16x32_bf16 v[24:27], v[140:143], v[202:205], v[24:27]
	v_mfma_f32_16x16x32_bf16 v[16:19], v[148:151], v[202:205], v[16:19]
	v_mfma_f32_16x16x32_bf16 v[16:19], v[152:155], v[206:209], v[16:19]
	v_mfma_f32_16x16x32_bf16 v[56:59], v[152:155], v[176:179], v[56:59]
	v_mfma_f32_16x16x32_bf16 v[56:59], v[148:151], v[172:175], v[56:59]
	v_mfma_f32_16x16x32_bf16 v[48:51], v[148:151], v[180:183], v[48:51]
	v_mfma_f32_16x16x32_bf16 v[48:51], v[152:155], v[184:187], v[48:51]
	v_mfma_f32_16x16x32_bf16 v[32:35], v[152:155], v[196:199], v[32:35]
	v_mfma_f32_16x16x32_bf16 v[32:35], v[148:151], v[188:191], v[32:35]
	v_mfma_f32_16x16x32_bf16 v[12:15], v[156:159], v[188:191], v[12:15]
	v_mfma_f32_16x16x32_bf16 v[12:15], v[160:163], v[196:199], v[12:15]
	v_mfma_f32_16x16x32_bf16 v[44:47], v[160:163], v[176:179], v[44:47]
	v_mfma_f32_16x16x32_bf16 v[44:47], v[156:159], v[172:175], v[44:47]
	v_mfma_f32_16x16x32_bf16 v[28:31], v[156:159], v[180:183], v[28:31]
	v_mfma_f32_16x16x32_bf16 v[28:31], v[160:163], v[184:187], v[28:31]
	v_mfma_f32_16x16x32_bf16 v[4:7], v[160:163], v[206:209], v[4:7]
	v_mfma_f32_16x16x32_bf16 v[4:7], v[156:159], v[202:205], v[4:7]
	v_mfma_f32_16x16x32_bf16 v[0:3], v[164:167], v[202:205], v[0:3]
	v_mfma_f32_16x16x32_bf16 v[0:3], v[168:171], v[206:209], v[0:3]
	v_mfma_f32_16x16x32_bf16 v[36:39], v[168:171], v[176:179], v[36:39]
	v_mfma_f32_16x16x32_bf16 v[36:39], v[164:167], v[172:175], v[36:39]
	v_mfma_f32_16x16x32_bf16 v[20:23], v[164:167], v[180:183], v[20:23]
	v_mfma_f32_16x16x32_bf16 v[20:23], v[168:171], v[184:187], v[20:23]
	v_mfma_f32_16x16x32_bf16 v[8:11], v[168:171], v[196:199], v[8:11]
	v_mfma_f32_16x16x32_bf16 v[8:11], v[164:167], v[188:191], v[8:11]
	s_barrier
	s_cmp_ge_u32 s36, s5
	s_mov_b32 s38, s36
	s_cbranch_scc0 .LBB0_1746
	s_cmpk_lt_u32 s16, 0x100
	s_cbranch_scc0 .LBB0_1749
	s_barrier
